# d4 with priorities swapped: load segment prio 1, MFMA segment prio 0
# speedup vs baseline: 1.0131x; 1.0131x over previous
; #define PG8_STAGE(bufoff, gbase, voff) do { _Pragma("unroll") for (int _i = 0; _i < 2; ++_i) \
;         __builtin_amdgcn_global_load_lds((const unsigned*)((const char*)(gbase) + (voff)[_i]), (LAS unsigned*)(lds + (bufoff) + ldsw + _i * 8192), 16, 0, 0); } while (0)
; #define PG8_LDA(dst, b, h) do { _Pragma("unroll") for (int m = 0; m < 4; ++m) _Pragma("unroll") for (int k = 0; k < 2; ++k) dst[m][k] = *(const LAS bf16x8*)(lds + PG8_SA(b, h) + aoff + m * 2048 + k * 1024); } while (0)
; #define PG8_LDB(dst, b, h) do { _Pragma("unroll") for (int n = 0; n < 2; ++n) _Pragma("unroll") for (int k = 0; k < 2; ++k) dst[n][k] = *(const LAS bf16x8*)(lds + PG8_SB(b, h) + boff + n * 2048 + k * 1024); } while (0)
; #define PG8_MMA(ai, bj, At, Bt) do { __builtin_amdgcn_s_setprio(1); _Pragma("unroll") for (int m = 0; m < 4; ++m) _Pragma("unroll") for (int n = 0; n < 2; ++n) _Pragma("unroll") for (int k = 0; k < 2; ++k) \
;         acc[ai][bj][m][n] = __builtin_amdgcn_mfma_f32_16x16x32_bf16(Bt[n][k], At[m][k], acc[ai][bj][m][n], 0, 0, 0); __builtin_amdgcn_s_setprio(0); } while (0)
; #define PG8_WAIT_V(n) asm volatile("s_waitcnt vmcnt(" #n ")" ::: "memory")
; #define PG8_WAIT_L(n) asm volatile("s_waitcnt lgkmcnt(" #n ")" ::: "memory")
; #define PG8_BAR __builtin_amdgcn_s_barrier()
; template <class Epi>
; __device__ __forceinline__ void gemm_phase(LAS unsigned char* lds, const Gemm g, const StaticOrder& S, const Epi& E) {
;     ...
;         for (int t = 0; t < nt; t += 2) {
;             const bool last = (t == nt - 2);
;             const char* a1 = cA + (size_t)(t + 1) * kstep;
;             const char* a2 = last ? nA : cA + (size_t)(t + 2) * kstep; const char* b2 = last ? nB : cB + (size_t)(t + 2) * kstep;
;             const char* a3 = a2 + kstep; const char* b3 = b2 + kstep;
;             if constexpr (Epi::MIDK > 0) { if (t == Epi::MIDK) E.mid(acc, cur, wr, wc, fr, fq); }
;             PG8_LDB(B0, 0, 0); PG8_LDB(B1, 0, 1); PG8_SCHED; PG8_LDA(At, 0, 0); PG8_STAGE(PG8_SA(1, 1), a1 + hstep, voffA);
;             PG8_WAIT_V(8); PG8_WAIT_L(0); PG8_BAR; PG8_MMA(0, 0, At, B0); PG8_MMA(0, 1, At, B1); PG8_BAR; PG8_SCHED;
;             PG8_LDA(At, 0, 1); PG8_STAGE(PG8_SB(0, 0), b2, voffB); PG8_STAGE(PG8_SB(0, 1), b2 + hstep, voffB); PG8_STAGE(PG8_SA(0, 0), a2, voffA);
;             PG8_WAIT_V(8); PG8_WAIT_L(0); PG8_BAR; PG8_MMA(1, 0, At, B0); PG8_MMA(1, 1, At, B1); PG8_BAR; PG8_SCHED;
.LBB0_134:
	ds_read_b128 v[158:161], v150
	ds_read_b128 v[162:165], v150 offset:1024
	ds_read_b128 v[166:169], v150 offset:2048
	ds_read_b128 v[174:177], v150 offset:3072
	ds_read_b128 v[178:181], v151
	ds_read_b128 v[182:185], v151 offset:1024
	ds_read_b128 v[186:189], v151 offset:2048
	ds_read_b128 v[190:193], v151 offset:3072
	s_add_u32 s66, s64, 0xfffc0080
	s_addc_u32 s67, s65, -1
	s_cmp_eq_u32 s92, 12
	s_cselect_b32 s69, s87, s67
	s_cselect_b32 s68, s88, s66
	s_cselect_b32 s67, s47, s91
	s_cselect_b32 s66, s89, s90
	s_add_i32 m0, s61, 0xc000
	ds_read_b128 v[194:197], v152
	ds_read_b128 v[198:201], v152 offset:1024
	ds_read_b128 v[202:205], v152 offset:2048
	ds_read_b128 v[206:209], v152 offset:3072
	ds_read_b128 v[210:213], v152 offset:4096
	ds_read_b128 v[214:217], v152 offset:5120
	ds_read_b128 v[218:221], v152 offset:6144
	ds_read_b128 v[222:225], v152 offset:7168
	global_load_lds_dwordx4 v140, s[64:65]
	s_add_i32 m0, s61, 0xe000
	s_nop 0
	global_load_lds_dwordx4 v142, s[64:65]
	s_waitcnt vmcnt(8)
	s_waitcnt lgkmcnt(0)
	s_setprio 0
	s_barrier
	v_mfma_f32_16x16x32_bf16 v[126:129], v[158:161], v[194:197], v[126:129]
	v_mfma_f32_16x16x32_bf16 v[118:121], v[166:169], v[194:197], v[118:121]
	v_mfma_f32_16x16x32_bf16 v[110:113], v[158:161], v[202:205], v[110:113]
	v_mfma_f32_16x16x32_bf16 v[102:105], v[166:169], v[202:205], v[102:105]
	v_mfma_f32_16x16x32_bf16 v[94:97], v[158:161], v[210:213], v[94:97]
	v_mfma_f32_16x16x32_bf16 v[86:89], v[166:169], v[210:213], v[86:89]
	v_mfma_f32_16x16x32_bf16 v[78:81], v[158:161], v[218:221], v[78:81]
	v_mfma_f32_16x16x32_bf16 v[70:73], v[166:169], v[218:221], v[70:73]
	v_mfma_f32_16x16x32_bf16 v[126:129], v[162:165], v[198:201], v[126:129]
	v_mfma_f32_16x16x32_bf16 v[118:121], v[174:177], v[198:201], v[118:121]
	v_mfma_f32_16x16x32_bf16 v[110:113], v[162:165], v[206:209], v[110:113]
	v_mfma_f32_16x16x32_bf16 v[102:105], v[174:177], v[206:209], v[102:105]
	v_mfma_f32_16x16x32_bf16 v[94:97], v[162:165], v[214:217], v[94:97]
	v_mfma_f32_16x16x32_bf16 v[86:89], v[174:177], v[214:217], v[86:89]
	v_mfma_f32_16x16x32_bf16 v[78:81], v[162:165], v[222:225], v[78:81]
	v_mfma_f32_16x16x32_bf16 v[70:73], v[174:177], v[222:225], v[70:73]
	v_mfma_f32_16x16x32_bf16 v[122:125], v[178:181], v[194:197], v[122:125]
	v_mfma_f32_16x16x32_bf16 v[114:117], v[186:189], v[194:197], v[114:117]
	v_mfma_f32_16x16x32_bf16 v[106:109], v[178:181], v[202:205], v[106:109]
	v_mfma_f32_16x16x32_bf16 v[98:101], v[186:189], v[202:205], v[98:101]
	v_mfma_f32_16x16x32_bf16 v[90:93], v[178:181], v[210:213], v[90:93]
	v_mfma_f32_16x16x32_bf16 v[82:85], v[186:189], v[210:213], v[82:85]
	v_mfma_f32_16x16x32_bf16 v[74:77], v[178:181], v[218:221], v[74:77]
	v_mfma_f32_16x16x32_bf16 v[66:69], v[186:189], v[218:221], v[66:69]
	v_mfma_f32_16x16x32_bf16 v[122:125], v[182:185], v[198:201], v[122:125]
	v_mfma_f32_16x16x32_bf16 v[114:117], v[190:193], v[198:201], v[114:117]
	v_mfma_f32_16x16x32_bf16 v[106:109], v[182:185], v[206:209], v[106:109]
	v_mfma_f32_16x16x32_bf16 v[98:101], v[190:193], v[206:209], v[98:101]
	v_mfma_f32_16x16x32_bf16 v[90:93], v[182:185], v[214:217], v[90:93]
	v_mfma_f32_16x16x32_bf16 v[82:85], v[190:193], v[214:217], v[82:85]
	v_mfma_f32_16x16x32_bf16 v[74:77], v[182:185], v[222:225], v[74:77]
	v_mfma_f32_16x16x32_bf16 v[66:69], v[190:193], v[222:225], v[66:69]
	s_barrier
	s_setprio 1
	s_add_u32 s98, s66, s8
	s_addc_u32 s99, s67, s9
	s_add_u32 s100, s68, s8
	s_addc_u32 s101, s69, s9
	s_add_i32 s93, s83, s6
	s_mov_b32 m0, s93
	ds_read_b128 v[194:197], v152 offset:16384
	ds_read_b128 v[198:201], v152 offset:17408
	ds_read_b128 v[202:205], v152 offset:18432
	ds_read_b128 v[206:209], v152 offset:19456
	ds_read_b128 v[210:213], v152 offset:20480
	ds_read_b128 v[214:217], v152 offset:21504
	ds_read_b128 v[218:221], v152 offset:22528
	ds_read_b128 v[222:225], v152 offset:23552
	global_load_lds_dwordx4 v132, s[66:67]
	s_add_i32 m0, s93, 0x2000
	s_add_u32 s94, s66, 0x40000
	s_addc_u32 s95, s67, 0
	s_add_i32 s93, s84, s6
	global_load_lds_dwordx4 v136, s[66:67]
	s_mov_b32 m0, s93
	s_nop 0
	global_load_lds_dwordx4 v132, s[94:95]
	s_add_i32 m0, s93, 0x2000
	s_nop 0
	global_load_lds_dwordx4 v136, s[94:95]
	s_mov_b32 m0, s61
	s_nop 0
	global_load_lds_dwordx4 v130, s[68:69]
	s_mov_b32 m0, s63
	s_nop 0
	global_load_lds_dwordx4 v134, s[68:69]
	s_waitcnt vmcnt(8)
	s_waitcnt lgkmcnt(0)
	s_setprio 0
	s_barrier
	v_mfma_f32_16x16x32_bf16 v[62:65], v[158:161], v[194:197], v[62:65]
	v_mfma_f32_16x16x32_bf16 v[54:57], v[166:169], v[194:197], v[54:57]
	v_mfma_f32_16x16x32_bf16 v[46:49], v[158:161], v[202:205], v[46:49]
	v_mfma_f32_16x16x32_bf16 v[38:41], v[166:169], v[202:205], v[38:41]
	v_mfma_f32_16x16x32_bf16 v[30:33], v[158:161], v[210:213], v[30:33]
	v_mfma_f32_16x16x32_bf16 v[22:25], v[166:169], v[210:213], v[22:25]
	v_mfma_f32_16x16x32_bf16 v[14:17], v[158:161], v[218:221], v[14:17]
	v_mfma_f32_16x16x32_bf16 v[6:9], v[166:169], v[218:221], v[6:9]
	v_mfma_f32_16x16x32_bf16 v[62:65], v[162:165], v[198:201], v[62:65]
	v_mfma_f32_16x16x32_bf16 v[54:57], v[174:177], v[198:201], v[54:57]
	v_mfma_f32_16x16x32_bf16 v[46:49], v[162:165], v[206:209], v[46:49]
	v_mfma_f32_16x16x32_bf16 v[38:41], v[174:177], v[206:209], v[38:41]
	v_mfma_f32_16x16x32_bf16 v[30:33], v[162:165], v[214:217], v[30:33]
	v_mfma_f32_16x16x32_bf16 v[22:25], v[174:177], v[214:217], v[22:25]
	v_mfma_f32_16x16x32_bf16 v[14:17], v[162:165], v[222:225], v[14:17]
	v_mfma_f32_16x16x32_bf16 v[6:9], v[174:177], v[222:225], v[6:9]
	v_mfma_f32_16x16x32_bf16 v[58:61], v[178:181], v[194:197], v[58:61]
	v_mfma_f32_16x16x32_bf16 v[50:53], v[186:189], v[194:197], v[50:53]
	v_mfma_f32_16x16x32_bf16 v[42:45], v[178:181], v[202:205], v[42:45]
	v_mfma_f32_16x16x32_bf16 v[34:37], v[186:189], v[202:205], v[34:37]
	v_mfma_f32_16x16x32_bf16 v[26:29], v[178:181], v[210:213], v[26:29]
	v_mfma_f32_16x16x32_bf16 v[18:21], v[186:189], v[210:213], v[18:21]
	v_mfma_f32_16x16x32_bf16 v[10:13], v[178:181], v[218:221], v[10:13]
	v_mfma_f32_16x16x32_bf16 v[2:5], v[186:189], v[218:221], v[2:5]
	v_mfma_f32_16x16x32_bf16 v[58:61], v[182:185], v[198:201], v[58:61]
	v_mfma_f32_16x16x32_bf16 v[50:53], v[190:193], v[198:201], v[50:53]
	v_mfma_f32_16x16x32_bf16 v[42:45], v[182:185], v[206:209], v[42:45]
	v_mfma_f32_16x16x32_bf16 v[34:37], v[190:193], v[206:209], v[34:37]
	v_mfma_f32_16x16x32_bf16 v[26:29], v[182:185], v[214:217], v[26:29]
	v_mfma_f32_16x16x32_bf16 v[18:21], v[190:193], v[214:217], v[18:21]
	v_mfma_f32_16x16x32_bf16 v[10:13], v[182:185], v[222:225], v[10:13]
	v_mfma_f32_16x16x32_bf16 v[2:5], v[190:193], v[222:225], v[2:5]
	s_barrier
; #define PG8_STAGE(bufoff, gbase, voff) do { _Pragma("unroll") for (int _i = 0; _i < 2; ++_i) \
;         __builtin_amdgcn_global_load_lds((const unsigned*)((const char*)(gbase) + (voff)[_i]), (LAS unsigned*)(lds + (bufoff) + ldsw + _i * 8192), 16, 0, 0); } while (0)
; #define PG8_LDA(dst, b, h) do { _Pragma("unroll") for (int m = 0; m < 4; ++m) _Pragma("unroll") for (int k = 0; k < 2; ++k) dst[m][k] = *(const LAS bf16x8*)(lds + PG8_SA(b, h) + aoff + m * 2048 + k * 1024); } while (0)
; #define PG8_LDB(dst, b, h) do { _Pragma("unroll") for (int n = 0; n < 2; ++n) _Pragma("unroll") for (int k = 0; k < 2; ++k) dst[n][k] = *(const LAS bf16x8*)(lds + PG8_SB(b, h) + boff + n * 2048 + k * 1024); } while (0)
; #define PG8_MMA(ai, bj, At, Bt) do { __builtin_amdgcn_s_setprio(1); _Pragma("unroll") for (int m = 0; m < 4; ++m) _Pragma("unroll") for (int n = 0; n < 2; ++n) _Pragma("unroll") for (int k = 0; k < 2; ++k) \
;         acc[ai][bj][m][n] = __builtin_amdgcn_mfma_f32_16x16x32_bf16(Bt[n][k], At[m][k], acc[ai][bj][m][n], 0, 0, 0); __builtin_amdgcn_s_setprio(0); } while (0)
; #define PG8_WAIT_V(n) asm volatile("s_waitcnt vmcnt(" #n ")" ::: "memory")
; #define PG8_WAIT_L(n) asm volatile("s_waitcnt lgkmcnt(" #n ")" ::: "memory")
; #define PG8_BAR __builtin_amdgcn_s_barrier()
; #define PG8_SCHED __builtin_amdgcn_sched_barrier(0)
; template <class Epi>
; __device__ __forceinline__ void gemm_phase(LAS unsigned char* lds, const Gemm g, const StaticOrder& S, const Epi& E) {
;     ...
;             PG8_LDB(B0, 1, 0); PG8_LDB(B1, 1, 1); PG8_SCHED; PG8_LDA(At, 1, 0); PG8_STAGE(PG8_SA(0, 1), a2 + hstep, voffA);
;             PG8_WAIT_V(8); PG8_WAIT_L(0); PG8_BAR; PG8_MMA(0, 0, At, B0); PG8_MMA(0, 1, At, B1); PG8_BAR; PG8_SCHED;
;             PG8_LDA(At, 1, 1); PG8_STAGE(PG8_SB(1, 0), b3, voffB); PG8_STAGE(PG8_SB(1, 1), b3 + hstep, voffB); PG8_STAGE(PG8_SA(1, 0), a3, voffA);
;             PG8_WAIT_V(8); PG8_WAIT_L(0); PG8_BAR; PG8_MMA(1, 0, At, B0); PG8_MMA(1, 1, At, B1); PG8_BAR; PG8_SCHED;
;         }
;         if (wr == 0) PG8_BAR;
	s_setprio 1
	s_add_i32 s93, 0, 0x18000
	s_add_i32 s94, 0, 0x1c000
	v_add_u32_e32 v174, s93, v148
	v_add_u32_e32 v190, s94, v148
	ds_read_b128 v[158:161], v174
	ds_read_b128 v[162:165], v174 offset:1024
	ds_read_b128 v[166:169], v174 offset:2048
	ds_read_b128 v[174:177], v174 offset:3072
	ds_read_b128 v[178:181], v190
	ds_read_b128 v[182:185], v190 offset:1024
	ds_read_b128 v[186:189], v190 offset:2048
	ds_read_b128 v[190:193], v190 offset:3072
	s_add_u32 s68, s68, 0x40000
	s_addc_u32 s69, s69, 0
	s_mov_b32 m0, s77
	ds_read_b128 v[194:197], v152 offset:32768
	ds_read_b128 v[198:201], v152 offset:33792
	ds_read_b128 v[202:205], v152 offset:34816
	ds_read_b128 v[206:209], v152 offset:35840
	ds_read_b128 v[210:213], v152 offset:36864
	ds_read_b128 v[214:217], v152 offset:37888
	ds_read_b128 v[218:221], v152 offset:38912
	ds_read_b128 v[222:225], v152 offset:39936
	global_load_lds_dwordx4 v130, s[68:69]
	s_mov_b32 m0, s78
	s_nop 0
	global_load_lds_dwordx4 v134, s[68:69]
	s_waitcnt vmcnt(8)
	s_waitcnt lgkmcnt(0)
	s_setprio 0
	s_barrier
	v_mfma_f32_16x16x32_bf16 v[126:129], v[158:161], v[194:197], v[126:129]
	v_mfma_f32_16x16x32_bf16 v[118:121], v[166:169], v[194:197], v[118:121]
	v_mfma_f32_16x16x32_bf16 v[110:113], v[158:161], v[202:205], v[110:113]
	v_mfma_f32_16x16x32_bf16 v[102:105], v[166:169], v[202:205], v[102:105]
	v_mfma_f32_16x16x32_bf16 v[94:97], v[158:161], v[210:213], v[94:97]
	v_mfma_f32_16x16x32_bf16 v[86:89], v[166:169], v[210:213], v[86:89]
	v_mfma_f32_16x16x32_bf16 v[78:81], v[158:161], v[218:221], v[78:81]
	v_mfma_f32_16x16x32_bf16 v[70:73], v[166:169], v[218:221], v[70:73]
	v_mfma_f32_16x16x32_bf16 v[126:129], v[162:165], v[198:201], v[126:129]
	v_mfma_f32_16x16x32_bf16 v[118:121], v[174:177], v[198:201], v[118:121]
	v_mfma_f32_16x16x32_bf16 v[110:113], v[162:165], v[206:209], v[110:113]
	v_mfma_f32_16x16x32_bf16 v[102:105], v[174:177], v[206:209], v[102:105]
	v_mfma_f32_16x16x32_bf16 v[94:97], v[162:165], v[214:217], v[94:97]
	v_mfma_f32_16x16x32_bf16 v[86:89], v[174:177], v[214:217], v[86:89]
	v_mfma_f32_16x16x32_bf16 v[78:81], v[162:165], v[222:225], v[78:81]
	v_mfma_f32_16x16x32_bf16 v[70:73], v[174:177], v[222:225], v[70:73]
	v_mfma_f32_16x16x32_bf16 v[122:125], v[178:181], v[194:197], v[122:125]
	v_mfma_f32_16x16x32_bf16 v[114:117], v[186:189], v[194:197], v[114:117]
	v_mfma_f32_16x16x32_bf16 v[106:109], v[178:181], v[202:205], v[106:109]
	v_mfma_f32_16x16x32_bf16 v[98:101], v[186:189], v[202:205], v[98:101]
	v_mfma_f32_16x16x32_bf16 v[90:93], v[178:181], v[210:213], v[90:93]
	v_mfma_f32_16x16x32_bf16 v[82:85], v[186:189], v[210:213], v[82:85]
	v_mfma_f32_16x16x32_bf16 v[74:77], v[178:181], v[218:221], v[74:77]
	v_mfma_f32_16x16x32_bf16 v[66:69], v[186:189], v[218:221], v[66:69]
	v_mfma_f32_16x16x32_bf16 v[122:125], v[182:185], v[198:201], v[122:125]
	v_mfma_f32_16x16x32_bf16 v[114:117], v[190:193], v[198:201], v[114:117]
	v_mfma_f32_16x16x32_bf16 v[106:109], v[182:185], v[206:209], v[106:109]
	v_mfma_f32_16x16x32_bf16 v[98:101], v[190:193], v[206:209], v[98:101]
	v_mfma_f32_16x16x32_bf16 v[90:93], v[182:185], v[214:217], v[90:93]
	v_mfma_f32_16x16x32_bf16 v[82:85], v[190:193], v[214:217], v[82:85]
	v_mfma_f32_16x16x32_bf16 v[74:77], v[182:185], v[222:225], v[74:77]
	v_mfma_f32_16x16x32_bf16 v[66:69], v[190:193], v[222:225], v[66:69]
	s_barrier
	s_setprio 1
	s_add_i32 s68, s93, s6
	s_mov_b32 m0, s68
	ds_read_b128 v[194:197], v152 offset:49152
	ds_read_b128 v[198:201], v152 offset:50176
	ds_read_b128 v[202:205], v152 offset:51200
	ds_read_b128 v[206:209], v152 offset:52224
	ds_read_b128 v[210:213], v152 offset:53248
	ds_read_b128 v[214:217], v152 offset:54272
	ds_read_b128 v[218:221], v152 offset:55296
	ds_read_b128 v[222:225], v152 offset:56320
	global_load_lds_dwordx4 v132, s[98:99]
	s_add_i32 m0, s68, 0x2000
	s_add_u32 s66, s66, 0x40080
	s_addc_u32 s67, s67, 0
	s_add_i32 s68, s94, s6
	global_load_lds_dwordx4 v136, s[98:99]
	s_mov_b32 m0, s68
	s_nop 0
	global_load_lds_dwordx4 v132, s[66:67]
	s_add_i32 m0, s68, 0x2000
	s_nop 0
	global_load_lds_dwordx4 v136, s[66:67]
	s_mov_b32 m0, s79
	s_nop 0
	global_load_lds_dwordx4 v130, s[100:101]
	s_mov_b32 m0, s80
	s_nop 0
	global_load_lds_dwordx4 v134, s[100:101]
	s_waitcnt vmcnt(8)
	s_waitcnt lgkmcnt(0)
	s_setprio 0
	s_barrier
	v_mfma_f32_16x16x32_bf16 v[62:65], v[158:161], v[194:197], v[62:65]
	v_mfma_f32_16x16x32_bf16 v[54:57], v[166:169], v[194:197], v[54:57]
	v_mfma_f32_16x16x32_bf16 v[46:49], v[158:161], v[202:205], v[46:49]
	v_mfma_f32_16x16x32_bf16 v[38:41], v[166:169], v[202:205], v[38:41]
	v_mfma_f32_16x16x32_bf16 v[30:33], v[158:161], v[210:213], v[30:33]
	v_mfma_f32_16x16x32_bf16 v[22:25], v[166:169], v[210:213], v[22:25]
	v_mfma_f32_16x16x32_bf16 v[14:17], v[158:161], v[218:221], v[14:17]
	v_mfma_f32_16x16x32_bf16 v[6:9], v[166:169], v[218:221], v[6:9]
	v_mfma_f32_16x16x32_bf16 v[62:65], v[162:165], v[198:201], v[62:65]
	v_mfma_f32_16x16x32_bf16 v[54:57], v[174:177], v[198:201], v[54:57]
	v_mfma_f32_16x16x32_bf16 v[46:49], v[162:165], v[206:209], v[46:49]
	v_mfma_f32_16x16x32_bf16 v[38:41], v[174:177], v[206:209], v[38:41]
	v_mfma_f32_16x16x32_bf16 v[30:33], v[162:165], v[214:217], v[30:33]
	v_mfma_f32_16x16x32_bf16 v[22:25], v[174:177], v[214:217], v[22:25]
	v_mfma_f32_16x16x32_bf16 v[14:17], v[162:165], v[222:225], v[14:17]
	v_mfma_f32_16x16x32_bf16 v[6:9], v[174:177], v[222:225], v[6:9]
	v_mfma_f32_16x16x32_bf16 v[58:61], v[178:181], v[194:197], v[58:61]
	v_mfma_f32_16x16x32_bf16 v[50:53], v[186:189], v[194:197], v[50:53]
	v_mfma_f32_16x16x32_bf16 v[42:45], v[178:181], v[202:205], v[42:45]
	v_mfma_f32_16x16x32_bf16 v[34:37], v[186:189], v[202:205], v[34:37]
	v_mfma_f32_16x16x32_bf16 v[26:29], v[178:181], v[210:213], v[26:29]
	v_mfma_f32_16x16x32_bf16 v[18:21], v[186:189], v[210:213], v[18:21]
	v_mfma_f32_16x16x32_bf16 v[10:13], v[178:181], v[218:221], v[10:13]
	v_mfma_f32_16x16x32_bf16 v[2:5], v[186:189], v[218:221], v[2:5]
	v_mfma_f32_16x16x32_bf16 v[58:61], v[182:185], v[198:201], v[58:61]
	v_mfma_f32_16x16x32_bf16 v[50:53], v[190:193], v[198:201], v[50:53]
	v_mfma_f32_16x16x32_bf16 v[42:45], v[182:185], v[206:209], v[42:45]
	v_mfma_f32_16x16x32_bf16 v[34:37], v[190:193], v[206:209], v[34:37]
	v_mfma_f32_16x16x32_bf16 v[26:29], v[182:185], v[214:217], v[26:29]
	v_mfma_f32_16x16x32_bf16 v[18:21], v[190:193], v[214:217], v[18:21]
	v_mfma_f32_16x16x32_bf16 v[10:13], v[182:185], v[222:225], v[10:13]
	v_mfma_f32_16x16x32_bf16 v[2:5], v[190:193], v[222:225], v[2:5]
	s_barrier
	s_setprio 1
	s_add_i32 s92, s92, 2
	s_add_u32 s64, s64, 0x100
	s_addc_u32 s65, s65, 0
	s_add_u32 s90, s90, 0x100
	s_addc_u32 s91, s91, 0
	s_cmp_gt_u32 s92, 13
	s_cbranch_scc0 .LBB0_134
	s_and_b64 vcc, exec, s[38:39]
	s_cbranch_vccz .LBB0_137
	s_barrier

; #define PG8_STAGE(bufoff, gbase, voff) do { _Pragma("unroll") for (int _i = 0; _i < 2; ++_i) \
;         __builtin_amdgcn_global_load_lds((const unsigned*)((const char*)(gbase) + (voff)[_i]), (LAS unsigned*)(lds + (bufoff) + ldsw + _i * 8192), 16, 0, 0); } while (0)
; #define PG8_LDA(dst, b, h) do { _Pragma("unroll") for (int m = 0; m < 4; ++m) _Pragma("unroll") for (int k = 0; k < 2; ++k) dst[m][k] = *(const LAS bf16x8*)(lds + PG8_SA(b, h) + aoff + m * 2048 + k * 1024); } while (0)
; #define PG8_LDB(dst, b, h) do { _Pragma("unroll") for (int n = 0; n < 2; ++n) _Pragma("unroll") for (int k = 0; k < 2; ++k) dst[n][k] = *(const LAS bf16x8*)(lds + PG8_SB(b, h) + boff + n * 2048 + k * 1024); } while (0)
; #define PG8_MMA(ai, bj, At, Bt) do { __builtin_amdgcn_s_setprio(1); _Pragma("unroll") for (int m = 0; m < 4; ++m) _Pragma("unroll") for (int n = 0; n < 2; ++n) _Pragma("unroll") for (int k = 0; k < 2; ++k) \
;         acc[ai][bj][m][n] = __builtin_amdgcn_mfma_f32_16x16x32_bf16(Bt[n][k], At[m][k], acc[ai][bj][m][n], 0, 0, 0); __builtin_amdgcn_s_setprio(0); } while (0)
; #define PG8_WAIT_V(n) asm volatile("s_waitcnt vmcnt(" #n ")" ::: "memory")
; #define PG8_WAIT_L(n) asm volatile("s_waitcnt lgkmcnt(" #n ")" ::: "memory")
; #define PG8_BAR __builtin_amdgcn_s_barrier()
; template <class Epi>
; __device__ __forceinline__ void gemm_phase(LAS unsigned char* lds, const Gemm g, const StaticOrder& S, const Epi& E) {
;     ...
;         for (int t = 0; t < nt; t += 2) {
;             const bool last = (t == nt - 2);
;             const char* a1 = cA + (size_t)(t + 1) * kstep;
;             const char* a2 = last ? nA : cA + (size_t)(t + 2) * kstep; const char* b2 = last ? nB : cB + (size_t)(t + 2) * kstep;
;             const char* a3 = a2 + kstep; const char* b3 = b2 + kstep;
;             if constexpr (Epi::MIDK > 0) { if (t == Epi::MIDK) E.mid(acc, cur, wr, wc, fr, fq); }
;             PG8_LDB(B0, 0, 0); PG8_LDB(B1, 0, 1); PG8_SCHED; PG8_LDA(At, 0, 0); PG8_STAGE(PG8_SA(1, 1), a1 + hstep, voffA);
;             PG8_WAIT_V(8); PG8_WAIT_L(0); PG8_BAR; PG8_MMA(0, 0, At, B0); PG8_MMA(0, 1, At, B1); PG8_BAR; PG8_SCHED;
;             PG8_LDA(At, 0, 1); PG8_STAGE(PG8_SB(0, 0), b2, voffB); PG8_STAGE(PG8_SB(0, 1), b2 + hstep, voffB); PG8_STAGE(PG8_SA(0, 0), a2, voffA);
;             PG8_WAIT_V(8); PG8_WAIT_L(0); PG8_BAR; PG8_MMA(1, 0, At, B0); PG8_MMA(1, 1, At, B1); PG8_BAR; PG8_SCHED;
.LBB0_221:
	ds_read_b128 v[130:133], v162
	ds_read_b128 v[134:137], v162 offset:1024
	ds_read_b128 v[154:157], v162 offset:2048
	ds_read_b128 v[166:169], v162 offset:3072
	ds_read_b128 v[174:177], v163
	ds_read_b128 v[178:181], v163 offset:1024
	ds_read_b128 v[182:185], v163 offset:2048
	ds_read_b128 v[186:189], v163 offset:3072
	s_add_u32 s48, s46, 0xfff50080
	s_addc_u32 s49, s47, -1
	s_cmp_eq_u32 s84, 40
	s_cselect_b32 s51, s5, s49
	s_cselect_b32 s50, s4, s48
	s_cselect_b32 s49, s45, s83
	s_cselect_b32 s48, s44, s82
	s_add_i32 m0, s59, 0xc000
	ds_read_b128 v[190:193], v164
	ds_read_b128 v[194:197], v164 offset:1024
	ds_read_b128 v[198:201], v164 offset:2048
	ds_read_b128 v[202:205], v164 offset:3072
	ds_read_b128 v[206:209], v164 offset:4096
	ds_read_b128 v[210:213], v164 offset:5120
	ds_read_b128 v[214:217], v164 offset:6144
	ds_read_b128 v[218:221], v164 offset:7168
	global_load_lds_dwordx4 v146, s[46:47]
	s_add_i32 m0, s59, 0xe000
	s_nop 0
	global_load_lds_dwordx4 v148, s[46:47]
	s_waitcnt vmcnt(8)
	s_waitcnt lgkmcnt(0)
	s_setprio 0
	s_barrier
	v_mfma_f32_16x16x32_bf16 v[126:129], v[130:133], v[190:193], v[126:129]
	v_mfma_f32_16x16x32_bf16 v[122:125], v[154:157], v[190:193], v[122:125]
	v_mfma_f32_16x16x32_bf16 v[110:113], v[130:133], v[198:201], v[110:113]
	v_mfma_f32_16x16x32_bf16 v[106:109], v[154:157], v[198:201], v[106:109]
	v_mfma_f32_16x16x32_bf16 v[94:97], v[130:133], v[206:209], v[94:97]
	v_mfma_f32_16x16x32_bf16 v[90:93], v[154:157], v[206:209], v[90:93]
	v_mfma_f32_16x16x32_bf16 v[78:81], v[130:133], v[214:217], v[78:81]
	v_mfma_f32_16x16x32_bf16 v[74:77], v[154:157], v[214:217], v[74:77]
	v_mfma_f32_16x16x32_bf16 v[126:129], v[134:137], v[194:197], v[126:129]
	v_mfma_f32_16x16x32_bf16 v[122:125], v[166:169], v[194:197], v[122:125]
	v_mfma_f32_16x16x32_bf16 v[110:113], v[134:137], v[202:205], v[110:113]
	v_mfma_f32_16x16x32_bf16 v[106:109], v[166:169], v[202:205], v[106:109]
	v_mfma_f32_16x16x32_bf16 v[94:97], v[134:137], v[210:213], v[94:97]
	v_mfma_f32_16x16x32_bf16 v[90:93], v[166:169], v[210:213], v[90:93]
	v_mfma_f32_16x16x32_bf16 v[78:81], v[134:137], v[218:221], v[78:81]
	v_mfma_f32_16x16x32_bf16 v[74:77], v[166:169], v[218:221], v[74:77]
	v_mfma_f32_16x16x32_bf16 v[118:121], v[174:177], v[190:193], v[118:121]
	v_mfma_f32_16x16x32_bf16 v[114:117], v[182:185], v[190:193], v[114:117]
	v_mfma_f32_16x16x32_bf16 v[102:105], v[174:177], v[198:201], v[102:105]
	v_mfma_f32_16x16x32_bf16 v[98:101], v[182:185], v[198:201], v[98:101]
	v_mfma_f32_16x16x32_bf16 v[86:89], v[174:177], v[206:209], v[86:89]
	v_mfma_f32_16x16x32_bf16 v[82:85], v[182:185], v[206:209], v[82:85]
	v_mfma_f32_16x16x32_bf16 v[70:73], v[174:177], v[214:217], v[70:73]
	v_mfma_f32_16x16x32_bf16 v[66:69], v[182:185], v[214:217], v[66:69]
	v_mfma_f32_16x16x32_bf16 v[118:121], v[178:181], v[194:197], v[118:121]
	v_mfma_f32_16x16x32_bf16 v[114:117], v[186:189], v[194:197], v[114:117]
	v_mfma_f32_16x16x32_bf16 v[102:105], v[178:181], v[202:205], v[102:105]
	v_mfma_f32_16x16x32_bf16 v[98:101], v[186:189], v[202:205], v[98:101]
	v_mfma_f32_16x16x32_bf16 v[86:89], v[178:181], v[210:213], v[86:89]
	v_mfma_f32_16x16x32_bf16 v[82:85], v[186:189], v[210:213], v[82:85]
	v_mfma_f32_16x16x32_bf16 v[70:73], v[178:181], v[218:221], v[70:73]
	v_mfma_f32_16x16x32_bf16 v[66:69], v[186:189], v[218:221], v[66:69]
	s_barrier
	s_setprio 1
	s_add_u32 s98, s48, s38
	s_addc_u32 s99, s49, s39
	s_add_u32 s100, s50, s38
	s_addc_u32 s101, s51, s39
	s_add_i32 s85, s76, s58
	s_mov_b32 m0, s85
	ds_read_b128 v[190:193], v164 offset:16384
	ds_read_b128 v[194:197], v164 offset:17408
	ds_read_b128 v[198:201], v164 offset:18432
	ds_read_b128 v[202:205], v164 offset:19456
	ds_read_b128 v[206:209], v164 offset:20480
	ds_read_b128 v[210:213], v164 offset:21504
	ds_read_b128 v[214:217], v164 offset:22528
	ds_read_b128 v[218:221], v164 offset:23552
	global_load_lds_dwordx4 v140, s[48:49]
	s_add_i32 m0, s85, 0x2000
	s_add_u32 s86, s48, 0xb0000
	s_addc_u32 s87, s49, 0
	s_add_i32 s85, s77, s58
	global_load_lds_dwordx4 v144, s[48:49]
	s_mov_b32 m0, s85
	s_nop 0
	global_load_lds_dwordx4 v140, s[86:87]
	s_add_i32 m0, s85, 0x2000
	s_nop 0
	global_load_lds_dwordx4 v144, s[86:87]
	s_mov_b32 m0, s59
	s_nop 0
	global_load_lds_dwordx4 v138, s[50:51]
	s_mov_b32 m0, s60
	s_nop 0
	global_load_lds_dwordx4 v142, s[50:51]
	s_waitcnt vmcnt(8)
	s_waitcnt lgkmcnt(0)
	s_setprio 0
	s_barrier
	v_mfma_f32_16x16x32_bf16 v[62:65], v[130:133], v[190:193], v[62:65]
	v_mfma_f32_16x16x32_bf16 v[58:61], v[154:157], v[190:193], v[58:61]
	v_mfma_f32_16x16x32_bf16 v[46:49], v[130:133], v[198:201], v[46:49]
	v_mfma_f32_16x16x32_bf16 v[42:45], v[154:157], v[198:201], v[42:45]
	v_mfma_f32_16x16x32_bf16 v[30:33], v[130:133], v[206:209], v[30:33]
	v_mfma_f32_16x16x32_bf16 v[26:29], v[154:157], v[206:209], v[26:29]
	v_mfma_f32_16x16x32_bf16 v[14:17], v[130:133], v[214:217], v[14:17]
	v_mfma_f32_16x16x32_bf16 v[10:13], v[154:157], v[214:217], v[10:13]
	v_mfma_f32_16x16x32_bf16 v[62:65], v[134:137], v[194:197], v[62:65]
	v_mfma_f32_16x16x32_bf16 v[58:61], v[166:169], v[194:197], v[58:61]
	v_mfma_f32_16x16x32_bf16 v[46:49], v[134:137], v[202:205], v[46:49]
	v_mfma_f32_16x16x32_bf16 v[42:45], v[166:169], v[202:205], v[42:45]
	v_mfma_f32_16x16x32_bf16 v[30:33], v[134:137], v[210:213], v[30:33]
	v_mfma_f32_16x16x32_bf16 v[26:29], v[166:169], v[210:213], v[26:29]
	v_mfma_f32_16x16x32_bf16 v[14:17], v[134:137], v[218:221], v[14:17]
	v_mfma_f32_16x16x32_bf16 v[10:13], v[166:169], v[218:221], v[10:13]
	v_mfma_f32_16x16x32_bf16 v[54:57], v[174:177], v[190:193], v[54:57]
	v_mfma_f32_16x16x32_bf16 v[50:53], v[182:185], v[190:193], v[50:53]
	v_mfma_f32_16x16x32_bf16 v[38:41], v[174:177], v[198:201], v[38:41]
	v_mfma_f32_16x16x32_bf16 v[34:37], v[182:185], v[198:201], v[34:37]
	v_mfma_f32_16x16x32_bf16 v[22:25], v[174:177], v[206:209], v[22:25]
	v_mfma_f32_16x16x32_bf16 v[18:21], v[182:185], v[206:209], v[18:21]
	v_mfma_f32_16x16x32_bf16 v[6:9], v[174:177], v[214:217], v[6:9]
	v_mfma_f32_16x16x32_bf16 v[2:5], v[182:185], v[214:217], v[2:5]
	v_mfma_f32_16x16x32_bf16 v[54:57], v[178:181], v[194:197], v[54:57]
	v_mfma_f32_16x16x32_bf16 v[50:53], v[186:189], v[194:197], v[50:53]
	v_mfma_f32_16x16x32_bf16 v[38:41], v[178:181], v[202:205], v[38:41]
	v_mfma_f32_16x16x32_bf16 v[34:37], v[186:189], v[202:205], v[34:37]
	v_mfma_f32_16x16x32_bf16 v[22:25], v[178:181], v[210:213], v[22:25]
	v_mfma_f32_16x16x32_bf16 v[18:21], v[186:189], v[210:213], v[18:21]
	v_mfma_f32_16x16x32_bf16 v[6:9], v[178:181], v[218:221], v[6:9]
	v_mfma_f32_16x16x32_bf16 v[2:5], v[186:189], v[218:221], v[2:5]
	s_barrier
; #define PG8_STAGE(bufoff, gbase, voff) do { _Pragma("unroll") for (int _i = 0; _i < 2; ++_i) \
;         __builtin_amdgcn_global_load_lds((const unsigned*)((const char*)(gbase) + (voff)[_i]), (LAS unsigned*)(lds + (bufoff) + ldsw + _i * 8192), 16, 0, 0); } while (0)
; #define PG8_LDA(dst, b, h) do { _Pragma("unroll") for (int m = 0; m < 4; ++m) _Pragma("unroll") for (int k = 0; k < 2; ++k) dst[m][k] = *(const LAS bf16x8*)(lds + PG8_SA(b, h) + aoff + m * 2048 + k * 1024); } while (0)
; #define PG8_LDB(dst, b, h) do { _Pragma("unroll") for (int n = 0; n < 2; ++n) _Pragma("unroll") for (int k = 0; k < 2; ++k) dst[n][k] = *(const LAS bf16x8*)(lds + PG8_SB(b, h) + boff + n * 2048 + k * 1024); } while (0)
; #define PG8_MMA(ai, bj, At, Bt) do { __builtin_amdgcn_s_setprio(1); _Pragma("unroll") for (int m = 0; m < 4; ++m) _Pragma("unroll") for (int n = 0; n < 2; ++n) _Pragma("unroll") for (int k = 0; k < 2; ++k) \
;         acc[ai][bj][m][n] = __builtin_amdgcn_mfma_f32_16x16x32_bf16(Bt[n][k], At[m][k], acc[ai][bj][m][n], 0, 0, 0); __builtin_amdgcn_s_setprio(0); } while (0)
; #define PG8_WAIT_V(n) asm volatile("s_waitcnt vmcnt(" #n ")" ::: "memory")
; #define PG8_WAIT_L(n) asm volatile("s_waitcnt lgkmcnt(" #n ")" ::: "memory")
; #define PG8_BAR __builtin_amdgcn_s_barrier()
; #define PG8_SCHED __builtin_amdgcn_sched_barrier(0)
; template <class Epi>
; __device__ __forceinline__ void gemm_phase(LAS unsigned char* lds, const Gemm g, const StaticOrder& S, const Epi& E) {
;     ...
;             PG8_LDB(B0, 1, 0); PG8_LDB(B1, 1, 1); PG8_SCHED; PG8_LDA(At, 1, 0); PG8_STAGE(PG8_SA(0, 1), a2 + hstep, voffA);
;             PG8_WAIT_V(8); PG8_WAIT_L(0); PG8_BAR; PG8_MMA(0, 0, At, B0); PG8_MMA(0, 1, At, B1); PG8_BAR; PG8_SCHED;
;             PG8_LDA(At, 1, 1); PG8_STAGE(PG8_SB(1, 0), b3, voffB); PG8_STAGE(PG8_SB(1, 1), b3 + hstep, voffB); PG8_STAGE(PG8_SA(1, 0), a3, voffA);
;             PG8_WAIT_V(8); PG8_WAIT_L(0); PG8_BAR; PG8_MMA(1, 0, At, B0); PG8_MMA(1, 1, At, B1); PG8_BAR; PG8_SCHED;
;         }
;         if (wr == 0) PG8_BAR;
	s_setprio 1
	s_add_i32 s85, 0, 0x18000
	s_add_i32 s86, 0, 0x1c000
	v_add_u32_e32 v166, s85, v160
	v_add_u32_e32 v186, s86, v160
	ds_read_b128 v[130:133], v166
	ds_read_b128 v[134:137], v166 offset:1024
	ds_read_b128 v[154:157], v166 offset:2048
	ds_read_b128 v[166:169], v166 offset:3072
	ds_read_b128 v[174:177], v186
	ds_read_b128 v[178:181], v186 offset:1024
	ds_read_b128 v[182:185], v186 offset:2048
	ds_read_b128 v[186:189], v186 offset:3072
	s_add_u32 s50, s50, 0xb0000
	s_addc_u32 s51, s51, 0
	s_mov_b32 m0, s61
	ds_read_b128 v[190:193], v164 offset:32768
	ds_read_b128 v[194:197], v164 offset:33792
	ds_read_b128 v[198:201], v164 offset:34816
	ds_read_b128 v[202:205], v164 offset:35840
	ds_read_b128 v[206:209], v164 offset:36864
	ds_read_b128 v[210:213], v164 offset:37888
	ds_read_b128 v[214:217], v164 offset:38912
	ds_read_b128 v[218:221], v164 offset:39936
	global_load_lds_dwordx4 v138, s[50:51]
	s_mov_b32 m0, s62
	s_nop 0
	global_load_lds_dwordx4 v142, s[50:51]
	s_waitcnt vmcnt(8)
	s_waitcnt lgkmcnt(0)
	s_setprio 0
	s_barrier
	v_mfma_f32_16x16x32_bf16 v[126:129], v[130:133], v[190:193], v[126:129]
	v_mfma_f32_16x16x32_bf16 v[122:125], v[154:157], v[190:193], v[122:125]
	v_mfma_f32_16x16x32_bf16 v[110:113], v[130:133], v[198:201], v[110:113]
	v_mfma_f32_16x16x32_bf16 v[106:109], v[154:157], v[198:201], v[106:109]
	v_mfma_f32_16x16x32_bf16 v[94:97], v[130:133], v[206:209], v[94:97]
	v_mfma_f32_16x16x32_bf16 v[90:93], v[154:157], v[206:209], v[90:93]
	v_mfma_f32_16x16x32_bf16 v[78:81], v[130:133], v[214:217], v[78:81]
	v_mfma_f32_16x16x32_bf16 v[74:77], v[154:157], v[214:217], v[74:77]
	v_mfma_f32_16x16x32_bf16 v[126:129], v[134:137], v[194:197], v[126:129]
	v_mfma_f32_16x16x32_bf16 v[122:125], v[166:169], v[194:197], v[122:125]
	v_mfma_f32_16x16x32_bf16 v[110:113], v[134:137], v[202:205], v[110:113]
	v_mfma_f32_16x16x32_bf16 v[106:109], v[166:169], v[202:205], v[106:109]
	v_mfma_f32_16x16x32_bf16 v[94:97], v[134:137], v[210:213], v[94:97]
	v_mfma_f32_16x16x32_bf16 v[90:93], v[166:169], v[210:213], v[90:93]
	v_mfma_f32_16x16x32_bf16 v[78:81], v[134:137], v[218:221], v[78:81]
	v_mfma_f32_16x16x32_bf16 v[74:77], v[166:169], v[218:221], v[74:77]
	v_mfma_f32_16x16x32_bf16 v[118:121], v[174:177], v[190:193], v[118:121]
	v_mfma_f32_16x16x32_bf16 v[114:117], v[182:185], v[190:193], v[114:117]
	v_mfma_f32_16x16x32_bf16 v[102:105], v[174:177], v[198:201], v[102:105]
	v_mfma_f32_16x16x32_bf16 v[98:101], v[182:185], v[198:201], v[98:101]
	v_mfma_f32_16x16x32_bf16 v[86:89], v[174:177], v[206:209], v[86:89]
	v_mfma_f32_16x16x32_bf16 v[82:85], v[182:185], v[206:209], v[82:85]
	v_mfma_f32_16x16x32_bf16 v[70:73], v[174:177], v[214:217], v[70:73]
	v_mfma_f32_16x16x32_bf16 v[66:69], v[182:185], v[214:217], v[66:69]
	v_mfma_f32_16x16x32_bf16 v[118:121], v[178:181], v[194:197], v[118:121]
	v_mfma_f32_16x16x32_bf16 v[114:117], v[186:189], v[194:197], v[114:117]
	v_mfma_f32_16x16x32_bf16 v[102:105], v[178:181], v[202:205], v[102:105]
	v_mfma_f32_16x16x32_bf16 v[98:101], v[186:189], v[202:205], v[98:101]
	v_mfma_f32_16x16x32_bf16 v[86:89], v[178:181], v[210:213], v[86:89]
	v_mfma_f32_16x16x32_bf16 v[82:85], v[186:189], v[210:213], v[82:85]
	v_mfma_f32_16x16x32_bf16 v[70:73], v[178:181], v[218:221], v[70:73]
	v_mfma_f32_16x16x32_bf16 v[66:69], v[186:189], v[218:221], v[66:69]
	s_barrier
	s_setprio 1
	s_add_i32 s50, s85, s58
	s_mov_b32 m0, s50
	ds_read_b128 v[190:193], v164 offset:49152
	ds_read_b128 v[194:197], v164 offset:50176
	ds_read_b128 v[198:201], v164 offset:51200
	ds_read_b128 v[202:205], v164 offset:52224
	ds_read_b128 v[206:209], v164 offset:53248
	ds_read_b128 v[210:213], v164 offset:54272
	ds_read_b128 v[214:217], v164 offset:55296
	ds_read_b128 v[218:221], v164 offset:56320
	global_load_lds_dwordx4 v140, s[98:99]
	s_add_i32 m0, s50, 0x2000
	s_add_u32 s48, s48, 0xb0080
	s_addc_u32 s49, s49, 0
	s_add_i32 s50, s86, s58
	global_load_lds_dwordx4 v144, s[98:99]
	s_mov_b32 m0, s50
	s_nop 0
	global_load_lds_dwordx4 v140, s[48:49]
	s_add_i32 m0, s50, 0x2000
	s_nop 0
	global_load_lds_dwordx4 v144, s[48:49]
	s_mov_b32 m0, s64
	s_nop 0
	global_load_lds_dwordx4 v138, s[100:101]
	s_mov_b32 m0, s65
	s_nop 0
	global_load_lds_dwordx4 v142, s[100:101]
	s_waitcnt vmcnt(8)
	s_waitcnt lgkmcnt(0)
	s_setprio 0
	s_barrier
	v_mfma_f32_16x16x32_bf16 v[62:65], v[130:133], v[190:193], v[62:65]
	v_mfma_f32_16x16x32_bf16 v[58:61], v[154:157], v[190:193], v[58:61]
	v_mfma_f32_16x16x32_bf16 v[46:49], v[130:133], v[198:201], v[46:49]
	v_mfma_f32_16x16x32_bf16 v[42:45], v[154:157], v[198:201], v[42:45]
	v_mfma_f32_16x16x32_bf16 v[30:33], v[130:133], v[206:209], v[30:33]
	v_mfma_f32_16x16x32_bf16 v[26:29], v[154:157], v[206:209], v[26:29]
	v_mfma_f32_16x16x32_bf16 v[14:17], v[130:133], v[214:217], v[14:17]
	v_mfma_f32_16x16x32_bf16 v[10:13], v[154:157], v[214:217], v[10:13]
	v_mfma_f32_16x16x32_bf16 v[62:65], v[134:137], v[194:197], v[62:65]
	v_mfma_f32_16x16x32_bf16 v[58:61], v[166:169], v[194:197], v[58:61]
	v_mfma_f32_16x16x32_bf16 v[46:49], v[134:137], v[202:205], v[46:49]
	v_mfma_f32_16x16x32_bf16 v[42:45], v[166:169], v[202:205], v[42:45]
	v_mfma_f32_16x16x32_bf16 v[30:33], v[134:137], v[210:213], v[30:33]
	v_mfma_f32_16x16x32_bf16 v[26:29], v[166:169], v[210:213], v[26:29]
	v_mfma_f32_16x16x32_bf16 v[14:17], v[134:137], v[218:221], v[14:17]
	v_mfma_f32_16x16x32_bf16 v[10:13], v[166:169], v[218:221], v[10:13]
	v_mfma_f32_16x16x32_bf16 v[54:57], v[174:177], v[190:193], v[54:57]
	v_mfma_f32_16x16x32_bf16 v[50:53], v[182:185], v[190:193], v[50:53]
	v_mfma_f32_16x16x32_bf16 v[38:41], v[174:177], v[198:201], v[38:41]
	v_mfma_f32_16x16x32_bf16 v[34:37], v[182:185], v[198:201], v[34:37]
	v_mfma_f32_16x16x32_bf16 v[22:25], v[174:177], v[206:209], v[22:25]
	v_mfma_f32_16x16x32_bf16 v[18:21], v[182:185], v[206:209], v[18:21]
	v_mfma_f32_16x16x32_bf16 v[6:9], v[174:177], v[214:217], v[6:9]
	v_mfma_f32_16x16x32_bf16 v[2:5], v[182:185], v[214:217], v[2:5]
	v_mfma_f32_16x16x32_bf16 v[54:57], v[178:181], v[194:197], v[54:57]
	v_mfma_f32_16x16x32_bf16 v[50:53], v[186:189], v[194:197], v[50:53]
	v_mfma_f32_16x16x32_bf16 v[38:41], v[178:181], v[202:205], v[38:41]
	v_mfma_f32_16x16x32_bf16 v[34:37], v[186:189], v[202:205], v[34:37]
	v_mfma_f32_16x16x32_bf16 v[22:25], v[178:181], v[210:213], v[22:25]
	v_mfma_f32_16x16x32_bf16 v[18:21], v[186:189], v[210:213], v[18:21]
	v_mfma_f32_16x16x32_bf16 v[6:9], v[178:181], v[218:221], v[6:9]
	v_mfma_f32_16x16x32_bf16 v[2:5], v[186:189], v[218:221], v[2:5]
	s_barrier
	s_setprio 1
	s_add_i32 s84, s84, 2
	s_add_u32 s46, s46, 0x100
	s_addc_u32 s47, s47, 0
	s_add_u32 s82, s82, 0x100
	s_addc_u32 s83, s83, 0
	s_cmp_gt_u32 s84, 41
	s_cbranch_scc0 .LBB0_221
	s_and_b64 vcc, exec, s[42:43]
	s_cbranch_vccz .LBB0_224
	s_barrier

; #define PG8_STAGE(bufoff, gbase, voff) do { _Pragma("unroll") for (int _i = 0; _i < 2; ++_i) \
;         __builtin_amdgcn_global_load_lds((const unsigned*)((const char*)(gbase) + (voff)[_i]), (LAS unsigned*)(lds + (bufoff) + ldsw + _i * 8192), 16, 0, 0); } while (0)
; #define PG8_LDA(dst, b, h) do { _Pragma("unroll") for (int m = 0; m < 4; ++m) _Pragma("unroll") for (int k = 0; k < 2; ++k) dst[m][k] = *(const LAS bf16x8*)(lds + PG8_SA(b, h) + aoff + m * 2048 + k * 1024); } while (0)
; #define PG8_LDB(dst, b, h) do { _Pragma("unroll") for (int n = 0; n < 2; ++n) _Pragma("unroll") for (int k = 0; k < 2; ++k) dst[n][k] = *(const LAS bf16x8*)(lds + PG8_SB(b, h) + boff + n * 2048 + k * 1024); } while (0)
; #define PG8_BAR __builtin_amdgcn_s_barrier()
; template <class Epi>
; __device__ __forceinline__ void gemm_phase(LAS unsigned char* lds, const Gemm g, const StaticOrder& S, const Epi& E) {
;     ...
;         for (int t = 0; t < nt; t += 2) {
;             const bool last = (t == nt - 2);
;             const char* a1 = cA + (size_t)(t + 1) * kstep;
;             const char* a2 = last ? nA : cA + (size_t)(t + 2) * kstep; const char* b2 = last ? nB : cB + (size_t)(t + 2) * kstep;
;             const char* a3 = a2 + kstep; const char* b3 = b2 + kstep;
;             if constexpr (Epi::MIDK > 0) { if (t == Epi::MIDK) E.mid(acc, cur, wr, wc, fr, fq); }
;             PG8_LDB(B0, 0, 0); PG8_LDB(B1, 0, 1); PG8_SCHED; PG8_LDA(At, 0, 0); PG8_STAGE(PG8_SA(1, 1), a1 + hstep, voffA);
;             PG8_WAIT_V(8); PG8_WAIT_L(0); PG8_BAR; PG8_MMA(0, 0, At, B0); PG8_MMA(0, 1, At, B1); PG8_BAR; PG8_SCHED;
;             PG8_LDA(At, 0, 1); PG8_STAGE(PG8_SB(0, 0), b2, voffB); PG8_STAGE(PG8_SB(0, 1), b2 + hstep, voffB); PG8_STAGE(PG8_SA(0, 0), a2, voffA);
;             PG8_WAIT_V(8); PG8_WAIT_L(0); PG8_BAR; PG8_MMA(1, 0, At, B0); PG8_MMA(1, 1, At, B1); PG8_BAR; PG8_SCHED;
;             PG8_LDB(B0, 1, 0); PG8_LDB(B1, 1, 1); PG8_SCHED; PG8_LDA(At, 1, 0); PG8_STAGE(PG8_SA(0, 1), a2 + hstep, voffA);
;             PG8_WAIT_V(8); PG8_WAIT_L(0); PG8_BAR; PG8_MMA(0, 0, At, B0); PG8_MMA(0, 1, At, B1); PG8_BAR; PG8_SCHED;
;             PG8_LDA(At, 1, 1); PG8_STAGE(PG8_SB(1, 0), b3, voffB); PG8_STAGE(PG8_SB(1, 1), b3 + hstep, voffB); PG8_STAGE(PG8_SA(1, 0), a3, voffA);
;             PG8_WAIT_V(8); PG8_WAIT_L(0); PG8_BAR; PG8_MMA(1, 0, At, B0); PG8_MMA(1, 1, At, B1); PG8_BAR; PG8_SCHED;
.LBB0_322:
	ds_read_b128 v[130:133], v191
	ds_read_b128 v[134:137], v191 offset:1024
	ds_read_b128 v[138:141], v191 offset:2048
	ds_read_b128 v[142:145], v191 offset:3072
	ds_read_b128 v[166:169], v193
	ds_read_b128 v[172:175], v193 offset:1024
	ds_read_b128 v[176:179], v193 offset:2048
	ds_read_b128 v[180:183], v193 offset:3072
	s_add_u32 s76, s88, 0xfffc0080
	s_addc_u32 s77, s89, -1
	s_cmp_eq_u32 vcc_hi, 12
	s_cselect_b32 s93, s1, s77
	s_cselect_b32 s92, s7, s76
	s_cselect_b32 s91, s9, vcc_lo
	s_cselect_b32 s90, s46, s81
	s_add_i32 m0, s96, 0xc000
	ds_read_b128 v[200:203], v194
	ds_read_b128 v[204:207], v194 offset:1024
	ds_read_b128 v[208:211], v194 offset:2048
	ds_read_b128 v[212:215], v194 offset:3072
	ds_read_b128 v[216:219], v194 offset:4096
	ds_read_b128 v[220:223], v194 offset:5120
	ds_read_b128 v[224:227], v194 offset:6144
	ds_read_b128 v[228:231], v194 offset:7168
	global_load_lds_dwordx4 v158, s[88:89]
	s_add_i32 m0, s96, 0xe000
	s_nop 0
	global_load_lds_dwordx4 v160, s[88:89]
	s_waitcnt vmcnt(8)
	s_waitcnt lgkmcnt(0)
	s_setprio 0
	s_barrier
	v_mfma_f32_16x16x32_bf16 v[126:129], v[130:133], v[200:203], v[126:129]
	v_mfma_f32_16x16x32_bf16 v[122:125], v[138:141], v[200:203], v[122:125]
	v_mfma_f32_16x16x32_bf16 v[110:113], v[130:133], v[208:211], v[110:113]
	v_mfma_f32_16x16x32_bf16 v[106:109], v[138:141], v[208:211], v[106:109]
	v_mfma_f32_16x16x32_bf16 v[94:97], v[130:133], v[216:219], v[94:97]
	v_mfma_f32_16x16x32_bf16 v[90:93], v[138:141], v[216:219], v[90:93]
	v_mfma_f32_16x16x32_bf16 v[78:81], v[130:133], v[224:227], v[78:81]
	v_mfma_f32_16x16x32_bf16 v[74:77], v[138:141], v[224:227], v[74:77]
	v_mfma_f32_16x16x32_bf16 v[126:129], v[134:137], v[204:207], v[126:129]
	v_mfma_f32_16x16x32_bf16 v[122:125], v[142:145], v[204:207], v[122:125]
	v_mfma_f32_16x16x32_bf16 v[110:113], v[134:137], v[212:215], v[110:113]
	v_mfma_f32_16x16x32_bf16 v[106:109], v[142:145], v[212:215], v[106:109]
	v_mfma_f32_16x16x32_bf16 v[94:97], v[134:137], v[220:223], v[94:97]
	v_mfma_f32_16x16x32_bf16 v[90:93], v[142:145], v[220:223], v[90:93]
	v_mfma_f32_16x16x32_bf16 v[78:81], v[134:137], v[228:231], v[78:81]
	v_mfma_f32_16x16x32_bf16 v[74:77], v[142:145], v[228:231], v[74:77]
	v_mfma_f32_16x16x32_bf16 v[118:121], v[166:169], v[200:203], v[118:121]
	v_mfma_f32_16x16x32_bf16 v[114:117], v[176:179], v[200:203], v[114:117]
	v_mfma_f32_16x16x32_bf16 v[102:105], v[166:169], v[208:211], v[102:105]
	v_mfma_f32_16x16x32_bf16 v[98:101], v[176:179], v[208:211], v[98:101]
	v_mfma_f32_16x16x32_bf16 v[86:89], v[166:169], v[216:219], v[86:89]
	v_mfma_f32_16x16x32_bf16 v[82:85], v[176:179], v[216:219], v[82:85]
	v_mfma_f32_16x16x32_bf16 v[70:73], v[166:169], v[224:227], v[70:73]
	v_mfma_f32_16x16x32_bf16 v[66:69], v[176:179], v[224:227], v[66:69]
	v_mfma_f32_16x16x32_bf16 v[118:121], v[172:175], v[204:207], v[118:121]
	v_mfma_f32_16x16x32_bf16 v[114:117], v[180:183], v[204:207], v[114:117]
	v_mfma_f32_16x16x32_bf16 v[102:105], v[172:175], v[212:215], v[102:105]
	v_mfma_f32_16x16x32_bf16 v[98:101], v[180:183], v[212:215], v[98:101]
	v_mfma_f32_16x16x32_bf16 v[86:89], v[172:175], v[220:223], v[86:89]
	v_mfma_f32_16x16x32_bf16 v[82:85], v[180:183], v[220:223], v[82:85]
	v_mfma_f32_16x16x32_bf16 v[70:73], v[172:175], v[228:231], v[70:73]
	v_mfma_f32_16x16x32_bf16 v[66:69], v[180:183], v[228:231], v[66:69]
	s_barrier
	s_setprio 1
	s_add_u32 s98, s90, s50
	s_addc_u32 s99, s91, s51
	s_add_u32 s100, s92, s50
	s_addc_u32 s101, s93, s51
	s_add_i32 s76, s42, s44
	s_mov_b32 m0, s76
	ds_read_b128 v[200:203], v194 offset:16384
	ds_read_b128 v[204:207], v194 offset:17408
	ds_read_b128 v[208:211], v194 offset:18432
	ds_read_b128 v[212:215], v194 offset:19456
	ds_read_b128 v[216:219], v194 offset:20480
	ds_read_b128 v[220:223], v194 offset:21504
	ds_read_b128 v[224:227], v194 offset:22528
	ds_read_b128 v[228:231], v194 offset:23552
	global_load_lds_dwordx4 v148, s[90:91]
	s_add_i32 m0, s76, 0x2000
	s_add_u32 s76, s90, 0x40000
	s_addc_u32 s77, s91, 0
	s_add_i32 s60, s43, s44
	global_load_lds_dwordx4 v152, s[90:91]
	s_mov_b32 m0, s60
	s_nop 0
	global_load_lds_dwordx4 v148, s[76:77]
	s_add_i32 m0, s60, 0x2000
	s_nop 0
	global_load_lds_dwordx4 v152, s[76:77]
	s_mov_b32 m0, s96
	s_nop 0
	global_load_lds_dwordx4 v146, s[92:93]
	s_mov_b32 m0, s97
	s_nop 0
	global_load_lds_dwordx4 v150, s[92:93]
	s_waitcnt vmcnt(8)
	s_waitcnt lgkmcnt(0)
	s_setprio 0
	s_barrier
	v_mfma_f32_16x16x32_bf16 v[62:65], v[130:133], v[200:203], v[62:65]
	v_mfma_f32_16x16x32_bf16 v[58:61], v[138:141], v[200:203], v[58:61]
	v_mfma_f32_16x16x32_bf16 v[46:49], v[130:133], v[208:211], v[46:49]
	v_mfma_f32_16x16x32_bf16 v[42:45], v[138:141], v[208:211], v[42:45]
	v_mfma_f32_16x16x32_bf16 v[30:33], v[130:133], v[216:219], v[30:33]
	v_mfma_f32_16x16x32_bf16 v[26:29], v[138:141], v[216:219], v[26:29]
	v_mfma_f32_16x16x32_bf16 v[14:17], v[130:133], v[224:227], v[14:17]
	v_mfma_f32_16x16x32_bf16 v[10:13], v[138:141], v[224:227], v[10:13]
	v_mfma_f32_16x16x32_bf16 v[62:65], v[134:137], v[204:207], v[62:65]
	v_mfma_f32_16x16x32_bf16 v[58:61], v[142:145], v[204:207], v[58:61]
	v_mfma_f32_16x16x32_bf16 v[46:49], v[134:137], v[212:215], v[46:49]
	v_mfma_f32_16x16x32_bf16 v[42:45], v[142:145], v[212:215], v[42:45]
	v_mfma_f32_16x16x32_bf16 v[30:33], v[134:137], v[220:223], v[30:33]
	v_mfma_f32_16x16x32_bf16 v[26:29], v[142:145], v[220:223], v[26:29]
	v_mfma_f32_16x16x32_bf16 v[14:17], v[134:137], v[228:231], v[14:17]
	v_mfma_f32_16x16x32_bf16 v[10:13], v[142:145], v[228:231], v[10:13]
	v_mfma_f32_16x16x32_bf16 v[54:57], v[166:169], v[200:203], v[54:57]
	v_mfma_f32_16x16x32_bf16 v[50:53], v[176:179], v[200:203], v[50:53]
	v_mfma_f32_16x16x32_bf16 v[38:41], v[166:169], v[208:211], v[38:41]
	v_mfma_f32_16x16x32_bf16 v[34:37], v[176:179], v[208:211], v[34:37]
	v_mfma_f32_16x16x32_bf16 v[22:25], v[166:169], v[216:219], v[22:25]
	v_mfma_f32_16x16x32_bf16 v[18:21], v[176:179], v[216:219], v[18:21]
	v_mfma_f32_16x16x32_bf16 v[6:9], v[166:169], v[224:227], v[6:9]
	v_mfma_f32_16x16x32_bf16 v[2:5], v[176:179], v[224:227], v[2:5]
	v_mfma_f32_16x16x32_bf16 v[54:57], v[172:175], v[204:207], v[54:57]
	v_mfma_f32_16x16x32_bf16 v[50:53], v[180:183], v[204:207], v[50:53]
	v_mfma_f32_16x16x32_bf16 v[38:41], v[172:175], v[212:215], v[38:41]
	v_mfma_f32_16x16x32_bf16 v[34:37], v[180:183], v[212:215], v[34:37]
	v_mfma_f32_16x16x32_bf16 v[22:25], v[172:175], v[220:223], v[22:25]
	v_mfma_f32_16x16x32_bf16 v[18:21], v[180:183], v[220:223], v[18:21]
	v_mfma_f32_16x16x32_bf16 v[6:9], v[172:175], v[228:231], v[6:9]
	v_mfma_f32_16x16x32_bf16 v[2:5], v[180:183], v[228:231], v[2:5]
	s_barrier
; #define PG8_STAGE(bufoff, gbase, voff) do { _Pragma("unroll") for (int _i = 0; _i < 2; ++_i) \
;         __builtin_amdgcn_global_load_lds((const unsigned*)((const char*)(gbase) + (voff)[_i]), (LAS unsigned*)(lds + (bufoff) + ldsw + _i * 8192), 16, 0, 0); } while (0)
; #define PG8_LDA(dst, b, h) do { _Pragma("unroll") for (int m = 0; m < 4; ++m) _Pragma("unroll") for (int k = 0; k < 2; ++k) dst[m][k] = *(const LAS bf16x8*)(lds + PG8_SA(b, h) + aoff + m * 2048 + k * 1024); } while (0)
; #define PG8_LDB(dst, b, h) do { _Pragma("unroll") for (int n = 0; n < 2; ++n) _Pragma("unroll") for (int k = 0; k < 2; ++k) dst[n][k] = *(const LAS bf16x8*)(lds + PG8_SB(b, h) + boff + n * 2048 + k * 1024); } while (0)
; #define PG8_MMA(ai, bj, At, Bt) do { __builtin_amdgcn_s_setprio(1); _Pragma("unroll") for (int m = 0; m < 4; ++m) _Pragma("unroll") for (int n = 0; n < 2; ++n) _Pragma("unroll") for (int k = 0; k < 2; ++k) \
;         acc[ai][bj][m][n] = __builtin_amdgcn_mfma_f32_16x16x32_bf16(Bt[n][k], At[m][k], acc[ai][bj][m][n], 0, 0, 0); __builtin_amdgcn_s_setprio(0); } while (0)
; #define PG8_WAIT_V(n) asm volatile("s_waitcnt vmcnt(" #n ")" ::: "memory")
; #define PG8_WAIT_L(n) asm volatile("s_waitcnt lgkmcnt(" #n ")" ::: "memory")
; #define PG8_BAR __builtin_amdgcn_s_barrier()
; #define PG8_SCHED __builtin_amdgcn_sched_barrier(0)
; template <class Epi>
; __device__ __forceinline__ void gemm_phase(LAS unsigned char* lds, const Gemm g, const StaticOrder& S, const Epi& E) {
;     ...
;             PG8_LDB(B0, 1, 0); PG8_LDB(B1, 1, 1); PG8_SCHED; PG8_LDA(At, 1, 0); PG8_STAGE(PG8_SA(0, 1), a2 + hstep, voffA);
;             PG8_WAIT_V(8); PG8_WAIT_L(0); PG8_BAR; PG8_MMA(0, 0, At, B0); PG8_MMA(0, 1, At, B1); PG8_BAR; PG8_SCHED;
;             PG8_LDA(At, 1, 1); PG8_STAGE(PG8_SB(1, 0), b3, voffB); PG8_STAGE(PG8_SB(1, 1), b3 + hstep, voffB); PG8_STAGE(PG8_SA(1, 0), a3, voffA);
;             PG8_WAIT_V(8); PG8_WAIT_L(0); PG8_BAR; PG8_MMA(1, 0, At, B0); PG8_MMA(1, 1, At, B1); PG8_BAR; PG8_SCHED;
;         }
	s_setprio 1
	s_add_i32 s60, 0, 0x18000
	s_add_i32 s61, 0, 0x1c000
	v_add_u32_e32 v142, s60, v187
	v_add_u32_e32 v180, s61, v187
	ds_read_b128 v[130:133], v142
	ds_read_b128 v[134:137], v142 offset:1024
	ds_read_b128 v[138:141], v142 offset:2048
	ds_read_b128 v[142:145], v142 offset:3072
	ds_read_b128 v[166:169], v180
	ds_read_b128 v[172:175], v180 offset:1024
	ds_read_b128 v[176:179], v180 offset:2048
	ds_read_b128 v[180:183], v180 offset:3072
	s_add_u32 s76, s92, 0x40000
	s_addc_u32 s77, s93, 0
	s_mov_b32 m0, s11
	ds_read_b128 v[200:203], v194 offset:32768
	ds_read_b128 v[204:207], v194 offset:33792
	ds_read_b128 v[208:211], v194 offset:34816
	ds_read_b128 v[212:215], v194 offset:35840
	ds_read_b128 v[216:219], v194 offset:36864
	ds_read_b128 v[220:223], v194 offset:37888
	ds_read_b128 v[224:227], v194 offset:38912
	ds_read_b128 v[228:231], v194 offset:39936
	global_load_lds_dwordx4 v146, s[76:77]
	s_mov_b32 m0, s94
	s_nop 0
	global_load_lds_dwordx4 v150, s[76:77]
	s_waitcnt vmcnt(8)
	s_waitcnt lgkmcnt(0)
	s_setprio 0
	s_barrier
	v_mfma_f32_16x16x32_bf16 v[126:129], v[130:133], v[200:203], v[126:129]
	v_mfma_f32_16x16x32_bf16 v[122:125], v[138:141], v[200:203], v[122:125]
	v_mfma_f32_16x16x32_bf16 v[110:113], v[130:133], v[208:211], v[110:113]
	v_mfma_f32_16x16x32_bf16 v[106:109], v[138:141], v[208:211], v[106:109]
	v_mfma_f32_16x16x32_bf16 v[94:97], v[130:133], v[216:219], v[94:97]
	v_mfma_f32_16x16x32_bf16 v[90:93], v[138:141], v[216:219], v[90:93]
	v_mfma_f32_16x16x32_bf16 v[78:81], v[130:133], v[224:227], v[78:81]
	v_mfma_f32_16x16x32_bf16 v[74:77], v[138:141], v[224:227], v[74:77]
	v_mfma_f32_16x16x32_bf16 v[126:129], v[134:137], v[204:207], v[126:129]
	v_mfma_f32_16x16x32_bf16 v[122:125], v[142:145], v[204:207], v[122:125]
	v_mfma_f32_16x16x32_bf16 v[110:113], v[134:137], v[212:215], v[110:113]
	v_mfma_f32_16x16x32_bf16 v[106:109], v[142:145], v[212:215], v[106:109]
	v_mfma_f32_16x16x32_bf16 v[94:97], v[134:137], v[220:223], v[94:97]
	v_mfma_f32_16x16x32_bf16 v[90:93], v[142:145], v[220:223], v[90:93]
	v_mfma_f32_16x16x32_bf16 v[78:81], v[134:137], v[228:231], v[78:81]
	v_mfma_f32_16x16x32_bf16 v[74:77], v[142:145], v[228:231], v[74:77]
	v_mfma_f32_16x16x32_bf16 v[118:121], v[166:169], v[200:203], v[118:121]
	v_mfma_f32_16x16x32_bf16 v[114:117], v[176:179], v[200:203], v[114:117]
	v_mfma_f32_16x16x32_bf16 v[102:105], v[166:169], v[208:211], v[102:105]
	v_mfma_f32_16x16x32_bf16 v[98:101], v[176:179], v[208:211], v[98:101]
	v_mfma_f32_16x16x32_bf16 v[86:89], v[166:169], v[216:219], v[86:89]
	v_mfma_f32_16x16x32_bf16 v[82:85], v[176:179], v[216:219], v[82:85]
	v_mfma_f32_16x16x32_bf16 v[70:73], v[166:169], v[224:227], v[70:73]
	v_mfma_f32_16x16x32_bf16 v[66:69], v[176:179], v[224:227], v[66:69]
	v_mfma_f32_16x16x32_bf16 v[118:121], v[172:175], v[204:207], v[118:121]
	v_mfma_f32_16x16x32_bf16 v[114:117], v[180:183], v[204:207], v[114:117]
	v_mfma_f32_16x16x32_bf16 v[102:105], v[172:175], v[212:215], v[102:105]
	v_mfma_f32_16x16x32_bf16 v[98:101], v[180:183], v[212:215], v[98:101]
	v_mfma_f32_16x16x32_bf16 v[86:89], v[172:175], v[220:223], v[86:89]
	v_mfma_f32_16x16x32_bf16 v[82:85], v[180:183], v[220:223], v[82:85]
	v_mfma_f32_16x16x32_bf16 v[70:73], v[172:175], v[228:231], v[70:73]
	v_mfma_f32_16x16x32_bf16 v[66:69], v[180:183], v[228:231], v[66:69]
	s_barrier
	s_setprio 1
	s_add_i32 s60, s60, s44
	s_mov_b32 m0, s60
	ds_read_b128 v[200:203], v194 offset:49152
	ds_read_b128 v[204:207], v194 offset:50176
	ds_read_b128 v[208:211], v194 offset:51200
	ds_read_b128 v[212:215], v194 offset:52224
	ds_read_b128 v[216:219], v194 offset:53248
	ds_read_b128 v[220:223], v194 offset:54272
	ds_read_b128 v[224:227], v194 offset:55296
	ds_read_b128 v[228:231], v194 offset:56320
	global_load_lds_dwordx4 v148, s[98:99]
	s_add_i32 m0, s60, 0x2000
	s_add_u32 s76, s90, 0x40080
	s_addc_u32 s77, s91, 0
	s_add_i32 s60, s61, s44
	global_load_lds_dwordx4 v152, s[98:99]
	s_mov_b32 m0, s60
	s_nop 0
	global_load_lds_dwordx4 v148, s[76:77]
	s_add_i32 m0, s60, 0x2000
	s_nop 0
	global_load_lds_dwordx4 v152, s[76:77]
	s_mov_b32 m0, s79
	s_nop 0
	global_load_lds_dwordx4 v146, s[100:101]
	s_mov_b32 m0, s33
	s_nop 0
	global_load_lds_dwordx4 v150, s[100:101]
	s_waitcnt vmcnt(8)
	s_waitcnt lgkmcnt(0)
	s_setprio 0
	s_barrier
	v_mfma_f32_16x16x32_bf16 v[62:65], v[130:133], v[200:203], v[62:65]
	v_mfma_f32_16x16x32_bf16 v[58:61], v[138:141], v[200:203], v[58:61]
	v_mfma_f32_16x16x32_bf16 v[46:49], v[130:133], v[208:211], v[46:49]
	v_mfma_f32_16x16x32_bf16 v[42:45], v[138:141], v[208:211], v[42:45]
	v_mfma_f32_16x16x32_bf16 v[30:33], v[130:133], v[216:219], v[30:33]
	v_mfma_f32_16x16x32_bf16 v[26:29], v[138:141], v[216:219], v[26:29]
	v_mfma_f32_16x16x32_bf16 v[14:17], v[130:133], v[224:227], v[14:17]
	v_mfma_f32_16x16x32_bf16 v[10:13], v[138:141], v[224:227], v[10:13]
	v_mfma_f32_16x16x32_bf16 v[62:65], v[134:137], v[204:207], v[62:65]
	v_mfma_f32_16x16x32_bf16 v[58:61], v[142:145], v[204:207], v[58:61]
	v_mfma_f32_16x16x32_bf16 v[46:49], v[134:137], v[212:215], v[46:49]
	v_mfma_f32_16x16x32_bf16 v[42:45], v[142:145], v[212:215], v[42:45]
	v_mfma_f32_16x16x32_bf16 v[30:33], v[134:137], v[220:223], v[30:33]
	v_mfma_f32_16x16x32_bf16 v[26:29], v[142:145], v[220:223], v[26:29]
	v_mfma_f32_16x16x32_bf16 v[14:17], v[134:137], v[228:231], v[14:17]
	v_mfma_f32_16x16x32_bf16 v[10:13], v[142:145], v[228:231], v[10:13]
	v_mfma_f32_16x16x32_bf16 v[54:57], v[166:169], v[200:203], v[54:57]
	v_mfma_f32_16x16x32_bf16 v[50:53], v[176:179], v[200:203], v[50:53]
	v_mfma_f32_16x16x32_bf16 v[38:41], v[166:169], v[208:211], v[38:41]
	v_mfma_f32_16x16x32_bf16 v[34:37], v[176:179], v[208:211], v[34:37]
	v_mfma_f32_16x16x32_bf16 v[22:25], v[166:169], v[216:219], v[22:25]
	v_mfma_f32_16x16x32_bf16 v[18:21], v[176:179], v[216:219], v[18:21]
	v_mfma_f32_16x16x32_bf16 v[6:9], v[166:169], v[224:227], v[6:9]
	v_mfma_f32_16x16x32_bf16 v[2:5], v[176:179], v[224:227], v[2:5]
	v_mfma_f32_16x16x32_bf16 v[54:57], v[172:175], v[204:207], v[54:57]
	v_mfma_f32_16x16x32_bf16 v[50:53], v[180:183], v[204:207], v[50:53]
	v_mfma_f32_16x16x32_bf16 v[38:41], v[172:175], v[212:215], v[38:41]
	v_mfma_f32_16x16x32_bf16 v[34:37], v[180:183], v[212:215], v[34:37]
	v_mfma_f32_16x16x32_bf16 v[22:25], v[172:175], v[220:223], v[22:25]
	v_mfma_f32_16x16x32_bf16 v[18:21], v[180:183], v[220:223], v[18:21]
	v_mfma_f32_16x16x32_bf16 v[6:9], v[172:175], v[228:231], v[6:9]
	v_mfma_f32_16x16x32_bf16 v[2:5], v[180:183], v[228:231], v[2:5]
	s_barrier
	s_setprio 1
	s_add_i32 vcc_hi, vcc_hi, 2
	s_add_u32 s88, s88, 0x100
	s_addc_u32 s89, s89, 0
	s_add_u32 s81, s81, 0x100
	s_addc_u32 vcc_lo, vcc_lo, 0
	s_cmp_gt_u32 vcc_hi, 13
	s_cbranch_scc0 .LBB0_322
	s_and_b64 vcc, exec, s[58:59]
	s_cbranch_vccz .LBB0_325
	s_barrier

; #define PG8_STAGE(bufoff, gbase, voff) do { _Pragma("unroll") for (int _i = 0; _i < 2; ++_i) \
;         __builtin_amdgcn_global_load_lds((const unsigned*)((const char*)(gbase) + (voff)[_i]), (LAS unsigned*)(lds + (bufoff) + ldsw + _i * 8192), 16, 0, 0); } while (0)
; #define PG8_LDA(dst, b, h) do { _Pragma("unroll") for (int m = 0; m < 4; ++m) _Pragma("unroll") for (int k = 0; k < 2; ++k) dst[m][k] = *(const LAS bf16x8*)(lds + PG8_SA(b, h) + aoff + m * 2048 + k * 1024); } while (0)
; #define PG8_LDB(dst, b, h) do { _Pragma("unroll") for (int n = 0; n < 2; ++n) _Pragma("unroll") for (int k = 0; k < 2; ++k) dst[n][k] = *(const LAS bf16x8*)(lds + PG8_SB(b, h) + boff + n * 2048 + k * 1024); } while (0)
; #define PG8_BAR __builtin_amdgcn_s_barrier()
; template <class Epi>
; __device__ __forceinline__ void gemm_phase(LAS unsigned char* lds, const Gemm g, const StaticOrder& S, const Epi& E) {
;     ...
;         for (int t = 0; t < nt; t += 2) {
;             const bool last = (t == nt - 2);
;             const char* a1 = cA + (size_t)(t + 1) * kstep;
;             const char* a2 = last ? nA : cA + (size_t)(t + 2) * kstep; const char* b2 = last ? nB : cB + (size_t)(t + 2) * kstep;
;             const char* a3 = a2 + kstep; const char* b3 = b2 + kstep;
;             if constexpr (Epi::MIDK > 0) { if (t == Epi::MIDK) E.mid(acc, cur, wr, wc, fr, fq); }
;             PG8_LDB(B0, 0, 0); PG8_LDB(B1, 0, 1); PG8_SCHED; PG8_LDA(At, 0, 0); PG8_STAGE(PG8_SA(1, 1), a1 + hstep, voffA);
;             PG8_WAIT_V(8); PG8_WAIT_L(0); PG8_BAR; PG8_MMA(0, 0, At, B0); PG8_MMA(0, 1, At, B1); PG8_BAR; PG8_SCHED;
;             PG8_LDA(At, 0, 1); PG8_STAGE(PG8_SB(0, 0), b2, voffB); PG8_STAGE(PG8_SB(0, 1), b2 + hstep, voffB); PG8_STAGE(PG8_SA(0, 0), a2, voffA);
;             PG8_WAIT_V(8); PG8_WAIT_L(0); PG8_BAR; PG8_MMA(1, 0, At, B0); PG8_MMA(1, 1, At, B1); PG8_BAR; PG8_SCHED;
;             PG8_LDB(B0, 1, 0); PG8_LDB(B1, 1, 1); PG8_SCHED; PG8_LDA(At, 1, 0); PG8_STAGE(PG8_SA(0, 1), a2 + hstep, voffA);
;             PG8_WAIT_V(8); PG8_WAIT_L(0); PG8_BAR; PG8_MMA(0, 0, At, B0); PG8_MMA(0, 1, At, B1); PG8_BAR; PG8_SCHED;
;             PG8_LDA(At, 1, 1); PG8_STAGE(PG8_SB(1, 0), b3, voffB); PG8_STAGE(PG8_SB(1, 1), b3 + hstep, voffB); PG8_STAGE(PG8_SA(1, 0), a3, voffA);
;             PG8_WAIT_V(8); PG8_WAIT_L(0); PG8_BAR; PG8_MMA(1, 0, At, B0); PG8_MMA(1, 1, At, B1); PG8_BAR; PG8_SCHED;
.LBB0_619:
	ds_read_b128 v[154:157], v174
	ds_read_b128 v[158:161], v174 offset:1024
	ds_read_b128 v[162:165], v174 offset:2048
	ds_read_b128 v[166:169], v174 offset:3072
	ds_read_b128 v[182:185], v175
	ds_read_b128 v[186:189], v175 offset:1024
	ds_read_b128 v[190:193], v175 offset:2048
	ds_read_b128 v[194:197], v175 offset:3072
	s_add_u32 s46, s44, 0xfffc0080
	s_addc_u32 s47, s45, -1
	s_cmp_eq_u32 s69, 12
	s_cselect_b32 s49, s64, s47
	s_cselect_b32 s48, s65, s46
	s_cselect_b32 s47, s25, s68
	s_cselect_b32 s46, s66, s67
	s_add_i32 m0, s43, 0xc000
	ds_read_b128 v[198:201], v176
	ds_read_b128 v[202:205], v176 offset:1024
	ds_read_b128 v[206:209], v176 offset:2048
	ds_read_b128 v[210:213], v176 offset:3072
	ds_read_b128 v[214:217], v176 offset:4096
	ds_read_b128 v[218:221], v176 offset:5120
	ds_read_b128 v[222:225], v176 offset:6144
	ds_read_b128 v[226:229], v176 offset:7168
	global_load_lds_dwordx4 v144, s[44:45]
	s_add_i32 m0, s43, 0xe000
	s_nop 0
	global_load_lds_dwordx4 v146, s[44:45]
	s_waitcnt vmcnt(8)
	s_waitcnt lgkmcnt(0)
	s_setprio 0
	s_barrier
	v_mfma_f32_16x16x32_bf16 v[126:129], v[154:157], v[198:201], v[126:129]
	v_mfma_f32_16x16x32_bf16 v[122:125], v[162:165], v[198:201], v[122:125]
	v_mfma_f32_16x16x32_bf16 v[110:113], v[154:157], v[206:209], v[110:113]
	v_mfma_f32_16x16x32_bf16 v[106:109], v[162:165], v[206:209], v[106:109]
	v_mfma_f32_16x16x32_bf16 v[94:97], v[154:157], v[214:217], v[94:97]
	v_mfma_f32_16x16x32_bf16 v[90:93], v[162:165], v[214:217], v[90:93]
	v_mfma_f32_16x16x32_bf16 v[78:81], v[154:157], v[222:225], v[78:81]
	v_mfma_f32_16x16x32_bf16 v[74:77], v[162:165], v[222:225], v[74:77]
	v_mfma_f32_16x16x32_bf16 v[126:129], v[158:161], v[202:205], v[126:129]
	v_mfma_f32_16x16x32_bf16 v[122:125], v[166:169], v[202:205], v[122:125]
	v_mfma_f32_16x16x32_bf16 v[110:113], v[158:161], v[210:213], v[110:113]
	v_mfma_f32_16x16x32_bf16 v[106:109], v[166:169], v[210:213], v[106:109]
	v_mfma_f32_16x16x32_bf16 v[94:97], v[158:161], v[218:221], v[94:97]
	v_mfma_f32_16x16x32_bf16 v[90:93], v[166:169], v[218:221], v[90:93]
	v_mfma_f32_16x16x32_bf16 v[78:81], v[158:161], v[226:229], v[78:81]
	v_mfma_f32_16x16x32_bf16 v[74:77], v[166:169], v[226:229], v[74:77]
	v_mfma_f32_16x16x32_bf16 v[118:121], v[182:185], v[198:201], v[118:121]
	v_mfma_f32_16x16x32_bf16 v[114:117], v[190:193], v[198:201], v[114:117]
	v_mfma_f32_16x16x32_bf16 v[102:105], v[182:185], v[206:209], v[102:105]
	v_mfma_f32_16x16x32_bf16 v[98:101], v[190:193], v[206:209], v[98:101]
	v_mfma_f32_16x16x32_bf16 v[86:89], v[182:185], v[214:217], v[86:89]
	v_mfma_f32_16x16x32_bf16 v[82:85], v[190:193], v[214:217], v[82:85]
	v_mfma_f32_16x16x32_bf16 v[70:73], v[182:185], v[222:225], v[70:73]
	v_mfma_f32_16x16x32_bf16 v[66:69], v[190:193], v[222:225], v[66:69]
	v_mfma_f32_16x16x32_bf16 v[118:121], v[186:189], v[202:205], v[118:121]
	v_mfma_f32_16x16x32_bf16 v[114:117], v[194:197], v[202:205], v[114:117]
	v_mfma_f32_16x16x32_bf16 v[102:105], v[186:189], v[210:213], v[102:105]
	v_mfma_f32_16x16x32_bf16 v[98:101], v[194:197], v[210:213], v[98:101]
	v_mfma_f32_16x16x32_bf16 v[86:89], v[186:189], v[218:221], v[86:89]
	v_mfma_f32_16x16x32_bf16 v[82:85], v[194:197], v[218:221], v[82:85]
	v_mfma_f32_16x16x32_bf16 v[70:73], v[186:189], v[226:229], v[70:73]
	v_mfma_f32_16x16x32_bf16 v[66:69], v[194:197], v[226:229], v[66:69]
	s_barrier
	s_setprio 1
	s_add_u32 s98, s46, s8
	s_addc_u32 s99, s47, s9
	s_add_u32 s100, s48, s8
	s_addc_u32 s101, s49, s9
	s_add_i32 s76, s60, s6
	s_mov_b32 m0, s76
	ds_read_b128 v[198:201], v176 offset:16384
	ds_read_b128 v[202:205], v176 offset:17408
	ds_read_b128 v[206:209], v176 offset:18432
	ds_read_b128 v[210:213], v176 offset:19456
	ds_read_b128 v[214:217], v176 offset:20480
	ds_read_b128 v[218:221], v176 offset:21504
	ds_read_b128 v[222:225], v176 offset:22528
	ds_read_b128 v[226:229], v176 offset:23552
	global_load_lds_dwordx4 v132, s[46:47]
	s_add_i32 m0, s76, 0x2000
	s_add_u32 s76, s46, 0x40000
	s_addc_u32 s77, s47, 0
	s_add_i32 s78, s61, s6
	global_load_lds_dwordx4 v136, s[46:47]
	s_mov_b32 m0, s78
	s_nop 0
	global_load_lds_dwordx4 v132, s[76:77]
	s_add_i32 m0, s78, 0x2000
	s_nop 0
	global_load_lds_dwordx4 v136, s[76:77]
	s_mov_b32 m0, s43
	s_nop 0
	global_load_lds_dwordx4 v130, s[48:49]
	s_mov_b32 m0, s51
	s_nop 0
	global_load_lds_dwordx4 v134, s[48:49]
	s_waitcnt vmcnt(8)
	s_waitcnt lgkmcnt(0)
	s_setprio 0
	s_barrier
	v_mfma_f32_16x16x32_bf16 v[62:65], v[154:157], v[198:201], v[62:65]
	v_mfma_f32_16x16x32_bf16 v[58:61], v[162:165], v[198:201], v[58:61]
	v_mfma_f32_16x16x32_bf16 v[46:49], v[154:157], v[206:209], v[46:49]
	v_mfma_f32_16x16x32_bf16 v[42:45], v[162:165], v[206:209], v[42:45]
	v_mfma_f32_16x16x32_bf16 v[30:33], v[154:157], v[214:217], v[30:33]
	v_mfma_f32_16x16x32_bf16 v[26:29], v[162:165], v[214:217], v[26:29]
	v_mfma_f32_16x16x32_bf16 v[14:17], v[154:157], v[222:225], v[14:17]
	v_mfma_f32_16x16x32_bf16 v[10:13], v[162:165], v[222:225], v[10:13]
	v_mfma_f32_16x16x32_bf16 v[62:65], v[158:161], v[202:205], v[62:65]
	v_mfma_f32_16x16x32_bf16 v[58:61], v[166:169], v[202:205], v[58:61]
	v_mfma_f32_16x16x32_bf16 v[46:49], v[158:161], v[210:213], v[46:49]
	v_mfma_f32_16x16x32_bf16 v[42:45], v[166:169], v[210:213], v[42:45]
	v_mfma_f32_16x16x32_bf16 v[30:33], v[158:161], v[218:221], v[30:33]
	v_mfma_f32_16x16x32_bf16 v[26:29], v[166:169], v[218:221], v[26:29]
	v_mfma_f32_16x16x32_bf16 v[14:17], v[158:161], v[226:229], v[14:17]
	v_mfma_f32_16x16x32_bf16 v[10:13], v[166:169], v[226:229], v[10:13]
	v_mfma_f32_16x16x32_bf16 v[54:57], v[182:185], v[198:201], v[54:57]
	v_mfma_f32_16x16x32_bf16 v[50:53], v[190:193], v[198:201], v[50:53]
	v_mfma_f32_16x16x32_bf16 v[38:41], v[182:185], v[206:209], v[38:41]
	v_mfma_f32_16x16x32_bf16 v[34:37], v[190:193], v[206:209], v[34:37]
	v_mfma_f32_16x16x32_bf16 v[22:25], v[182:185], v[214:217], v[22:25]
	v_mfma_f32_16x16x32_bf16 v[18:21], v[190:193], v[214:217], v[18:21]
	v_mfma_f32_16x16x32_bf16 v[6:9], v[182:185], v[222:225], v[6:9]
	v_mfma_f32_16x16x32_bf16 v[2:5], v[190:193], v[222:225], v[2:5]
	v_mfma_f32_16x16x32_bf16 v[54:57], v[186:189], v[202:205], v[54:57]
	v_mfma_f32_16x16x32_bf16 v[50:53], v[194:197], v[202:205], v[50:53]
	v_mfma_f32_16x16x32_bf16 v[38:41], v[186:189], v[210:213], v[38:41]
	v_mfma_f32_16x16x32_bf16 v[34:37], v[194:197], v[210:213], v[34:37]
	v_mfma_f32_16x16x32_bf16 v[22:25], v[186:189], v[218:221], v[22:25]
	v_mfma_f32_16x16x32_bf16 v[18:21], v[194:197], v[218:221], v[18:21]
	v_mfma_f32_16x16x32_bf16 v[6:9], v[186:189], v[226:229], v[6:9]
	v_mfma_f32_16x16x32_bf16 v[2:5], v[194:197], v[226:229], v[2:5]
	s_barrier
; #define PG8_STAGE(bufoff, gbase, voff) do { _Pragma("unroll") for (int _i = 0; _i < 2; ++_i) \
;         __builtin_amdgcn_global_load_lds((const unsigned*)((const char*)(gbase) + (voff)[_i]), (LAS unsigned*)(lds + (bufoff) + ldsw + _i * 8192), 16, 0, 0); } while (0)
; #define PG8_LDA(dst, b, h) do { _Pragma("unroll") for (int m = 0; m < 4; ++m) _Pragma("unroll") for (int k = 0; k < 2; ++k) dst[m][k] = *(const LAS bf16x8*)(lds + PG8_SA(b, h) + aoff + m * 2048 + k * 1024); } while (0)
; #define PG8_LDB(dst, b, h) do { _Pragma("unroll") for (int n = 0; n < 2; ++n) _Pragma("unroll") for (int k = 0; k < 2; ++k) dst[n][k] = *(const LAS bf16x8*)(lds + PG8_SB(b, h) + boff + n * 2048 + k * 1024); } while (0)
; #define PG8_MMA(ai, bj, At, Bt) do { __builtin_amdgcn_s_setprio(1); _Pragma("unroll") for (int m = 0; m < 4; ++m) _Pragma("unroll") for (int n = 0; n < 2; ++n) _Pragma("unroll") for (int k = 0; k < 2; ++k) \
;         acc[ai][bj][m][n] = __builtin_amdgcn_mfma_f32_16x16x32_bf16(Bt[n][k], At[m][k], acc[ai][bj][m][n], 0, 0, 0); __builtin_amdgcn_s_setprio(0); } while (0)
; #define PG8_WAIT_V(n) asm volatile("s_waitcnt vmcnt(" #n ")" ::: "memory")
; #define PG8_WAIT_L(n) asm volatile("s_waitcnt lgkmcnt(" #n ")" ::: "memory")
; #define PG8_BAR __builtin_amdgcn_s_barrier()
; #define PG8_SCHED __builtin_amdgcn_sched_barrier(0)
; template <class Epi>
; __device__ __forceinline__ void gemm_phase(LAS unsigned char* lds, const Gemm g, const StaticOrder& S, const Epi& E) {
;     ...
;             PG8_LDB(B0, 1, 0); PG8_LDB(B1, 1, 1); PG8_SCHED; PG8_LDA(At, 1, 0); PG8_STAGE(PG8_SA(0, 1), a2 + hstep, voffA);
;             PG8_WAIT_V(8); PG8_WAIT_L(0); PG8_BAR; PG8_MMA(0, 0, At, B0); PG8_MMA(0, 1, At, B1); PG8_BAR; PG8_SCHED;
;             PG8_LDA(At, 1, 1); PG8_STAGE(PG8_SB(1, 0), b3, voffB); PG8_STAGE(PG8_SB(1, 1), b3 + hstep, voffB); PG8_STAGE(PG8_SA(1, 0), a3, voffA);
;             PG8_WAIT_V(8); PG8_WAIT_L(0); PG8_BAR; PG8_MMA(1, 0, At, B0); PG8_MMA(1, 1, At, B1); PG8_BAR; PG8_SCHED;
;         }
	s_setprio 1
	s_add_i32 s76, 0, 0x18000
	v_add_u32_e32 v138, s76, v172
	s_add_i32 s77, 0, 0x1c000
	ds_read_b128 v[154:157], v138
	ds_read_b128 v[158:161], v138 offset:1024
	ds_read_b128 v[162:165], v138 offset:2048
	ds_read_b128 v[166:169], v138 offset:3072
	v_add_u32_e32 v138, s77, v172
	ds_read_b128 v[182:185], v138
	ds_read_b128 v[186:189], v138 offset:1024
	ds_read_b128 v[190:193], v138 offset:2048
	ds_read_b128 v[194:197], v138 offset:3072
	s_add_u32 s48, s48, 0x40000
	s_addc_u32 s49, s49, 0
	s_mov_b32 m0, s52
	ds_read_b128 v[198:201], v176 offset:32768
	ds_read_b128 v[202:205], v176 offset:33792
	ds_read_b128 v[206:209], v176 offset:34816
	ds_read_b128 v[210:213], v176 offset:35840
	ds_read_b128 v[214:217], v176 offset:36864
	ds_read_b128 v[218:221], v176 offset:37888
	ds_read_b128 v[222:225], v176 offset:38912
	ds_read_b128 v[226:229], v176 offset:39936
	global_load_lds_dwordx4 v130, s[48:49]
	s_mov_b32 m0, s53
	s_nop 0
	global_load_lds_dwordx4 v134, s[48:49]
	s_waitcnt vmcnt(8)
	s_waitcnt lgkmcnt(0)
	s_setprio 0
	s_barrier
	v_mfma_f32_16x16x32_bf16 v[126:129], v[154:157], v[198:201], v[126:129]
	v_mfma_f32_16x16x32_bf16 v[122:125], v[162:165], v[198:201], v[122:125]
	v_mfma_f32_16x16x32_bf16 v[110:113], v[154:157], v[206:209], v[110:113]
	v_mfma_f32_16x16x32_bf16 v[106:109], v[162:165], v[206:209], v[106:109]
	v_mfma_f32_16x16x32_bf16 v[94:97], v[154:157], v[214:217], v[94:97]
	v_mfma_f32_16x16x32_bf16 v[90:93], v[162:165], v[214:217], v[90:93]
	v_mfma_f32_16x16x32_bf16 v[78:81], v[154:157], v[222:225], v[78:81]
	v_mfma_f32_16x16x32_bf16 v[74:77], v[162:165], v[222:225], v[74:77]
	v_mfma_f32_16x16x32_bf16 v[126:129], v[158:161], v[202:205], v[126:129]
	v_mfma_f32_16x16x32_bf16 v[122:125], v[166:169], v[202:205], v[122:125]
	v_mfma_f32_16x16x32_bf16 v[110:113], v[158:161], v[210:213], v[110:113]
	v_mfma_f32_16x16x32_bf16 v[106:109], v[166:169], v[210:213], v[106:109]
	v_mfma_f32_16x16x32_bf16 v[94:97], v[158:161], v[218:221], v[94:97]
	v_mfma_f32_16x16x32_bf16 v[90:93], v[166:169], v[218:221], v[90:93]
	v_mfma_f32_16x16x32_bf16 v[78:81], v[158:161], v[226:229], v[78:81]
	v_mfma_f32_16x16x32_bf16 v[74:77], v[166:169], v[226:229], v[74:77]
	v_mfma_f32_16x16x32_bf16 v[118:121], v[182:185], v[198:201], v[118:121]
	v_mfma_f32_16x16x32_bf16 v[114:117], v[190:193], v[198:201], v[114:117]
	v_mfma_f32_16x16x32_bf16 v[102:105], v[182:185], v[206:209], v[102:105]
	v_mfma_f32_16x16x32_bf16 v[98:101], v[190:193], v[206:209], v[98:101]
	v_mfma_f32_16x16x32_bf16 v[86:89], v[182:185], v[214:217], v[86:89]
	v_mfma_f32_16x16x32_bf16 v[82:85], v[190:193], v[214:217], v[82:85]
	v_mfma_f32_16x16x32_bf16 v[70:73], v[182:185], v[222:225], v[70:73]
	v_mfma_f32_16x16x32_bf16 v[66:69], v[190:193], v[222:225], v[66:69]
	v_mfma_f32_16x16x32_bf16 v[118:121], v[186:189], v[202:205], v[118:121]
	v_mfma_f32_16x16x32_bf16 v[114:117], v[194:197], v[202:205], v[114:117]
	v_mfma_f32_16x16x32_bf16 v[102:105], v[186:189], v[210:213], v[102:105]
	v_mfma_f32_16x16x32_bf16 v[98:101], v[194:197], v[210:213], v[98:101]
	v_mfma_f32_16x16x32_bf16 v[86:89], v[186:189], v[218:221], v[86:89]
	v_mfma_f32_16x16x32_bf16 v[82:85], v[194:197], v[218:221], v[82:85]
	v_mfma_f32_16x16x32_bf16 v[70:73], v[186:189], v[226:229], v[70:73]
	v_mfma_f32_16x16x32_bf16 v[66:69], v[194:197], v[226:229], v[66:69]
	s_barrier
	s_setprio 1
	s_add_i32 s48, s76, s6
	s_mov_b32 m0, s48
	ds_read_b128 v[198:201], v176 offset:49152
	ds_read_b128 v[202:205], v176 offset:50176
	ds_read_b128 v[206:209], v176 offset:51200
	ds_read_b128 v[210:213], v176 offset:52224
	ds_read_b128 v[214:217], v176 offset:53248
	ds_read_b128 v[218:221], v176 offset:54272
	ds_read_b128 v[222:225], v176 offset:55296
	ds_read_b128 v[226:229], v176 offset:56320
	global_load_lds_dwordx4 v132, s[98:99]
	s_add_i32 m0, s48, 0x2000
	s_add_u32 s46, s46, 0x40080
	s_addc_u32 s47, s47, 0
	s_add_i32 s48, s77, s6
	global_load_lds_dwordx4 v136, s[98:99]
	s_mov_b32 m0, s48
	s_nop 0
	global_load_lds_dwordx4 v132, s[46:47]
	s_add_i32 m0, s48, 0x2000
	s_nop 0
	global_load_lds_dwordx4 v136, s[46:47]
	s_mov_b32 m0, s56
	s_nop 0
	global_load_lds_dwordx4 v130, s[100:101]
	s_mov_b32 m0, s57
	s_nop 0
	global_load_lds_dwordx4 v134, s[100:101]
	s_waitcnt vmcnt(8)
	s_waitcnt lgkmcnt(0)
	s_setprio 0
	s_barrier
	v_mfma_f32_16x16x32_bf16 v[62:65], v[154:157], v[198:201], v[62:65]
	v_mfma_f32_16x16x32_bf16 v[58:61], v[162:165], v[198:201], v[58:61]
	v_mfma_f32_16x16x32_bf16 v[46:49], v[154:157], v[206:209], v[46:49]
	v_mfma_f32_16x16x32_bf16 v[42:45], v[162:165], v[206:209], v[42:45]
	v_mfma_f32_16x16x32_bf16 v[30:33], v[154:157], v[214:217], v[30:33]
	v_mfma_f32_16x16x32_bf16 v[26:29], v[162:165], v[214:217], v[26:29]
	v_mfma_f32_16x16x32_bf16 v[14:17], v[154:157], v[222:225], v[14:17]
	v_mfma_f32_16x16x32_bf16 v[10:13], v[162:165], v[222:225], v[10:13]
	v_mfma_f32_16x16x32_bf16 v[62:65], v[158:161], v[202:205], v[62:65]
	v_mfma_f32_16x16x32_bf16 v[58:61], v[166:169], v[202:205], v[58:61]
	v_mfma_f32_16x16x32_bf16 v[46:49], v[158:161], v[210:213], v[46:49]
	v_mfma_f32_16x16x32_bf16 v[42:45], v[166:169], v[210:213], v[42:45]
	v_mfma_f32_16x16x32_bf16 v[30:33], v[158:161], v[218:221], v[30:33]
	v_mfma_f32_16x16x32_bf16 v[26:29], v[166:169], v[218:221], v[26:29]
	v_mfma_f32_16x16x32_bf16 v[14:17], v[158:161], v[226:229], v[14:17]
	v_mfma_f32_16x16x32_bf16 v[10:13], v[166:169], v[226:229], v[10:13]
	v_mfma_f32_16x16x32_bf16 v[54:57], v[182:185], v[198:201], v[54:57]
	v_mfma_f32_16x16x32_bf16 v[50:53], v[190:193], v[198:201], v[50:53]
	v_mfma_f32_16x16x32_bf16 v[38:41], v[182:185], v[206:209], v[38:41]
	v_mfma_f32_16x16x32_bf16 v[34:37], v[190:193], v[206:209], v[34:37]
	v_mfma_f32_16x16x32_bf16 v[22:25], v[182:185], v[214:217], v[22:25]
	v_mfma_f32_16x16x32_bf16 v[18:21], v[190:193], v[214:217], v[18:21]
	v_mfma_f32_16x16x32_bf16 v[6:9], v[182:185], v[222:225], v[6:9]
	v_mfma_f32_16x16x32_bf16 v[2:5], v[190:193], v[222:225], v[2:5]
	v_mfma_f32_16x16x32_bf16 v[54:57], v[186:189], v[202:205], v[54:57]
	v_mfma_f32_16x16x32_bf16 v[50:53], v[194:197], v[202:205], v[50:53]
	v_mfma_f32_16x16x32_bf16 v[38:41], v[186:189], v[210:213], v[38:41]
	v_mfma_f32_16x16x32_bf16 v[34:37], v[194:197], v[210:213], v[34:37]
	v_mfma_f32_16x16x32_bf16 v[22:25], v[186:189], v[218:221], v[22:25]
	v_mfma_f32_16x16x32_bf16 v[18:21], v[194:197], v[218:221], v[18:21]
	v_mfma_f32_16x16x32_bf16 v[6:9], v[186:189], v[226:229], v[6:9]
	v_mfma_f32_16x16x32_bf16 v[2:5], v[194:197], v[226:229], v[2:5]
	s_barrier
	s_setprio 1
	s_add_i32 s69, s69, 2
	s_add_u32 s44, s44, 0x100
	s_addc_u32 s45, s45, 0
	s_add_u32 s67, s67, 0x100
	s_addc_u32 s68, s68, 0
	s_cmp_gt_u32 s69, 13
	s_cbranch_scc0 .LBB0_619
	s_and_b64 vcc, exec, s[18:19]
	s_cbranch_vccz .LBB0_622
	s_barrier

; #define PG8_STAGE(bufoff, gbase, voff) do { _Pragma("unroll") for (int _i = 0; _i < 2; ++_i) \
;         __builtin_amdgcn_global_load_lds((const unsigned*)((const char*)(gbase) + (voff)[_i]), (LAS unsigned*)(lds + (bufoff) + ldsw + _i * 8192), 16, 0, 0); } while (0)
; #define PG8_LDA(dst, b, h) do { _Pragma("unroll") for (int m = 0; m < 4; ++m) _Pragma("unroll") for (int k = 0; k < 2; ++k) dst[m][k] = *(const LAS bf16x8*)(lds + PG8_SA(b, h) + aoff + m * 2048 + k * 1024); } while (0)
; #define PG8_LDB(dst, b, h) do { _Pragma("unroll") for (int n = 0; n < 2; ++n) _Pragma("unroll") for (int k = 0; k < 2; ++k) dst[n][k] = *(const LAS bf16x8*)(lds + PG8_SB(b, h) + boff + n * 2048 + k * 1024); } while (0)
; #define PG8_MMA(ai, bj, At, Bt) do { __builtin_amdgcn_s_setprio(1); _Pragma("unroll") for (int m = 0; m < 4; ++m) _Pragma("unroll") for (int n = 0; n < 2; ++n) _Pragma("unroll") for (int k = 0; k < 2; ++k) \
;         acc[ai][bj][m][n] = __builtin_amdgcn_mfma_f32_16x16x32_bf16(Bt[n][k], At[m][k], acc[ai][bj][m][n], 0, 0, 0); __builtin_amdgcn_s_setprio(0); } while (0)
; #define PG8_WAIT_V(n) asm volatile("s_waitcnt vmcnt(" #n ")" ::: "memory")
; #define PG8_WAIT_L(n) asm volatile("s_waitcnt lgkmcnt(" #n ")" ::: "memory")
; #define PG8_BAR __builtin_amdgcn_s_barrier()
; template <class Epi>
; __device__ __forceinline__ void gemm_phase(LAS unsigned char* lds, const Gemm g, const StaticOrder& S, const Epi& E) {
;     ...
;         for (int t = 0; t < nt; t += 2) {
;             const bool last = (t == nt - 2);
;             const char* a1 = cA + (size_t)(t + 1) * kstep;
;             const char* a2 = last ? nA : cA + (size_t)(t + 2) * kstep; const char* b2 = last ? nB : cB + (size_t)(t + 2) * kstep;
;             const char* a3 = a2 + kstep; const char* b3 = b2 + kstep;
;             if constexpr (Epi::MIDK > 0) { if (t == Epi::MIDK) E.mid(acc, cur, wr, wc, fr, fq); }
;             PG8_LDB(B0, 0, 0); PG8_LDB(B1, 0, 1); PG8_SCHED; PG8_LDA(At, 0, 0); PG8_STAGE(PG8_SA(1, 1), a1 + hstep, voffA);
;             PG8_WAIT_V(8); PG8_WAIT_L(0); PG8_BAR; PG8_MMA(0, 0, At, B0); PG8_MMA(0, 1, At, B1); PG8_BAR; PG8_SCHED;
;             PG8_LDA(At, 0, 1); PG8_STAGE(PG8_SB(0, 0), b2, voffB); PG8_STAGE(PG8_SB(0, 1), b2 + hstep, voffB); PG8_STAGE(PG8_SA(0, 0), a2, voffA);
;             PG8_WAIT_V(8); PG8_WAIT_L(0); PG8_BAR; PG8_MMA(1, 0, At, B0); PG8_MMA(1, 1, At, B1); PG8_BAR; PG8_SCHED;
.LBB0_700:
	v_add_u32_e32 v3, s68, v198
	ds_read_b128 v[134:137], v3
	ds_read_b128 v[138:141], v3 offset:1024
	ds_read_b128 v[142:145], v3 offset:2048
	ds_read_b128 v[146:149], v3 offset:3072
	v_add_u32_e32 v3, s69, v198
	s_add_u32 s52, s48, s50
	ds_read_b128 v[158:161], v3
	ds_read_b128 v[162:165], v3 offset:1024
	ds_read_b128 v[166:169], v3 offset:2048
	ds_read_b128 v[188:191], v3 offset:3072
	s_addc_u32 s53, s49, s51
	s_add_u32 s52, s52, 0x100
	s_addc_u32 s53, s53, 0
	s_add_u32 s81, s78, s50
	s_addc_u32 s82, s79, s51
	s_cmpk_eq_i32 s50, 0x700
	s_cselect_b32 s55, s43, s53
	s_cselect_b32 s54, s76, s52
	s_cselect_b32 s53, s41, s82
	s_cselect_b32 s52, s77, s81
	v_lshl_add_u64 v[4:5], v[154:155], 0, s[50:51]
	s_add_i32 m0, s59, 0xc000
	ds_read_b128 v[192:195], v200
	ds_read_b128 v[202:205], v200 offset:1024
	ds_read_b128 v[206:209], v200 offset:2048
	ds_read_b128 v[210:213], v200 offset:3072
	ds_read_b128 v[214:217], v200 offset:4096
	ds_read_b128 v[218:221], v200 offset:5120
	ds_read_b128 v[222:225], v200 offset:6144
	ds_read_b128 v[226:229], v200 offset:7168
	global_load_lds_dwordx4 v[4:5], off
	v_lshl_add_u64 v[4:5], v[156:157], 0, s[50:51]
	s_add_i32 m0, s59, 0xe000
	s_nop 0
	global_load_lds_dwordx4 v[4:5], off
	s_waitcnt vmcnt(8)
	s_waitcnt lgkmcnt(0)
	s_setprio 0
	s_barrier
	v_mfma_f32_16x16x32_bf16 v[130:133], v[134:137], v[192:195], v[130:133]
	v_mfma_f32_16x16x32_bf16 v[126:129], v[142:145], v[192:195], v[126:129]
	v_mfma_f32_16x16x32_bf16 v[114:117], v[134:137], v[206:209], v[114:117]
	v_mfma_f32_16x16x32_bf16 v[110:113], v[142:145], v[206:209], v[110:113]
	v_mfma_f32_16x16x32_bf16 v[98:101], v[134:137], v[214:217], v[98:101]
	v_mfma_f32_16x16x32_bf16 v[94:97], v[142:145], v[214:217], v[94:97]
	v_mfma_f32_16x16x32_bf16 v[82:85], v[134:137], v[222:225], v[82:85]
	v_mfma_f32_16x16x32_bf16 v[78:81], v[142:145], v[222:225], v[78:81]
	v_mfma_f32_16x16x32_bf16 v[130:133], v[138:141], v[202:205], v[130:133]
	v_mfma_f32_16x16x32_bf16 v[126:129], v[146:149], v[202:205], v[126:129]
	v_mfma_f32_16x16x32_bf16 v[114:117], v[138:141], v[210:213], v[114:117]
	v_mfma_f32_16x16x32_bf16 v[110:113], v[146:149], v[210:213], v[110:113]
	v_mfma_f32_16x16x32_bf16 v[98:101], v[138:141], v[218:221], v[98:101]
	v_mfma_f32_16x16x32_bf16 v[94:97], v[146:149], v[218:221], v[94:97]
	v_mfma_f32_16x16x32_bf16 v[82:85], v[138:141], v[226:229], v[82:85]
	v_mfma_f32_16x16x32_bf16 v[78:81], v[146:149], v[226:229], v[78:81]
	v_mfma_f32_16x16x32_bf16 v[122:125], v[158:161], v[192:195], v[122:125]
	v_mfma_f32_16x16x32_bf16 v[118:121], v[166:169], v[192:195], v[118:121]
	v_mfma_f32_16x16x32_bf16 v[106:109], v[158:161], v[206:209], v[106:109]
	v_mfma_f32_16x16x32_bf16 v[102:105], v[166:169], v[206:209], v[102:105]
	v_mfma_f32_16x16x32_bf16 v[90:93], v[158:161], v[214:217], v[90:93]
	v_mfma_f32_16x16x32_bf16 v[86:89], v[166:169], v[214:217], v[86:89]
	v_mfma_f32_16x16x32_bf16 v[74:77], v[158:161], v[222:225], v[74:77]
	v_mfma_f32_16x16x32_bf16 v[70:73], v[166:169], v[222:225], v[70:73]
	v_mfma_f32_16x16x32_bf16 v[122:125], v[162:165], v[202:205], v[122:125]
	v_mfma_f32_16x16x32_bf16 v[118:121], v[188:191], v[202:205], v[118:121]
	v_mfma_f32_16x16x32_bf16 v[106:109], v[162:165], v[210:213], v[106:109]
	v_mfma_f32_16x16x32_bf16 v[102:105], v[188:191], v[210:213], v[102:105]
	v_mfma_f32_16x16x32_bf16 v[90:93], v[162:165], v[218:221], v[90:93]
	v_mfma_f32_16x16x32_bf16 v[86:89], v[188:191], v[218:221], v[86:89]
	v_mfma_f32_16x16x32_bf16 v[74:77], v[162:165], v[226:229], v[74:77]
	v_mfma_f32_16x16x32_bf16 v[70:73], v[188:191], v[226:229], v[70:73]
	s_barrier
	s_setprio 1
	s_add_u32 s98, s52, s12
	s_addc_u32 s99, s53, s13
	s_add_u32 s100, s54, s12
	s_addc_u32 s101, s55, s13
	s_add_i32 s81, s68, s56
	s_mov_b32 m0, s81
	ds_read_b128 v[192:195], v200 offset:16384
	ds_read_b128 v[202:205], v200 offset:17408
	ds_read_b128 v[206:209], v200 offset:18432
	ds_read_b128 v[210:213], v200 offset:19456
	ds_read_b128 v[214:217], v200 offset:20480
	ds_read_b128 v[218:221], v200 offset:21504
	ds_read_b128 v[222:225], v200 offset:22528
	ds_read_b128 v[226:229], v200 offset:23552
	global_load_lds_dwordx4 v176, s[52:53]
	s_add_i32 m0, s81, 0x2000
	s_add_u32 s82, s52, 0x40000
	s_addc_u32 s83, s53, 0
	s_add_i32 s81, s69, s56
	global_load_lds_dwordx4 v172, s[52:53]
	s_mov_b32 m0, s81
	s_nop 0
	global_load_lds_dwordx4 v176, s[82:83]
	v_lshl_add_u64 v[4:5], s[82:83], 0, v[172:173]
	s_add_i32 m0, s81, 0x2000
	v_lshl_add_u64 v[234:235], s[54:55], 0, v[174:175]
	global_load_lds_dwordx4 v172, s[82:83]
	s_mov_b32 m0, s59
	s_nop 0
	global_load_lds_dwordx4 v178, s[54:55]
	s_mov_b32 m0, s60
	s_nop 0
	global_load_lds_dwordx4 v174, s[54:55]
	s_waitcnt vmcnt(8)
	s_waitcnt lgkmcnt(0)
	s_setprio 0
	s_barrier
; #define PG8_STAGE(bufoff, gbase, voff) do { _Pragma("unroll") for (int _i = 0; _i < 2; ++_i) \
;         __builtin_amdgcn_global_load_lds((const unsigned*)((const char*)(gbase) + (voff)[_i]), (LAS unsigned*)(lds + (bufoff) + ldsw + _i * 8192), 16, 0, 0); } while (0)
; #define PG8_LDA(dst, b, h) do { _Pragma("unroll") for (int m = 0; m < 4; ++m) _Pragma("unroll") for (int k = 0; k < 2; ++k) dst[m][k] = *(const LAS bf16x8*)(lds + PG8_SA(b, h) + aoff + m * 2048 + k * 1024); } while (0)
; #define PG8_LDB(dst, b, h) do { _Pragma("unroll") for (int n = 0; n < 2; ++n) _Pragma("unroll") for (int k = 0; k < 2; ++k) dst[n][k] = *(const LAS bf16x8*)(lds + PG8_SB(b, h) + boff + n * 2048 + k * 1024); } while (0)
; #define PG8_MMA(ai, bj, At, Bt) do { __builtin_amdgcn_s_setprio(1); _Pragma("unroll") for (int m = 0; m < 4; ++m) _Pragma("unroll") for (int n = 0; n < 2; ++n) _Pragma("unroll") for (int k = 0; k < 2; ++k) \
;         acc[ai][bj][m][n] = __builtin_amdgcn_mfma_f32_16x16x32_bf16(Bt[n][k], At[m][k], acc[ai][bj][m][n], 0, 0, 0); __builtin_amdgcn_s_setprio(0); } while (0)
; #define PG8_WAIT_V(n) asm volatile("s_waitcnt vmcnt(" #n ")" ::: "memory")
; #define PG8_WAIT_L(n) asm volatile("s_waitcnt lgkmcnt(" #n ")" ::: "memory")
; #define PG8_BAR __builtin_amdgcn_s_barrier()
; #define PG8_SCHED __builtin_amdgcn_sched_barrier(0)
; template <class Epi>
; __device__ __forceinline__ void gemm_phase(LAS unsigned char* lds, const Gemm g, const StaticOrder& S, const Epi& E) {
;     ...
;             PG8_WAIT_V(8); PG8_WAIT_L(0); PG8_BAR; PG8_MMA(1, 0, At, B0); PG8_MMA(1, 1, At, B1); PG8_BAR; PG8_SCHED;
;             PG8_LDB(B0, 1, 0); PG8_LDB(B1, 1, 1); PG8_SCHED; PG8_LDA(At, 1, 0); PG8_STAGE(PG8_SA(0, 1), a2 + hstep, voffA);
;             PG8_WAIT_V(8); PG8_WAIT_L(0); PG8_BAR; PG8_MMA(0, 0, At, B0); PG8_MMA(0, 1, At, B1); PG8_BAR; PG8_SCHED;
	v_mfma_f32_16x16x32_bf16 v[66:69], v[134:137], v[192:195], v[66:69]
	v_mfma_f32_16x16x32_bf16 v[62:65], v[142:145], v[192:195], v[62:65]
	v_mfma_f32_16x16x32_bf16 v[50:53], v[134:137], v[206:209], v[50:53]
	v_mfma_f32_16x16x32_bf16 v[46:49], v[142:145], v[206:209], v[46:49]
	v_mfma_f32_16x16x32_bf16 v[34:37], v[134:137], v[214:217], v[34:37]
	v_mfma_f32_16x16x32_bf16 v[30:33], v[142:145], v[214:217], v[30:33]
	v_mfma_f32_16x16x32_bf16 v[18:21], v[134:137], v[222:225], v[18:21]
	v_mfma_f32_16x16x32_bf16 v[14:17], v[142:145], v[222:225], v[14:17]
	v_mfma_f32_16x16x32_bf16 v[66:69], v[138:141], v[202:205], v[66:69]
	v_mfma_f32_16x16x32_bf16 v[62:65], v[146:149], v[202:205], v[62:65]
	v_mfma_f32_16x16x32_bf16 v[50:53], v[138:141], v[210:213], v[50:53]
	v_mfma_f32_16x16x32_bf16 v[46:49], v[146:149], v[210:213], v[46:49]
	v_mfma_f32_16x16x32_bf16 v[34:37], v[138:141], v[218:221], v[34:37]
	v_mfma_f32_16x16x32_bf16 v[30:33], v[146:149], v[218:221], v[30:33]
	v_mfma_f32_16x16x32_bf16 v[18:21], v[138:141], v[226:229], v[18:21]
	v_mfma_f32_16x16x32_bf16 v[14:17], v[146:149], v[226:229], v[14:17]
	v_mfma_f32_16x16x32_bf16 v[58:61], v[158:161], v[192:195], v[58:61]
	v_mfma_f32_16x16x32_bf16 v[54:57], v[166:169], v[192:195], v[54:57]
	v_mfma_f32_16x16x32_bf16 v[42:45], v[158:161], v[206:209], v[42:45]
	v_mfma_f32_16x16x32_bf16 v[38:41], v[166:169], v[206:209], v[38:41]
	v_mfma_f32_16x16x32_bf16 v[26:29], v[158:161], v[214:217], v[26:29]
	v_mfma_f32_16x16x32_bf16 v[22:25], v[166:169], v[214:217], v[22:25]
	v_mfma_f32_16x16x32_bf16 v[10:13], v[158:161], v[222:225], v[10:13]
	v_mfma_f32_16x16x32_bf16 v[4:7], v[166:169], v[222:225], v[6:9]
	v_mfma_f32_16x16x32_bf16 v[58:61], v[162:165], v[202:205], v[58:61]
	v_mfma_f32_16x16x32_bf16 v[54:57], v[188:191], v[202:205], v[54:57]
	v_mfma_f32_16x16x32_bf16 v[42:45], v[162:165], v[210:213], v[42:45]
	v_mfma_f32_16x16x32_bf16 v[38:41], v[188:191], v[210:213], v[38:41]
	v_mfma_f32_16x16x32_bf16 v[26:29], v[162:165], v[218:221], v[26:29]
	v_mfma_f32_16x16x32_bf16 v[22:25], v[188:191], v[218:221], v[22:25]
	v_mfma_f32_16x16x32_bf16 v[10:13], v[162:165], v[226:229], v[10:13]
	v_mfma_f32_16x16x32_bf16 v[4:7], v[188:191], v[226:229], v[4:7]
	s_barrier
	s_setprio 1
	s_add_i32 s81, 0, 0x18000
	v_add_u32_e32 v3, s81, v198
	s_add_i32 s82, 0, 0x1c000
	ds_read_b128 v[134:137], v3
	ds_read_b128 v[138:141], v3 offset:1024
	ds_read_b128 v[142:145], v3 offset:2048
	ds_read_b128 v[146:149], v3 offset:3072
	v_add_u32_e32 v3, s82, v198
	ds_read_b128 v[158:161], v3
	ds_read_b128 v[162:165], v3 offset:1024
	ds_read_b128 v[166:169], v3 offset:2048
	ds_read_b128 v[188:191], v3 offset:3072
	s_add_u32 s54, s54, 0x40000
	s_addc_u32 s55, s55, 0
	s_mov_b32 m0, s61
	ds_read_b128 v[192:195], v200 offset:32768
	ds_read_b128 v[202:205], v200 offset:33792
	ds_read_b128 v[206:209], v200 offset:34816
	ds_read_b128 v[210:213], v200 offset:35840
	ds_read_b128 v[214:217], v200 offset:36864
	ds_read_b128 v[218:221], v200 offset:37888
	ds_read_b128 v[222:225], v200 offset:38912
	ds_read_b128 v[226:229], v200 offset:39936
	global_load_lds_dwordx4 v178, s[54:55]
	s_mov_b32 m0, s62
	s_nop 0
	global_load_lds_dwordx4 v174, s[54:55]
	s_waitcnt vmcnt(8)
	s_waitcnt lgkmcnt(0)
	s_setprio 0
	s_barrier
	v_mfma_f32_16x16x32_bf16 v[130:133], v[134:137], v[192:195], v[130:133]
	v_mfma_f32_16x16x32_bf16 v[126:129], v[142:145], v[192:195], v[126:129]
	v_mfma_f32_16x16x32_bf16 v[114:117], v[134:137], v[206:209], v[114:117]
	v_mfma_f32_16x16x32_bf16 v[110:113], v[142:145], v[206:209], v[110:113]
	v_mfma_f32_16x16x32_bf16 v[98:101], v[134:137], v[214:217], v[98:101]
	v_mfma_f32_16x16x32_bf16 v[94:97], v[142:145], v[214:217], v[94:97]
	v_mfma_f32_16x16x32_bf16 v[82:85], v[134:137], v[222:225], v[82:85]
	v_mfma_f32_16x16x32_bf16 v[78:81], v[142:145], v[222:225], v[78:81]
	v_mfma_f32_16x16x32_bf16 v[130:133], v[138:141], v[202:205], v[130:133]
	v_mfma_f32_16x16x32_bf16 v[126:129], v[146:149], v[202:205], v[126:129]
	v_mfma_f32_16x16x32_bf16 v[114:117], v[138:141], v[210:213], v[114:117]
	v_mfma_f32_16x16x32_bf16 v[110:113], v[146:149], v[210:213], v[110:113]
	v_mfma_f32_16x16x32_bf16 v[98:101], v[138:141], v[218:221], v[98:101]
	v_mfma_f32_16x16x32_bf16 v[94:97], v[146:149], v[218:221], v[94:97]
	v_mfma_f32_16x16x32_bf16 v[82:85], v[138:141], v[226:229], v[82:85]
	v_mfma_f32_16x16x32_bf16 v[78:81], v[146:149], v[226:229], v[78:81]
	v_mfma_f32_16x16x32_bf16 v[122:125], v[158:161], v[192:195], v[122:125]
	v_mfma_f32_16x16x32_bf16 v[118:121], v[166:169], v[192:195], v[118:121]
	v_mfma_f32_16x16x32_bf16 v[106:109], v[158:161], v[206:209], v[106:109]
	v_mfma_f32_16x16x32_bf16 v[102:105], v[166:169], v[206:209], v[102:105]
	v_mfma_f32_16x16x32_bf16 v[90:93], v[158:161], v[214:217], v[90:93]
	v_mfma_f32_16x16x32_bf16 v[86:89], v[166:169], v[214:217], v[86:89]
	v_mfma_f32_16x16x32_bf16 v[74:77], v[158:161], v[222:225], v[74:77]
	v_mfma_f32_16x16x32_bf16 v[70:73], v[166:169], v[222:225], v[70:73]
	v_mfma_f32_16x16x32_bf16 v[122:125], v[162:165], v[202:205], v[122:125]
	v_mfma_f32_16x16x32_bf16 v[118:121], v[188:191], v[202:205], v[118:121]
	v_mfma_f32_16x16x32_bf16 v[106:109], v[162:165], v[210:213], v[106:109]
	v_mfma_f32_16x16x32_bf16 v[102:105], v[188:191], v[210:213], v[102:105]
	v_mfma_f32_16x16x32_bf16 v[90:93], v[162:165], v[218:221], v[90:93]
	v_mfma_f32_16x16x32_bf16 v[86:89], v[188:191], v[218:221], v[86:89]
	v_mfma_f32_16x16x32_bf16 v[74:77], v[162:165], v[226:229], v[74:77]
	v_mfma_f32_16x16x32_bf16 v[70:73], v[188:191], v[226:229], v[70:73]
	s_barrier
; #define PG8_STAGE(bufoff, gbase, voff) do { _Pragma("unroll") for (int _i = 0; _i < 2; ++_i) \
;         __builtin_amdgcn_global_load_lds((const unsigned*)((const char*)(gbase) + (voff)[_i]), (LAS unsigned*)(lds + (bufoff) + ldsw + _i * 8192), 16, 0, 0); } while (0)
; #define PG8_LDA(dst, b, h) do { _Pragma("unroll") for (int m = 0; m < 4; ++m) _Pragma("unroll") for (int k = 0; k < 2; ++k) dst[m][k] = *(const LAS bf16x8*)(lds + PG8_SA(b, h) + aoff + m * 2048 + k * 1024); } while (0)
; #define PG8_MMA(ai, bj, At, Bt) do { __builtin_amdgcn_s_setprio(1); _Pragma("unroll") for (int m = 0; m < 4; ++m) _Pragma("unroll") for (int n = 0; n < 2; ++n) _Pragma("unroll") for (int k = 0; k < 2; ++k) \
;         acc[ai][bj][m][n] = __builtin_amdgcn_mfma_f32_16x16x32_bf16(Bt[n][k], At[m][k], acc[ai][bj][m][n], 0, 0, 0); __builtin_amdgcn_s_setprio(0); } while (0)
; #define PG8_WAIT_V(n) asm volatile("s_waitcnt vmcnt(" #n ")" ::: "memory")
; #define PG8_WAIT_L(n) asm volatile("s_waitcnt lgkmcnt(" #n ")" ::: "memory")
; #define PG8_BAR __builtin_amdgcn_s_barrier()
; #define PG8_SCHED __builtin_amdgcn_sched_barrier(0)
; template <class Epi>
; __device__ __forceinline__ void gemm_phase(LAS unsigned char* lds, const Gemm g, const StaticOrder& S, const Epi& E) {
;     ...
;             PG8_LDA(At, 1, 1); PG8_STAGE(PG8_SB(1, 0), b3, voffB); PG8_STAGE(PG8_SB(1, 1), b3 + hstep, voffB); PG8_STAGE(PG8_SA(1, 0), a3, voffA);
;             PG8_WAIT_V(8); PG8_WAIT_L(0); PG8_BAR; PG8_MMA(1, 0, At, B0); PG8_MMA(1, 1, At, B1); PG8_BAR; PG8_SCHED;
;         }
	s_setprio 1
	s_add_i32 s54, s81, s56
	s_mov_b32 m0, s54
	ds_read_b128 v[192:195], v200 offset:49152
	ds_read_b128 v[202:205], v200 offset:50176
	ds_read_b128 v[206:209], v200 offset:51200
	ds_read_b128 v[210:213], v200 offset:52224
	ds_read_b128 v[214:217], v200 offset:53248
	ds_read_b128 v[218:221], v200 offset:54272
	ds_read_b128 v[222:225], v200 offset:55296
	ds_read_b128 v[226:229], v200 offset:56320
	global_load_lds_dwordx4 v176, s[98:99]
	s_add_i32 m0, s54, 0x2000
	s_add_u32 s52, s52, 0x40080
	s_addc_u32 s53, s53, 0
	s_add_i32 s54, s82, s56
	global_load_lds_dwordx4 v172, s[98:99]
	s_mov_b32 m0, s54
	s_nop 0
	global_load_lds_dwordx4 v176, s[52:53]
	s_add_i32 m0, s54, 0x2000
	s_nop 0
	global_load_lds_dwordx4 v172, s[52:53]
	s_mov_b32 m0, s64
	s_nop 0
	global_load_lds_dwordx4 v178, s[100:101]
	v_lshl_add_u64 v[8:9], v[234:235], 0, s[12:13]
	s_mov_b32 m0, s65
	s_nop 0
	global_load_lds_dwordx4 v174, s[100:101]
	s_waitcnt vmcnt(8)
	s_waitcnt lgkmcnt(0)
	s_setprio 0
	s_barrier
	v_mfma_f32_16x16x32_bf16 v[66:69], v[134:137], v[192:195], v[66:69]
	v_mfma_f32_16x16x32_bf16 v[62:65], v[142:145], v[192:195], v[62:65]
	v_mfma_f32_16x16x32_bf16 v[50:53], v[134:137], v[206:209], v[50:53]
	v_mfma_f32_16x16x32_bf16 v[46:49], v[142:145], v[206:209], v[46:49]
	v_mfma_f32_16x16x32_bf16 v[34:37], v[134:137], v[214:217], v[34:37]
	v_mfma_f32_16x16x32_bf16 v[30:33], v[142:145], v[214:217], v[30:33]
	v_mfma_f32_16x16x32_bf16 v[18:21], v[134:137], v[222:225], v[18:21]
	v_mfma_f32_16x16x32_bf16 v[14:17], v[142:145], v[222:225], v[14:17]
	v_mfma_f32_16x16x32_bf16 v[66:69], v[138:141], v[202:205], v[66:69]
	v_mfma_f32_16x16x32_bf16 v[62:65], v[146:149], v[202:205], v[62:65]
	v_mfma_f32_16x16x32_bf16 v[50:53], v[138:141], v[210:213], v[50:53]
	v_mfma_f32_16x16x32_bf16 v[46:49], v[146:149], v[210:213], v[46:49]
	v_mfma_f32_16x16x32_bf16 v[34:37], v[138:141], v[218:221], v[34:37]
	v_mfma_f32_16x16x32_bf16 v[30:33], v[146:149], v[218:221], v[30:33]
	v_mfma_f32_16x16x32_bf16 v[18:21], v[138:141], v[226:229], v[18:21]
	v_mfma_f32_16x16x32_bf16 v[14:17], v[146:149], v[226:229], v[14:17]
	v_mfma_f32_16x16x32_bf16 v[58:61], v[158:161], v[192:195], v[58:61]
	v_mfma_f32_16x16x32_bf16 v[54:57], v[166:169], v[192:195], v[54:57]
	v_mfma_f32_16x16x32_bf16 v[42:45], v[158:161], v[206:209], v[42:45]
	v_mfma_f32_16x16x32_bf16 v[38:41], v[166:169], v[206:209], v[38:41]
	v_mfma_f32_16x16x32_bf16 v[26:29], v[158:161], v[214:217], v[26:29]
	v_mfma_f32_16x16x32_bf16 v[22:25], v[166:169], v[214:217], v[22:25]
	v_mfma_f32_16x16x32_bf16 v[8:11], v[158:161], v[222:225], v[10:13]
	v_mfma_f32_16x16x32_bf16 v[4:7], v[166:169], v[222:225], v[4:7]
	v_mfma_f32_16x16x32_bf16 v[58:61], v[162:165], v[202:205], v[58:61]
	v_mfma_f32_16x16x32_bf16 v[54:57], v[188:191], v[202:205], v[54:57]
	v_mfma_f32_16x16x32_bf16 v[42:45], v[162:165], v[210:213], v[42:45]
	v_mfma_f32_16x16x32_bf16 v[38:41], v[188:191], v[210:213], v[38:41]
	v_mfma_f32_16x16x32_bf16 v[26:29], v[162:165], v[218:221], v[26:29]
	v_mfma_f32_16x16x32_bf16 v[22:25], v[188:191], v[218:221], v[22:25]
	v_mfma_f32_16x16x32_bf16 v[10:13], v[162:165], v[226:229], v[8:11]
	v_mfma_f32_16x16x32_bf16 v[6:9], v[188:191], v[226:229], v[4:7]
	s_barrier
	s_setprio 1
	s_add_i32 s80, s80, 2
	s_add_u32 s50, s50, 0x100
	s_addc_u32 s51, s51, 0
	s_cmp_gt_u32 s80, 13
	s_cbranch_scc1 .LBB0_703

; #define PG8_STAGE(bufoff, gbase, voff) do { _Pragma("unroll") for (int _i = 0; _i < 2; ++_i) \
;         __builtin_amdgcn_global_load_lds((const unsigned*)((const char*)(gbase) + (voff)[_i]), (LAS unsigned*)(lds + (bufoff) + ldsw + _i * 8192), 16, 0, 0); } while (0)
; #define PG8_LDA(dst, b, h) do { _Pragma("unroll") for (int m = 0; m < 4; ++m) _Pragma("unroll") for (int k = 0; k < 2; ++k) dst[m][k] = *(const LAS bf16x8*)(lds + PG8_SA(b, h) + aoff + m * 2048 + k * 1024); } while (0)
; #define PG8_LDB(dst, b, h) do { _Pragma("unroll") for (int n = 0; n < 2; ++n) _Pragma("unroll") for (int k = 0; k < 2; ++k) dst[n][k] = *(const LAS bf16x8*)(lds + PG8_SB(b, h) + boff + n * 2048 + k * 1024); } while (0)
; #define PG8_BAR __builtin_amdgcn_s_barrier()
; template <class Epi>
; __device__ __forceinline__ void gemm_phase(LAS unsigned char* lds, const Gemm g, const StaticOrder& S, const Epi& E) {
;     ...
;         for (int t = 0; t < nt; t += 2) {
;             const bool last = (t == nt - 2);
;             const char* a1 = cA + (size_t)(t + 1) * kstep;
;             const char* a2 = last ? nA : cA + (size_t)(t + 2) * kstep; const char* b2 = last ? nB : cB + (size_t)(t + 2) * kstep;
;             const char* a3 = a2 + kstep; const char* b3 = b2 + kstep;
;             if constexpr (Epi::MIDK > 0) { if (t == Epi::MIDK) E.mid(acc, cur, wr, wc, fr, fq); }
;             PG8_LDB(B0, 0, 0); PG8_LDB(B1, 0, 1); PG8_SCHED; PG8_LDA(At, 0, 0); PG8_STAGE(PG8_SA(1, 1), a1 + hstep, voffA);
;             PG8_WAIT_V(8); PG8_WAIT_L(0); PG8_BAR; PG8_MMA(0, 0, At, B0); PG8_MMA(0, 1, At, B1); PG8_BAR; PG8_SCHED;
;             PG8_LDA(At, 0, 1); PG8_STAGE(PG8_SB(0, 0), b2, voffB); PG8_STAGE(PG8_SB(0, 1), b2 + hstep, voffB); PG8_STAGE(PG8_SA(0, 0), a2, voffA);
;             PG8_WAIT_V(8); PG8_WAIT_L(0); PG8_BAR; PG8_MMA(1, 0, At, B0); PG8_MMA(1, 1, At, B1); PG8_BAR; PG8_SCHED;
;             PG8_LDB(B0, 1, 0); PG8_LDB(B1, 1, 1); PG8_SCHED; PG8_LDA(At, 1, 0); PG8_STAGE(PG8_SA(0, 1), a2 + hstep, voffA);
;             PG8_WAIT_V(8); PG8_WAIT_L(0); PG8_BAR; PG8_MMA(0, 0, At, B0); PG8_MMA(0, 1, At, B1); PG8_BAR; PG8_SCHED;
;             PG8_LDA(At, 1, 1); PG8_STAGE(PG8_SB(1, 0), b3, voffB); PG8_STAGE(PG8_SB(1, 1), b3 + hstep, voffB); PG8_STAGE(PG8_SA(1, 0), a3, voffA);
;             PG8_WAIT_V(8); PG8_WAIT_L(0); PG8_BAR; PG8_MMA(1, 0, At, B0); PG8_MMA(1, 1, At, B1); PG8_BAR; PG8_SCHED;
.LBB0_785:
	ds_read_b128 v[130:133], v162
	ds_read_b128 v[134:137], v162 offset:1024
	ds_read_b128 v[154:157], v162 offset:2048
	ds_read_b128 v[166:169], v162 offset:3072
	ds_read_b128 v[172:175], v163
	ds_read_b128 v[176:179], v163 offset:1024
	ds_read_b128 v[180:183], v163 offset:2048
	ds_read_b128 v[184:187], v163 offset:3072
	s_add_u32 s40, s38, 0xfffc0080
	s_addc_u32 s41, s39, -1
	s_cmp_eq_u32 s63, 12
	s_cselect_b32 s43, s21, s41
	s_cselect_b32 s42, s27, s40
	s_cselect_b32 s41, s19, s62
	s_cselect_b32 s40, s60, s61
	s_add_i32 m0, s45, 0xc000
	ds_read_b128 v[188:191], v164
	ds_read_b128 v[192:195], v164 offset:1024
	ds_read_b128 v[196:199], v164 offset:2048
	ds_read_b128 v[200:203], v164 offset:3072
	ds_read_b128 v[204:207], v164 offset:4096
	ds_read_b128 v[208:211], v164 offset:5120
	ds_read_b128 v[212:215], v164 offset:6144
	ds_read_b128 v[216:219], v164 offset:7168
	global_load_lds_dwordx4 v146, s[38:39]
	s_add_i32 m0, s45, 0xe000
	s_nop 0
	global_load_lds_dwordx4 v148, s[38:39]
	s_waitcnt vmcnt(8)
	s_waitcnt lgkmcnt(0)
	s_setprio 0
	s_barrier
	v_mfma_f32_16x16x32_bf16 v[126:129], v[130:133], v[188:191], v[126:129]
	v_mfma_f32_16x16x32_bf16 v[122:125], v[154:157], v[188:191], v[122:125]
	v_mfma_f32_16x16x32_bf16 v[110:113], v[130:133], v[196:199], v[110:113]
	v_mfma_f32_16x16x32_bf16 v[106:109], v[154:157], v[196:199], v[106:109]
	v_mfma_f32_16x16x32_bf16 v[94:97], v[130:133], v[204:207], v[94:97]
	v_mfma_f32_16x16x32_bf16 v[90:93], v[154:157], v[204:207], v[90:93]
	v_mfma_f32_16x16x32_bf16 v[78:81], v[130:133], v[212:215], v[78:81]
	v_mfma_f32_16x16x32_bf16 v[74:77], v[154:157], v[212:215], v[74:77]
	v_mfma_f32_16x16x32_bf16 v[126:129], v[134:137], v[192:195], v[126:129]
	v_mfma_f32_16x16x32_bf16 v[122:125], v[166:169], v[192:195], v[122:125]
	v_mfma_f32_16x16x32_bf16 v[110:113], v[134:137], v[200:203], v[110:113]
	v_mfma_f32_16x16x32_bf16 v[106:109], v[166:169], v[200:203], v[106:109]
	v_mfma_f32_16x16x32_bf16 v[94:97], v[134:137], v[208:211], v[94:97]
	v_mfma_f32_16x16x32_bf16 v[90:93], v[166:169], v[208:211], v[90:93]
	v_mfma_f32_16x16x32_bf16 v[78:81], v[134:137], v[216:219], v[78:81]
	v_mfma_f32_16x16x32_bf16 v[74:77], v[166:169], v[216:219], v[74:77]
	v_mfma_f32_16x16x32_bf16 v[118:121], v[172:175], v[188:191], v[118:121]
	v_mfma_f32_16x16x32_bf16 v[114:117], v[180:183], v[188:191], v[114:117]
	v_mfma_f32_16x16x32_bf16 v[102:105], v[172:175], v[196:199], v[102:105]
	v_mfma_f32_16x16x32_bf16 v[98:101], v[180:183], v[196:199], v[98:101]
	v_mfma_f32_16x16x32_bf16 v[86:89], v[172:175], v[204:207], v[86:89]
	v_mfma_f32_16x16x32_bf16 v[82:85], v[180:183], v[204:207], v[82:85]
	v_mfma_f32_16x16x32_bf16 v[70:73], v[172:175], v[212:215], v[70:73]
	v_mfma_f32_16x16x32_bf16 v[66:69], v[180:183], v[212:215], v[66:69]
	v_mfma_f32_16x16x32_bf16 v[118:121], v[176:179], v[192:195], v[118:121]
	v_mfma_f32_16x16x32_bf16 v[114:117], v[184:187], v[192:195], v[114:117]
	v_mfma_f32_16x16x32_bf16 v[102:105], v[176:179], v[200:203], v[102:105]
	v_mfma_f32_16x16x32_bf16 v[98:101], v[184:187], v[200:203], v[98:101]
	v_mfma_f32_16x16x32_bf16 v[86:89], v[176:179], v[208:211], v[86:89]
	v_mfma_f32_16x16x32_bf16 v[82:85], v[184:187], v[208:211], v[82:85]
	v_mfma_f32_16x16x32_bf16 v[70:73], v[176:179], v[216:219], v[70:73]
	v_mfma_f32_16x16x32_bf16 v[66:69], v[184:187], v[216:219], v[66:69]
	s_barrier
	s_setprio 1
	s_add_u32 s98, s40, s12
	s_addc_u32 s99, s41, s13
	s_add_u32 s100, s42, s12
	s_addc_u32 s101, s43, s13
	s_add_i32 s64, s57, s44
	s_mov_b32 m0, s64
	ds_read_b128 v[188:191], v164 offset:16384
	ds_read_b128 v[192:195], v164 offset:17408
	ds_read_b128 v[196:199], v164 offset:18432
	ds_read_b128 v[200:203], v164 offset:19456
	ds_read_b128 v[204:207], v164 offset:20480
	ds_read_b128 v[208:211], v164 offset:21504
	ds_read_b128 v[212:215], v164 offset:22528
	ds_read_b128 v[216:219], v164 offset:23552
	global_load_lds_dwordx4 v140, s[40:41]
	s_add_i32 m0, s64, 0x2000
	s_add_u32 s64, s40, 0x40000
	s_addc_u32 s65, s41, 0
	s_add_i32 s66, s58, s44
	global_load_lds_dwordx4 v144, s[40:41]
	s_mov_b32 m0, s66
	s_nop 0
	global_load_lds_dwordx4 v140, s[64:65]
	s_add_i32 m0, s66, 0x2000
	s_nop 0
	global_load_lds_dwordx4 v144, s[64:65]
	s_mov_b32 m0, s45
	s_nop 0
	global_load_lds_dwordx4 v138, s[42:43]
	s_mov_b32 m0, s46
	s_nop 0
	global_load_lds_dwordx4 v142, s[42:43]
	s_waitcnt vmcnt(8)
	s_waitcnt lgkmcnt(0)
	s_setprio 0
	s_barrier
	v_mfma_f32_16x16x32_bf16 v[62:65], v[130:133], v[188:191], v[62:65]
	v_mfma_f32_16x16x32_bf16 v[58:61], v[154:157], v[188:191], v[58:61]
	v_mfma_f32_16x16x32_bf16 v[46:49], v[130:133], v[196:199], v[46:49]
	v_mfma_f32_16x16x32_bf16 v[42:45], v[154:157], v[196:199], v[42:45]
	v_mfma_f32_16x16x32_bf16 v[30:33], v[130:133], v[204:207], v[30:33]
	v_mfma_f32_16x16x32_bf16 v[26:29], v[154:157], v[204:207], v[26:29]
	v_mfma_f32_16x16x32_bf16 v[14:17], v[130:133], v[212:215], v[14:17]
	v_mfma_f32_16x16x32_bf16 v[10:13], v[154:157], v[212:215], v[10:13]
	v_mfma_f32_16x16x32_bf16 v[62:65], v[134:137], v[192:195], v[62:65]
	v_mfma_f32_16x16x32_bf16 v[58:61], v[166:169], v[192:195], v[58:61]
	v_mfma_f32_16x16x32_bf16 v[46:49], v[134:137], v[200:203], v[46:49]
	v_mfma_f32_16x16x32_bf16 v[42:45], v[166:169], v[200:203], v[42:45]
	v_mfma_f32_16x16x32_bf16 v[30:33], v[134:137], v[208:211], v[30:33]
	v_mfma_f32_16x16x32_bf16 v[26:29], v[166:169], v[208:211], v[26:29]
	v_mfma_f32_16x16x32_bf16 v[14:17], v[134:137], v[216:219], v[14:17]
	v_mfma_f32_16x16x32_bf16 v[10:13], v[166:169], v[216:219], v[10:13]
	v_mfma_f32_16x16x32_bf16 v[54:57], v[172:175], v[188:191], v[54:57]
	v_mfma_f32_16x16x32_bf16 v[50:53], v[180:183], v[188:191], v[50:53]
	v_mfma_f32_16x16x32_bf16 v[38:41], v[172:175], v[196:199], v[38:41]
	v_mfma_f32_16x16x32_bf16 v[34:37], v[180:183], v[196:199], v[34:37]
	v_mfma_f32_16x16x32_bf16 v[22:25], v[172:175], v[204:207], v[22:25]
	v_mfma_f32_16x16x32_bf16 v[18:21], v[180:183], v[204:207], v[18:21]
	v_mfma_f32_16x16x32_bf16 v[6:9], v[172:175], v[212:215], v[6:9]
	v_mfma_f32_16x16x32_bf16 v[2:5], v[180:183], v[212:215], v[2:5]
	v_mfma_f32_16x16x32_bf16 v[54:57], v[176:179], v[192:195], v[54:57]
	v_mfma_f32_16x16x32_bf16 v[50:53], v[184:187], v[192:195], v[50:53]
	v_mfma_f32_16x16x32_bf16 v[38:41], v[176:179], v[200:203], v[38:41]
	v_mfma_f32_16x16x32_bf16 v[34:37], v[184:187], v[200:203], v[34:37]
	v_mfma_f32_16x16x32_bf16 v[22:25], v[176:179], v[208:211], v[22:25]
	v_mfma_f32_16x16x32_bf16 v[18:21], v[184:187], v[208:211], v[18:21]
	v_mfma_f32_16x16x32_bf16 v[6:9], v[176:179], v[216:219], v[6:9]
	v_mfma_f32_16x16x32_bf16 v[2:5], v[184:187], v[216:219], v[2:5]
	s_barrier
; #define PG8_STAGE(bufoff, gbase, voff) do { _Pragma("unroll") for (int _i = 0; _i < 2; ++_i) \
;         __builtin_amdgcn_global_load_lds((const unsigned*)((const char*)(gbase) + (voff)[_i]), (LAS unsigned*)(lds + (bufoff) + ldsw + _i * 8192), 16, 0, 0); } while (0)
; #define PG8_LDA(dst, b, h) do { _Pragma("unroll") for (int m = 0; m < 4; ++m) _Pragma("unroll") for (int k = 0; k < 2; ++k) dst[m][k] = *(const LAS bf16x8*)(lds + PG8_SA(b, h) + aoff + m * 2048 + k * 1024); } while (0)
; #define PG8_LDB(dst, b, h) do { _Pragma("unroll") for (int n = 0; n < 2; ++n) _Pragma("unroll") for (int k = 0; k < 2; ++k) dst[n][k] = *(const LAS bf16x8*)(lds + PG8_SB(b, h) + boff + n * 2048 + k * 1024); } while (0)
; #define PG8_MMA(ai, bj, At, Bt) do { __builtin_amdgcn_s_setprio(1); _Pragma("unroll") for (int m = 0; m < 4; ++m) _Pragma("unroll") for (int n = 0; n < 2; ++n) _Pragma("unroll") for (int k = 0; k < 2; ++k) \
;         acc[ai][bj][m][n] = __builtin_amdgcn_mfma_f32_16x16x32_bf16(Bt[n][k], At[m][k], acc[ai][bj][m][n], 0, 0, 0); __builtin_amdgcn_s_setprio(0); } while (0)
; #define PG8_WAIT_V(n) asm volatile("s_waitcnt vmcnt(" #n ")" ::: "memory")
; #define PG8_WAIT_L(n) asm volatile("s_waitcnt lgkmcnt(" #n ")" ::: "memory")
; #define PG8_BAR __builtin_amdgcn_s_barrier()
; #define PG8_SCHED __builtin_amdgcn_sched_barrier(0)
; template <class Epi>
; __device__ __forceinline__ void gemm_phase(LAS unsigned char* lds, const Gemm g, const StaticOrder& S, const Epi& E) {
;     ...
;             PG8_LDB(B0, 1, 0); PG8_LDB(B1, 1, 1); PG8_SCHED; PG8_LDA(At, 1, 0); PG8_STAGE(PG8_SA(0, 1), a2 + hstep, voffA);
;             PG8_WAIT_V(8); PG8_WAIT_L(0); PG8_BAR; PG8_MMA(0, 0, At, B0); PG8_MMA(0, 1, At, B1); PG8_BAR; PG8_SCHED;
;             PG8_LDA(At, 1, 1); PG8_STAGE(PG8_SB(1, 0), b3, voffB); PG8_STAGE(PG8_SB(1, 1), b3 + hstep, voffB); PG8_STAGE(PG8_SA(1, 0), a3, voffA);
;             PG8_WAIT_V(8); PG8_WAIT_L(0); PG8_BAR; PG8_MMA(1, 0, At, B0); PG8_MMA(1, 1, At, B1); PG8_BAR; PG8_SCHED;
;         }
	s_setprio 1
	s_add_i32 s64, 0, 0x18000
	s_add_i32 s65, 0, 0x1c000
	v_add_u32_e32 v166, s64, v160
	v_add_u32_e32 v184, s65, v160
	ds_read_b128 v[130:133], v166
	ds_read_b128 v[134:137], v166 offset:1024
	ds_read_b128 v[154:157], v166 offset:2048
	ds_read_b128 v[166:169], v166 offset:3072
	ds_read_b128 v[172:175], v184
	ds_read_b128 v[176:179], v184 offset:1024
	ds_read_b128 v[180:183], v184 offset:2048
	ds_read_b128 v[184:187], v184 offset:3072
	s_add_u32 s42, s42, 0x40000
	s_addc_u32 s43, s43, 0
	s_mov_b32 m0, s47
	ds_read_b128 v[188:191], v164 offset:32768
	ds_read_b128 v[192:195], v164 offset:33792
	ds_read_b128 v[196:199], v164 offset:34816
	ds_read_b128 v[200:203], v164 offset:35840
	ds_read_b128 v[204:207], v164 offset:36864
	ds_read_b128 v[208:211], v164 offset:37888
	ds_read_b128 v[212:215], v164 offset:38912
	ds_read_b128 v[216:219], v164 offset:39936
	global_load_lds_dwordx4 v138, s[42:43]
	s_mov_b32 m0, s48
	s_nop 0
	global_load_lds_dwordx4 v142, s[42:43]
	s_waitcnt vmcnt(8)
	s_waitcnt lgkmcnt(0)
	s_setprio 0
	s_barrier
	v_mfma_f32_16x16x32_bf16 v[126:129], v[130:133], v[188:191], v[126:129]
	v_mfma_f32_16x16x32_bf16 v[122:125], v[154:157], v[188:191], v[122:125]
	v_mfma_f32_16x16x32_bf16 v[110:113], v[130:133], v[196:199], v[110:113]
	v_mfma_f32_16x16x32_bf16 v[106:109], v[154:157], v[196:199], v[106:109]
	v_mfma_f32_16x16x32_bf16 v[94:97], v[130:133], v[204:207], v[94:97]
	v_mfma_f32_16x16x32_bf16 v[90:93], v[154:157], v[204:207], v[90:93]
	v_mfma_f32_16x16x32_bf16 v[78:81], v[130:133], v[212:215], v[78:81]
	v_mfma_f32_16x16x32_bf16 v[74:77], v[154:157], v[212:215], v[74:77]
	v_mfma_f32_16x16x32_bf16 v[126:129], v[134:137], v[192:195], v[126:129]
	v_mfma_f32_16x16x32_bf16 v[122:125], v[166:169], v[192:195], v[122:125]
	v_mfma_f32_16x16x32_bf16 v[110:113], v[134:137], v[200:203], v[110:113]
	v_mfma_f32_16x16x32_bf16 v[106:109], v[166:169], v[200:203], v[106:109]
	v_mfma_f32_16x16x32_bf16 v[94:97], v[134:137], v[208:211], v[94:97]
	v_mfma_f32_16x16x32_bf16 v[90:93], v[166:169], v[208:211], v[90:93]
	v_mfma_f32_16x16x32_bf16 v[78:81], v[134:137], v[216:219], v[78:81]
	v_mfma_f32_16x16x32_bf16 v[74:77], v[166:169], v[216:219], v[74:77]
	v_mfma_f32_16x16x32_bf16 v[118:121], v[172:175], v[188:191], v[118:121]
	v_mfma_f32_16x16x32_bf16 v[114:117], v[180:183], v[188:191], v[114:117]
	v_mfma_f32_16x16x32_bf16 v[102:105], v[172:175], v[196:199], v[102:105]
	v_mfma_f32_16x16x32_bf16 v[98:101], v[180:183], v[196:199], v[98:101]
	v_mfma_f32_16x16x32_bf16 v[86:89], v[172:175], v[204:207], v[86:89]
	v_mfma_f32_16x16x32_bf16 v[82:85], v[180:183], v[204:207], v[82:85]
	v_mfma_f32_16x16x32_bf16 v[70:73], v[172:175], v[212:215], v[70:73]
	v_mfma_f32_16x16x32_bf16 v[66:69], v[180:183], v[212:215], v[66:69]
	v_mfma_f32_16x16x32_bf16 v[118:121], v[176:179], v[192:195], v[118:121]
	v_mfma_f32_16x16x32_bf16 v[114:117], v[184:187], v[192:195], v[114:117]
	v_mfma_f32_16x16x32_bf16 v[102:105], v[176:179], v[200:203], v[102:105]
	v_mfma_f32_16x16x32_bf16 v[98:101], v[184:187], v[200:203], v[98:101]
	v_mfma_f32_16x16x32_bf16 v[86:89], v[176:179], v[208:211], v[86:89]
	v_mfma_f32_16x16x32_bf16 v[82:85], v[184:187], v[208:211], v[82:85]
	v_mfma_f32_16x16x32_bf16 v[70:73], v[176:179], v[216:219], v[70:73]
	v_mfma_f32_16x16x32_bf16 v[66:69], v[184:187], v[216:219], v[66:69]
	s_barrier
	s_setprio 1
	s_add_i32 s42, s64, s44
	s_mov_b32 m0, s42
	ds_read_b128 v[188:191], v164 offset:49152
	ds_read_b128 v[192:195], v164 offset:50176
	ds_read_b128 v[196:199], v164 offset:51200
	ds_read_b128 v[200:203], v164 offset:52224
	ds_read_b128 v[204:207], v164 offset:53248
	ds_read_b128 v[208:211], v164 offset:54272
	ds_read_b128 v[212:215], v164 offset:55296
	ds_read_b128 v[216:219], v164 offset:56320
	global_load_lds_dwordx4 v140, s[98:99]
	s_add_i32 m0, s42, 0x2000
	s_add_u32 s40, s40, 0x40080
	s_addc_u32 s41, s41, 0
	s_add_i32 s42, s65, s44
	global_load_lds_dwordx4 v144, s[98:99]
	s_mov_b32 m0, s42
	s_nop 0
	global_load_lds_dwordx4 v140, s[40:41]
	s_add_i32 m0, s42, 0x2000
	s_nop 0
	global_load_lds_dwordx4 v144, s[40:41]
	s_mov_b32 m0, s50
	s_nop 0
	global_load_lds_dwordx4 v138, s[100:101]
	s_mov_b32 m0, s51
	s_nop 0
	global_load_lds_dwordx4 v142, s[100:101]
	s_waitcnt vmcnt(8)
	s_waitcnt lgkmcnt(0)
	s_setprio 0
	s_barrier
	v_mfma_f32_16x16x32_bf16 v[62:65], v[130:133], v[188:191], v[62:65]
	v_mfma_f32_16x16x32_bf16 v[58:61], v[154:157], v[188:191], v[58:61]
	v_mfma_f32_16x16x32_bf16 v[46:49], v[130:133], v[196:199], v[46:49]
	v_mfma_f32_16x16x32_bf16 v[42:45], v[154:157], v[196:199], v[42:45]
	v_mfma_f32_16x16x32_bf16 v[30:33], v[130:133], v[204:207], v[30:33]
	v_mfma_f32_16x16x32_bf16 v[26:29], v[154:157], v[204:207], v[26:29]
	v_mfma_f32_16x16x32_bf16 v[14:17], v[130:133], v[212:215], v[14:17]
	v_mfma_f32_16x16x32_bf16 v[10:13], v[154:157], v[212:215], v[10:13]
	v_mfma_f32_16x16x32_bf16 v[62:65], v[134:137], v[192:195], v[62:65]
	v_mfma_f32_16x16x32_bf16 v[58:61], v[166:169], v[192:195], v[58:61]
	v_mfma_f32_16x16x32_bf16 v[46:49], v[134:137], v[200:203], v[46:49]
	v_mfma_f32_16x16x32_bf16 v[42:45], v[166:169], v[200:203], v[42:45]
	v_mfma_f32_16x16x32_bf16 v[30:33], v[134:137], v[208:211], v[30:33]
	v_mfma_f32_16x16x32_bf16 v[26:29], v[166:169], v[208:211], v[26:29]
	v_mfma_f32_16x16x32_bf16 v[14:17], v[134:137], v[216:219], v[14:17]
	v_mfma_f32_16x16x32_bf16 v[10:13], v[166:169], v[216:219], v[10:13]
	v_mfma_f32_16x16x32_bf16 v[54:57], v[172:175], v[188:191], v[54:57]
	v_mfma_f32_16x16x32_bf16 v[50:53], v[180:183], v[188:191], v[50:53]
	v_mfma_f32_16x16x32_bf16 v[38:41], v[172:175], v[196:199], v[38:41]
	v_mfma_f32_16x16x32_bf16 v[34:37], v[180:183], v[196:199], v[34:37]
	v_mfma_f32_16x16x32_bf16 v[22:25], v[172:175], v[204:207], v[22:25]
	v_mfma_f32_16x16x32_bf16 v[18:21], v[180:183], v[204:207], v[18:21]
	v_mfma_f32_16x16x32_bf16 v[6:9], v[172:175], v[212:215], v[6:9]
	v_mfma_f32_16x16x32_bf16 v[2:5], v[180:183], v[212:215], v[2:5]
	v_mfma_f32_16x16x32_bf16 v[54:57], v[176:179], v[192:195], v[54:57]
	v_mfma_f32_16x16x32_bf16 v[50:53], v[184:187], v[192:195], v[50:53]
	v_mfma_f32_16x16x32_bf16 v[38:41], v[176:179], v[200:203], v[38:41]
	v_mfma_f32_16x16x32_bf16 v[34:37], v[184:187], v[200:203], v[34:37]
	v_mfma_f32_16x16x32_bf16 v[22:25], v[176:179], v[208:211], v[22:25]
	v_mfma_f32_16x16x32_bf16 v[18:21], v[184:187], v[208:211], v[18:21]
	v_mfma_f32_16x16x32_bf16 v[6:9], v[176:179], v[216:219], v[6:9]
	v_mfma_f32_16x16x32_bf16 v[2:5], v[184:187], v[216:219], v[2:5]
	s_barrier
	s_setprio 1
	s_add_i32 s63, s63, 2
	s_add_u32 s38, s38, 0x100
	s_addc_u32 s39, s39, 0
	s_add_u32 s61, s61, 0x100
	s_addc_u32 s62, s62, 0
	s_cmp_gt_u32 s63, 13
	s_cbranch_scc0 .LBB0_785
	s_and_b64 vcc, exec, s[14:15]
	s_cbranch_vccz .LBB0_788
	s_barrier

; #define PG8_STAGE(bufoff, gbase, voff) do { _Pragma("unroll") for (int _i = 0; _i < 2; ++_i) \
;         __builtin_amdgcn_global_load_lds((const unsigned*)((const char*)(gbase) + (voff)[_i]), (LAS unsigned*)(lds + (bufoff) + ldsw + _i * 8192), 16, 0, 0); } while (0)
; #define PG8_LDA(dst, b, h) do { _Pragma("unroll") for (int m = 0; m < 4; ++m) _Pragma("unroll") for (int k = 0; k < 2; ++k) dst[m][k] = *(const LAS bf16x8*)(lds + PG8_SA(b, h) + aoff + m * 2048 + k * 1024); } while (0)
; #define PG8_LDB(dst, b, h) do { _Pragma("unroll") for (int n = 0; n < 2; ++n) _Pragma("unroll") for (int k = 0; k < 2; ++k) dst[n][k] = *(const LAS bf16x8*)(lds + PG8_SB(b, h) + boff + n * 2048 + k * 1024); } while (0)
; #define PG8_BAR __builtin_amdgcn_s_barrier()
; template <class Epi>
; __device__ __forceinline__ void gemm_phase(LAS unsigned char* lds, const Gemm g, const StaticOrder& S, const Epi& E) {
;     ...
;         for (int t = 0; t < nt; t += 2) {
;             const bool last = (t == nt - 2);
;             const char* a1 = cA + (size_t)(t + 1) * kstep;
;             const char* a2 = last ? nA : cA + (size_t)(t + 2) * kstep; const char* b2 = last ? nB : cB + (size_t)(t + 2) * kstep;
;             const char* a3 = a2 + kstep; const char* b3 = b2 + kstep;
;             if constexpr (Epi::MIDK > 0) { if (t == Epi::MIDK) E.mid(acc, cur, wr, wc, fr, fq); }
;             PG8_LDB(B0, 0, 0); PG8_LDB(B1, 0, 1); PG8_SCHED; PG8_LDA(At, 0, 0); PG8_STAGE(PG8_SA(1, 1), a1 + hstep, voffA);
;             PG8_WAIT_V(8); PG8_WAIT_L(0); PG8_BAR; PG8_MMA(0, 0, At, B0); PG8_MMA(0, 1, At, B1); PG8_BAR; PG8_SCHED;
;             PG8_LDA(At, 0, 1); PG8_STAGE(PG8_SB(0, 0), b2, voffB); PG8_STAGE(PG8_SB(0, 1), b2 + hstep, voffB); PG8_STAGE(PG8_SA(0, 0), a2, voffA);
;             PG8_WAIT_V(8); PG8_WAIT_L(0); PG8_BAR; PG8_MMA(1, 0, At, B0); PG8_MMA(1, 1, At, B1); PG8_BAR; PG8_SCHED;
;             PG8_LDB(B0, 1, 0); PG8_LDB(B1, 1, 1); PG8_SCHED; PG8_LDA(At, 1, 0); PG8_STAGE(PG8_SA(0, 1), a2 + hstep, voffA);
;             PG8_WAIT_V(8); PG8_WAIT_L(0); PG8_BAR; PG8_MMA(0, 0, At, B0); PG8_MMA(0, 1, At, B1); PG8_BAR; PG8_SCHED;
;             PG8_LDA(At, 1, 1); PG8_STAGE(PG8_SB(1, 0), b3, voffB); PG8_STAGE(PG8_SB(1, 1), b3 + hstep, voffB); PG8_STAGE(PG8_SA(1, 0), a3, voffA);
;             PG8_WAIT_V(8); PG8_WAIT_L(0); PG8_BAR; PG8_MMA(1, 0, At, B0); PG8_MMA(1, 1, At, B1); PG8_BAR; PG8_SCHED;
.LBB0_884:
	ds_read_b128 v[158:161], v150
	ds_read_b128 v[162:165], v150 offset:1024
	ds_read_b128 v[166:169], v150 offset:2048
	ds_read_b128 v[174:177], v150 offset:3072
	ds_read_b128 v[178:181], v151
	ds_read_b128 v[182:185], v151 offset:1024
	ds_read_b128 v[186:189], v151 offset:2048
	ds_read_b128 v[190:193], v151 offset:3072
	s_add_u32 s46, s44, 0xfffc0080
	s_addc_u32 s47, s45, -1
	s_cmp_eq_u32 s67, 12
	s_cselect_b32 s49, s62, s47
	s_cselect_b32 s48, s63, s46
	s_cselect_b32 s47, s23, s66
	s_cselect_b32 s46, s64, s65
	s_add_i32 m0, s41, 0xc000
	ds_read_b128 v[194:197], v152
	ds_read_b128 v[198:201], v152 offset:1024
	ds_read_b128 v[202:205], v152 offset:2048
	ds_read_b128 v[206:209], v152 offset:3072
	ds_read_b128 v[210:213], v152 offset:4096
	ds_read_b128 v[214:217], v152 offset:5120
	ds_read_b128 v[218:221], v152 offset:6144
	ds_read_b128 v[222:225], v152 offset:7168
	global_load_lds_dwordx4 v140, s[44:45]
	s_add_i32 m0, s41, 0xe000
	s_nop 0
	global_load_lds_dwordx4 v142, s[44:45]
	s_waitcnt vmcnt(8)
	s_waitcnt lgkmcnt(0)
	s_setprio 0
	s_barrier
	v_mfma_f32_16x16x32_bf16 v[126:129], v[158:161], v[194:197], v[126:129]
	v_mfma_f32_16x16x32_bf16 v[118:121], v[166:169], v[194:197], v[118:121]
	v_mfma_f32_16x16x32_bf16 v[110:113], v[158:161], v[202:205], v[110:113]
	v_mfma_f32_16x16x32_bf16 v[102:105], v[166:169], v[202:205], v[102:105]
	v_mfma_f32_16x16x32_bf16 v[94:97], v[158:161], v[210:213], v[94:97]
	v_mfma_f32_16x16x32_bf16 v[86:89], v[166:169], v[210:213], v[86:89]
	v_mfma_f32_16x16x32_bf16 v[78:81], v[158:161], v[218:221], v[78:81]
	v_mfma_f32_16x16x32_bf16 v[70:73], v[166:169], v[218:221], v[70:73]
	v_mfma_f32_16x16x32_bf16 v[126:129], v[162:165], v[198:201], v[126:129]
	v_mfma_f32_16x16x32_bf16 v[118:121], v[174:177], v[198:201], v[118:121]
	v_mfma_f32_16x16x32_bf16 v[110:113], v[162:165], v[206:209], v[110:113]
	v_mfma_f32_16x16x32_bf16 v[102:105], v[174:177], v[206:209], v[102:105]
	v_mfma_f32_16x16x32_bf16 v[94:97], v[162:165], v[214:217], v[94:97]
	v_mfma_f32_16x16x32_bf16 v[86:89], v[174:177], v[214:217], v[86:89]
	v_mfma_f32_16x16x32_bf16 v[78:81], v[162:165], v[222:225], v[78:81]
	v_mfma_f32_16x16x32_bf16 v[70:73], v[174:177], v[222:225], v[70:73]
	v_mfma_f32_16x16x32_bf16 v[122:125], v[178:181], v[194:197], v[122:125]
	v_mfma_f32_16x16x32_bf16 v[114:117], v[186:189], v[194:197], v[114:117]
	v_mfma_f32_16x16x32_bf16 v[106:109], v[178:181], v[202:205], v[106:109]
	v_mfma_f32_16x16x32_bf16 v[98:101], v[186:189], v[202:205], v[98:101]
	v_mfma_f32_16x16x32_bf16 v[90:93], v[178:181], v[210:213], v[90:93]
	v_mfma_f32_16x16x32_bf16 v[82:85], v[186:189], v[210:213], v[82:85]
	v_mfma_f32_16x16x32_bf16 v[74:77], v[178:181], v[218:221], v[74:77]
	v_mfma_f32_16x16x32_bf16 v[66:69], v[186:189], v[218:221], v[66:69]
	v_mfma_f32_16x16x32_bf16 v[122:125], v[182:185], v[198:201], v[122:125]
	v_mfma_f32_16x16x32_bf16 v[114:117], v[190:193], v[198:201], v[114:117]
	v_mfma_f32_16x16x32_bf16 v[106:109], v[182:185], v[206:209], v[106:109]
	v_mfma_f32_16x16x32_bf16 v[98:101], v[190:193], v[206:209], v[98:101]
	v_mfma_f32_16x16x32_bf16 v[90:93], v[182:185], v[214:217], v[90:93]
	v_mfma_f32_16x16x32_bf16 v[82:85], v[190:193], v[214:217], v[82:85]
	v_mfma_f32_16x16x32_bf16 v[74:77], v[182:185], v[222:225], v[74:77]
	v_mfma_f32_16x16x32_bf16 v[66:69], v[190:193], v[222:225], v[66:69]
	s_barrier
	s_setprio 1
	s_add_u32 s98, s46, s8
	s_addc_u32 s99, s47, s9
	s_add_u32 s100, s48, s8
	s_addc_u32 s101, s49, s9
	s_add_i32 s68, s58, s6
	s_mov_b32 m0, s68
	ds_read_b128 v[194:197], v152 offset:16384
	ds_read_b128 v[198:201], v152 offset:17408
	ds_read_b128 v[202:205], v152 offset:18432
	ds_read_b128 v[206:209], v152 offset:19456
	ds_read_b128 v[210:213], v152 offset:20480
	ds_read_b128 v[214:217], v152 offset:21504
	ds_read_b128 v[218:221], v152 offset:22528
	ds_read_b128 v[222:225], v152 offset:23552
	global_load_lds_dwordx4 v132, s[46:47]
	s_add_i32 m0, s68, 0x2000
	s_add_u32 s68, s46, 0x40000
	s_addc_u32 s69, s47, 0
	s_add_i32 s76, s59, s6
	global_load_lds_dwordx4 v136, s[46:47]
	s_mov_b32 m0, s76
	s_nop 0
	global_load_lds_dwordx4 v132, s[68:69]
	s_add_i32 m0, s76, 0x2000
	s_nop 0
	global_load_lds_dwordx4 v136, s[68:69]
	s_mov_b32 m0, s41
	s_nop 0
	global_load_lds_dwordx4 v130, s[48:49]
	s_mov_b32 m0, s43
	s_nop 0
	global_load_lds_dwordx4 v134, s[48:49]
	s_waitcnt vmcnt(8)
	s_waitcnt lgkmcnt(0)
	s_setprio 0
	s_barrier
	v_mfma_f32_16x16x32_bf16 v[62:65], v[158:161], v[194:197], v[62:65]
	v_mfma_f32_16x16x32_bf16 v[54:57], v[166:169], v[194:197], v[54:57]
	v_mfma_f32_16x16x32_bf16 v[46:49], v[158:161], v[202:205], v[46:49]
	v_mfma_f32_16x16x32_bf16 v[38:41], v[166:169], v[202:205], v[38:41]
	v_mfma_f32_16x16x32_bf16 v[30:33], v[158:161], v[210:213], v[30:33]
	v_mfma_f32_16x16x32_bf16 v[22:25], v[166:169], v[210:213], v[22:25]
	v_mfma_f32_16x16x32_bf16 v[14:17], v[158:161], v[218:221], v[14:17]
	v_mfma_f32_16x16x32_bf16 v[6:9], v[166:169], v[218:221], v[6:9]
	v_mfma_f32_16x16x32_bf16 v[62:65], v[162:165], v[198:201], v[62:65]
	v_mfma_f32_16x16x32_bf16 v[54:57], v[174:177], v[198:201], v[54:57]
	v_mfma_f32_16x16x32_bf16 v[46:49], v[162:165], v[206:209], v[46:49]
	v_mfma_f32_16x16x32_bf16 v[38:41], v[174:177], v[206:209], v[38:41]
	v_mfma_f32_16x16x32_bf16 v[30:33], v[162:165], v[214:217], v[30:33]
	v_mfma_f32_16x16x32_bf16 v[22:25], v[174:177], v[214:217], v[22:25]
	v_mfma_f32_16x16x32_bf16 v[14:17], v[162:165], v[222:225], v[14:17]
	v_mfma_f32_16x16x32_bf16 v[6:9], v[174:177], v[222:225], v[6:9]
	v_mfma_f32_16x16x32_bf16 v[58:61], v[178:181], v[194:197], v[58:61]
	v_mfma_f32_16x16x32_bf16 v[50:53], v[186:189], v[194:197], v[50:53]
	v_mfma_f32_16x16x32_bf16 v[42:45], v[178:181], v[202:205], v[42:45]
	v_mfma_f32_16x16x32_bf16 v[34:37], v[186:189], v[202:205], v[34:37]
	v_mfma_f32_16x16x32_bf16 v[26:29], v[178:181], v[210:213], v[26:29]
	v_mfma_f32_16x16x32_bf16 v[18:21], v[186:189], v[210:213], v[18:21]
	v_mfma_f32_16x16x32_bf16 v[10:13], v[178:181], v[218:221], v[10:13]
	v_mfma_f32_16x16x32_bf16 v[2:5], v[186:189], v[218:221], v[2:5]
	v_mfma_f32_16x16x32_bf16 v[58:61], v[182:185], v[198:201], v[58:61]
	v_mfma_f32_16x16x32_bf16 v[50:53], v[190:193], v[198:201], v[50:53]
	v_mfma_f32_16x16x32_bf16 v[42:45], v[182:185], v[206:209], v[42:45]
	v_mfma_f32_16x16x32_bf16 v[34:37], v[190:193], v[206:209], v[34:37]
	v_mfma_f32_16x16x32_bf16 v[26:29], v[182:185], v[214:217], v[26:29]
	v_mfma_f32_16x16x32_bf16 v[18:21], v[190:193], v[214:217], v[18:21]
	v_mfma_f32_16x16x32_bf16 v[10:13], v[182:185], v[222:225], v[10:13]
	v_mfma_f32_16x16x32_bf16 v[2:5], v[190:193], v[222:225], v[2:5]
	s_barrier
; #define PG8_STAGE(bufoff, gbase, voff) do { _Pragma("unroll") for (int _i = 0; _i < 2; ++_i) \
;         __builtin_amdgcn_global_load_lds((const unsigned*)((const char*)(gbase) + (voff)[_i]), (LAS unsigned*)(lds + (bufoff) + ldsw + _i * 8192), 16, 0, 0); } while (0)
; #define PG8_LDA(dst, b, h) do { _Pragma("unroll") for (int m = 0; m < 4; ++m) _Pragma("unroll") for (int k = 0; k < 2; ++k) dst[m][k] = *(const LAS bf16x8*)(lds + PG8_SA(b, h) + aoff + m * 2048 + k * 1024); } while (0)
; #define PG8_LDB(dst, b, h) do { _Pragma("unroll") for (int n = 0; n < 2; ++n) _Pragma("unroll") for (int k = 0; k < 2; ++k) dst[n][k] = *(const LAS bf16x8*)(lds + PG8_SB(b, h) + boff + n * 2048 + k * 1024); } while (0)
; #define PG8_MMA(ai, bj, At, Bt) do { __builtin_amdgcn_s_setprio(1); _Pragma("unroll") for (int m = 0; m < 4; ++m) _Pragma("unroll") for (int n = 0; n < 2; ++n) _Pragma("unroll") for (int k = 0; k < 2; ++k) \
;         acc[ai][bj][m][n] = __builtin_amdgcn_mfma_f32_16x16x32_bf16(Bt[n][k], At[m][k], acc[ai][bj][m][n], 0, 0, 0); __builtin_amdgcn_s_setprio(0); } while (0)
; #define PG8_WAIT_V(n) asm volatile("s_waitcnt vmcnt(" #n ")" ::: "memory")
; #define PG8_WAIT_L(n) asm volatile("s_waitcnt lgkmcnt(" #n ")" ::: "memory")
; #define PG8_BAR __builtin_amdgcn_s_barrier()
; #define PG8_SCHED __builtin_amdgcn_sched_barrier(0)
; template <class Epi>
; __device__ __forceinline__ void gemm_phase(LAS unsigned char* lds, const Gemm g, const StaticOrder& S, const Epi& E) {
;     ...
;             PG8_LDB(B0, 1, 0); PG8_LDB(B1, 1, 1); PG8_SCHED; PG8_LDA(At, 1, 0); PG8_STAGE(PG8_SA(0, 1), a2 + hstep, voffA);
;             PG8_WAIT_V(8); PG8_WAIT_L(0); PG8_BAR; PG8_MMA(0, 0, At, B0); PG8_MMA(0, 1, At, B1); PG8_BAR; PG8_SCHED;
;             PG8_LDA(At, 1, 1); PG8_STAGE(PG8_SB(1, 0), b3, voffB); PG8_STAGE(PG8_SB(1, 1), b3 + hstep, voffB); PG8_STAGE(PG8_SA(1, 0), a3, voffA);
;             PG8_WAIT_V(8); PG8_WAIT_L(0); PG8_BAR; PG8_MMA(1, 0, At, B0); PG8_MMA(1, 1, At, B1); PG8_BAR; PG8_SCHED;
;         }
	s_setprio 1
	s_add_i32 s68, 0, 0x18000
	s_add_i32 s69, 0, 0x1c000
	v_add_u32_e32 v174, s68, v148
	v_add_u32_e32 v190, s69, v148
	ds_read_b128 v[158:161], v174
	ds_read_b128 v[162:165], v174 offset:1024
	ds_read_b128 v[166:169], v174 offset:2048
	ds_read_b128 v[174:177], v174 offset:3072
	ds_read_b128 v[178:181], v190
	ds_read_b128 v[182:185], v190 offset:1024
	ds_read_b128 v[186:189], v190 offset:2048
	ds_read_b128 v[190:193], v190 offset:3072
	s_add_u32 s48, s48, 0x40000
	s_addc_u32 s49, s49, 0
	s_mov_b32 m0, s51
	ds_read_b128 v[194:197], v152 offset:32768
	ds_read_b128 v[198:201], v152 offset:33792
	ds_read_b128 v[202:205], v152 offset:34816
	ds_read_b128 v[206:209], v152 offset:35840
	ds_read_b128 v[210:213], v152 offset:36864
	ds_read_b128 v[214:217], v152 offset:37888
	ds_read_b128 v[218:221], v152 offset:38912
	ds_read_b128 v[222:225], v152 offset:39936
	global_load_lds_dwordx4 v130, s[48:49]
	s_mov_b32 m0, s52
	s_nop 0
	global_load_lds_dwordx4 v134, s[48:49]
	s_waitcnt vmcnt(8)
	s_waitcnt lgkmcnt(0)
	s_setprio 0
	s_barrier
	v_mfma_f32_16x16x32_bf16 v[126:129], v[158:161], v[194:197], v[126:129]
	v_mfma_f32_16x16x32_bf16 v[118:121], v[166:169], v[194:197], v[118:121]
	v_mfma_f32_16x16x32_bf16 v[110:113], v[158:161], v[202:205], v[110:113]
	v_mfma_f32_16x16x32_bf16 v[102:105], v[166:169], v[202:205], v[102:105]
	v_mfma_f32_16x16x32_bf16 v[94:97], v[158:161], v[210:213], v[94:97]
	v_mfma_f32_16x16x32_bf16 v[86:89], v[166:169], v[210:213], v[86:89]
	v_mfma_f32_16x16x32_bf16 v[78:81], v[158:161], v[218:221], v[78:81]
	v_mfma_f32_16x16x32_bf16 v[70:73], v[166:169], v[218:221], v[70:73]
	v_mfma_f32_16x16x32_bf16 v[126:129], v[162:165], v[198:201], v[126:129]
	v_mfma_f32_16x16x32_bf16 v[118:121], v[174:177], v[198:201], v[118:121]
	v_mfma_f32_16x16x32_bf16 v[110:113], v[162:165], v[206:209], v[110:113]
	v_mfma_f32_16x16x32_bf16 v[102:105], v[174:177], v[206:209], v[102:105]
	v_mfma_f32_16x16x32_bf16 v[94:97], v[162:165], v[214:217], v[94:97]
	v_mfma_f32_16x16x32_bf16 v[86:89], v[174:177], v[214:217], v[86:89]
	v_mfma_f32_16x16x32_bf16 v[78:81], v[162:165], v[222:225], v[78:81]
	v_mfma_f32_16x16x32_bf16 v[70:73], v[174:177], v[222:225], v[70:73]
	v_mfma_f32_16x16x32_bf16 v[122:125], v[178:181], v[194:197], v[122:125]
	v_mfma_f32_16x16x32_bf16 v[114:117], v[186:189], v[194:197], v[114:117]
	v_mfma_f32_16x16x32_bf16 v[106:109], v[178:181], v[202:205], v[106:109]
	v_mfma_f32_16x16x32_bf16 v[98:101], v[186:189], v[202:205], v[98:101]
	v_mfma_f32_16x16x32_bf16 v[90:93], v[178:181], v[210:213], v[90:93]
	v_mfma_f32_16x16x32_bf16 v[82:85], v[186:189], v[210:213], v[82:85]
	v_mfma_f32_16x16x32_bf16 v[74:77], v[178:181], v[218:221], v[74:77]
	v_mfma_f32_16x16x32_bf16 v[66:69], v[186:189], v[218:221], v[66:69]
	v_mfma_f32_16x16x32_bf16 v[122:125], v[182:185], v[198:201], v[122:125]
	v_mfma_f32_16x16x32_bf16 v[114:117], v[190:193], v[198:201], v[114:117]
	v_mfma_f32_16x16x32_bf16 v[106:109], v[182:185], v[206:209], v[106:109]
	v_mfma_f32_16x16x32_bf16 v[98:101], v[190:193], v[206:209], v[98:101]
	v_mfma_f32_16x16x32_bf16 v[90:93], v[182:185], v[214:217], v[90:93]
	v_mfma_f32_16x16x32_bf16 v[82:85], v[190:193], v[214:217], v[82:85]
	v_mfma_f32_16x16x32_bf16 v[74:77], v[182:185], v[222:225], v[74:77]
	v_mfma_f32_16x16x32_bf16 v[66:69], v[190:193], v[222:225], v[66:69]
	s_barrier
	s_setprio 1
	s_add_i32 s48, s68, s6
	s_mov_b32 m0, s48
	ds_read_b128 v[194:197], v152 offset:49152
	ds_read_b128 v[198:201], v152 offset:50176
	ds_read_b128 v[202:205], v152 offset:51200
	ds_read_b128 v[206:209], v152 offset:52224
	ds_read_b128 v[210:213], v152 offset:53248
	ds_read_b128 v[214:217], v152 offset:54272
	ds_read_b128 v[218:221], v152 offset:55296
	ds_read_b128 v[222:225], v152 offset:56320
	global_load_lds_dwordx4 v132, s[98:99]
	s_add_i32 m0, s48, 0x2000
	s_add_u32 s46, s46, 0x40080
	s_addc_u32 s47, s47, 0
	s_add_i32 s48, s69, s6
	global_load_lds_dwordx4 v136, s[98:99]
	s_mov_b32 m0, s48
	s_nop 0
	global_load_lds_dwordx4 v132, s[46:47]
	s_add_i32 m0, s48, 0x2000
	s_nop 0
	global_load_lds_dwordx4 v136, s[46:47]
	s_mov_b32 m0, s53
	s_nop 0
	global_load_lds_dwordx4 v130, s[100:101]
	s_mov_b32 m0, s54
	s_nop 0
	global_load_lds_dwordx4 v134, s[100:101]
	s_waitcnt vmcnt(8)
	s_waitcnt lgkmcnt(0)
	s_setprio 0
	s_barrier
	v_mfma_f32_16x16x32_bf16 v[62:65], v[158:161], v[194:197], v[62:65]
	v_mfma_f32_16x16x32_bf16 v[54:57], v[166:169], v[194:197], v[54:57]
	v_mfma_f32_16x16x32_bf16 v[46:49], v[158:161], v[202:205], v[46:49]
	v_mfma_f32_16x16x32_bf16 v[38:41], v[166:169], v[202:205], v[38:41]
	v_mfma_f32_16x16x32_bf16 v[30:33], v[158:161], v[210:213], v[30:33]
	v_mfma_f32_16x16x32_bf16 v[22:25], v[166:169], v[210:213], v[22:25]
	v_mfma_f32_16x16x32_bf16 v[14:17], v[158:161], v[218:221], v[14:17]
	v_mfma_f32_16x16x32_bf16 v[6:9], v[166:169], v[218:221], v[6:9]
	v_mfma_f32_16x16x32_bf16 v[62:65], v[162:165], v[198:201], v[62:65]
	v_mfma_f32_16x16x32_bf16 v[54:57], v[174:177], v[198:201], v[54:57]
	v_mfma_f32_16x16x32_bf16 v[46:49], v[162:165], v[206:209], v[46:49]
	v_mfma_f32_16x16x32_bf16 v[38:41], v[174:177], v[206:209], v[38:41]
	v_mfma_f32_16x16x32_bf16 v[30:33], v[162:165], v[214:217], v[30:33]
	v_mfma_f32_16x16x32_bf16 v[22:25], v[174:177], v[214:217], v[22:25]
	v_mfma_f32_16x16x32_bf16 v[14:17], v[162:165], v[222:225], v[14:17]
	v_mfma_f32_16x16x32_bf16 v[6:9], v[174:177], v[222:225], v[6:9]
	v_mfma_f32_16x16x32_bf16 v[58:61], v[178:181], v[194:197], v[58:61]
	v_mfma_f32_16x16x32_bf16 v[50:53], v[186:189], v[194:197], v[50:53]
	v_mfma_f32_16x16x32_bf16 v[42:45], v[178:181], v[202:205], v[42:45]
	v_mfma_f32_16x16x32_bf16 v[34:37], v[186:189], v[202:205], v[34:37]
	v_mfma_f32_16x16x32_bf16 v[26:29], v[178:181], v[210:213], v[26:29]
	v_mfma_f32_16x16x32_bf16 v[18:21], v[186:189], v[210:213], v[18:21]
	v_mfma_f32_16x16x32_bf16 v[10:13], v[178:181], v[218:221], v[10:13]
	v_mfma_f32_16x16x32_bf16 v[2:5], v[186:189], v[218:221], v[2:5]
	v_mfma_f32_16x16x32_bf16 v[58:61], v[182:185], v[198:201], v[58:61]
	v_mfma_f32_16x16x32_bf16 v[50:53], v[190:193], v[198:201], v[50:53]
	v_mfma_f32_16x16x32_bf16 v[42:45], v[182:185], v[206:209], v[42:45]
	v_mfma_f32_16x16x32_bf16 v[34:37], v[190:193], v[206:209], v[34:37]
	v_mfma_f32_16x16x32_bf16 v[26:29], v[182:185], v[214:217], v[26:29]
	v_mfma_f32_16x16x32_bf16 v[18:21], v[190:193], v[214:217], v[18:21]
	v_mfma_f32_16x16x32_bf16 v[10:13], v[182:185], v[222:225], v[10:13]
	v_mfma_f32_16x16x32_bf16 v[2:5], v[190:193], v[222:225], v[2:5]
	s_barrier
	s_setprio 1
	s_add_i32 s67, s67, 2
	s_add_u32 s44, s44, 0x100
	s_addc_u32 s45, s45, 0
	s_add_u32 s65, s65, 0x100
	s_addc_u32 s66, s66, 0
	s_cmp_gt_u32 s67, 13
	s_cbranch_scc0 .LBB0_884
	s_and_b64 vcc, exec, s[14:15]
	s_cbranch_vccz .LBB0_887
	s_barrier

; #define PG8_STAGE(bufoff, gbase, voff) do { _Pragma("unroll") for (int _i = 0; _i < 2; ++_i) \
;         __builtin_amdgcn_global_load_lds((const unsigned*)((const char*)(gbase) + (voff)[_i]), (LAS unsigned*)(lds + (bufoff) + ldsw + _i * 8192), 16, 0, 0); } while (0)
; #define PG8_LDA(dst, b, h) do { _Pragma("unroll") for (int m = 0; m < 4; ++m) _Pragma("unroll") for (int k = 0; k < 2; ++k) dst[m][k] = *(const LAS bf16x8*)(lds + PG8_SA(b, h) + aoff + m * 2048 + k * 1024); } while (0)
; #define PG8_LDB(dst, b, h) do { _Pragma("unroll") for (int n = 0; n < 2; ++n) _Pragma("unroll") for (int k = 0; k < 2; ++k) dst[n][k] = *(const LAS bf16x8*)(lds + PG8_SB(b, h) + boff + n * 2048 + k * 1024); } while (0)
; #define PG8_BAR __builtin_amdgcn_s_barrier()
; template <class Epi>
; __device__ __forceinline__ void gemm_phase(LAS unsigned char* lds, const Gemm g, const StaticOrder& S, const Epi& E) {
;     ...
;         for (int t = 0; t < nt; t += 2) {
;             const bool last = (t == nt - 2);
;             const char* a1 = cA + (size_t)(t + 1) * kstep;
;             const char* a2 = last ? nA : cA + (size_t)(t + 2) * kstep; const char* b2 = last ? nB : cB + (size_t)(t + 2) * kstep;
;             const char* a3 = a2 + kstep; const char* b3 = b2 + kstep;
;             if constexpr (Epi::MIDK > 0) { if (t == Epi::MIDK) E.mid(acc, cur, wr, wc, fr, fq); }
;             PG8_LDB(B0, 0, 0); PG8_LDB(B1, 0, 1); PG8_SCHED; PG8_LDA(At, 0, 0); PG8_STAGE(PG8_SA(1, 1), a1 + hstep, voffA);
;             PG8_WAIT_V(8); PG8_WAIT_L(0); PG8_BAR; PG8_MMA(0, 0, At, B0); PG8_MMA(0, 1, At, B1); PG8_BAR; PG8_SCHED;
;             PG8_LDA(At, 0, 1); PG8_STAGE(PG8_SB(0, 0), b2, voffB); PG8_STAGE(PG8_SB(0, 1), b2 + hstep, voffB); PG8_STAGE(PG8_SA(0, 0), a2, voffA);
;             PG8_WAIT_V(8); PG8_WAIT_L(0); PG8_BAR; PG8_MMA(1, 0, At, B0); PG8_MMA(1, 1, At, B1); PG8_BAR; PG8_SCHED;
;             PG8_LDB(B0, 1, 0); PG8_LDB(B1, 1, 1); PG8_SCHED; PG8_LDA(At, 1, 0); PG8_STAGE(PG8_SA(0, 1), a2 + hstep, voffA);
;             PG8_WAIT_V(8); PG8_WAIT_L(0); PG8_BAR; PG8_MMA(0, 0, At, B0); PG8_MMA(0, 1, At, B1); PG8_BAR; PG8_SCHED;
;             PG8_LDA(At, 1, 1); PG8_STAGE(PG8_SB(1, 0), b3, voffB); PG8_STAGE(PG8_SB(1, 1), b3 + hstep, voffB); PG8_STAGE(PG8_SA(1, 0), a3, voffA);
;             PG8_WAIT_V(8); PG8_WAIT_L(0); PG8_BAR; PG8_MMA(1, 0, At, B0); PG8_MMA(1, 1, At, B1); PG8_BAR; PG8_SCHED;
.LBB0_971:
	ds_read_b128 v[130:133], v162
	ds_read_b128 v[134:137], v162 offset:1024
	ds_read_b128 v[154:157], v162 offset:2048
	ds_read_b128 v[166:169], v162 offset:3072
	ds_read_b128 v[174:177], v163
	ds_read_b128 v[178:181], v163 offset:1024
	ds_read_b128 v[182:185], v163 offset:2048
	ds_read_b128 v[186:189], v163 offset:3072
	s_add_u32 s24, s22, 0xfff50080
	s_addc_u32 s25, s23, -1
	s_cmp_eq_u32 s59, 40
	s_cselect_b32 s27, s5, s25
	s_cselect_b32 s26, s4, s24
	s_cselect_b32 s25, s21, s58
	s_cselect_b32 s24, s20, s57
	s_add_i32 m0, s39, 0xc000
	ds_read_b128 v[190:193], v164
	ds_read_b128 v[194:197], v164 offset:1024
	ds_read_b128 v[198:201], v164 offset:2048
	ds_read_b128 v[202:205], v164 offset:3072
	ds_read_b128 v[206:209], v164 offset:4096
	ds_read_b128 v[210:213], v164 offset:5120
	ds_read_b128 v[214:217], v164 offset:6144
	ds_read_b128 v[218:221], v164 offset:7168
	global_load_lds_dwordx4 v146, s[22:23]
	s_add_i32 m0, s39, 0xe000
	s_nop 0
	global_load_lds_dwordx4 v148, s[22:23]
	s_waitcnt vmcnt(8)
	s_waitcnt lgkmcnt(0)
	s_setprio 0
	s_barrier
	v_mfma_f32_16x16x32_bf16 v[126:129], v[130:133], v[190:193], v[126:129]
	v_mfma_f32_16x16x32_bf16 v[122:125], v[154:157], v[190:193], v[122:125]
	v_mfma_f32_16x16x32_bf16 v[110:113], v[130:133], v[198:201], v[110:113]
	v_mfma_f32_16x16x32_bf16 v[106:109], v[154:157], v[198:201], v[106:109]
	v_mfma_f32_16x16x32_bf16 v[94:97], v[130:133], v[206:209], v[94:97]
	v_mfma_f32_16x16x32_bf16 v[90:93], v[154:157], v[206:209], v[90:93]
	v_mfma_f32_16x16x32_bf16 v[78:81], v[130:133], v[214:217], v[78:81]
	v_mfma_f32_16x16x32_bf16 v[74:77], v[154:157], v[214:217], v[74:77]
	v_mfma_f32_16x16x32_bf16 v[126:129], v[134:137], v[194:197], v[126:129]
	v_mfma_f32_16x16x32_bf16 v[122:125], v[166:169], v[194:197], v[122:125]
	v_mfma_f32_16x16x32_bf16 v[110:113], v[134:137], v[202:205], v[110:113]
	v_mfma_f32_16x16x32_bf16 v[106:109], v[166:169], v[202:205], v[106:109]
	v_mfma_f32_16x16x32_bf16 v[94:97], v[134:137], v[210:213], v[94:97]
	v_mfma_f32_16x16x32_bf16 v[90:93], v[166:169], v[210:213], v[90:93]
	v_mfma_f32_16x16x32_bf16 v[78:81], v[134:137], v[218:221], v[78:81]
	v_mfma_f32_16x16x32_bf16 v[74:77], v[166:169], v[218:221], v[74:77]
	v_mfma_f32_16x16x32_bf16 v[118:121], v[174:177], v[190:193], v[118:121]
	v_mfma_f32_16x16x32_bf16 v[114:117], v[182:185], v[190:193], v[114:117]
	v_mfma_f32_16x16x32_bf16 v[102:105], v[174:177], v[198:201], v[102:105]
	v_mfma_f32_16x16x32_bf16 v[98:101], v[182:185], v[198:201], v[98:101]
	v_mfma_f32_16x16x32_bf16 v[86:89], v[174:177], v[206:209], v[86:89]
	v_mfma_f32_16x16x32_bf16 v[82:85], v[182:185], v[206:209], v[82:85]
	v_mfma_f32_16x16x32_bf16 v[70:73], v[174:177], v[214:217], v[70:73]
	v_mfma_f32_16x16x32_bf16 v[66:69], v[182:185], v[214:217], v[66:69]
	v_mfma_f32_16x16x32_bf16 v[118:121], v[178:181], v[194:197], v[118:121]
	v_mfma_f32_16x16x32_bf16 v[114:117], v[186:189], v[194:197], v[114:117]
	v_mfma_f32_16x16x32_bf16 v[102:105], v[178:181], v[202:205], v[102:105]
	v_mfma_f32_16x16x32_bf16 v[98:101], v[186:189], v[202:205], v[98:101]
	v_mfma_f32_16x16x32_bf16 v[86:89], v[178:181], v[210:213], v[86:89]
	v_mfma_f32_16x16x32_bf16 v[82:85], v[186:189], v[210:213], v[82:85]
	v_mfma_f32_16x16x32_bf16 v[70:73], v[178:181], v[218:221], v[70:73]
	v_mfma_f32_16x16x32_bf16 v[66:69], v[186:189], v[218:221], v[66:69]
	s_barrier
	s_setprio 1
	s_add_u32 s98, s24, s14
	s_addc_u32 s99, s25, s15
	s_add_u32 s100, s26, s14
	s_addc_u32 s101, s27, s15
	s_add_i32 s60, s51, s38
	s_mov_b32 m0, s60
	ds_read_b128 v[190:193], v164 offset:16384
	ds_read_b128 v[194:197], v164 offset:17408
	ds_read_b128 v[198:201], v164 offset:18432
	ds_read_b128 v[202:205], v164 offset:19456
	ds_read_b128 v[206:209], v164 offset:20480
	ds_read_b128 v[210:213], v164 offset:21504
	ds_read_b128 v[214:217], v164 offset:22528
	ds_read_b128 v[218:221], v164 offset:23552
	global_load_lds_dwordx4 v140, s[24:25]
	s_add_i32 m0, s60, 0x2000
	s_add_u32 s60, s24, 0xb0000
	s_addc_u32 s61, s25, 0
	s_add_i32 s62, s52, s38
	global_load_lds_dwordx4 v144, s[24:25]
	s_mov_b32 m0, s62
	s_nop 0
	global_load_lds_dwordx4 v140, s[60:61]
	s_add_i32 m0, s62, 0x2000
	s_nop 0
	global_load_lds_dwordx4 v144, s[60:61]
	s_mov_b32 m0, s39
	s_nop 0
	global_load_lds_dwordx4 v138, s[26:27]
	s_mov_b32 m0, s40
	s_nop 0
	global_load_lds_dwordx4 v142, s[26:27]
	s_waitcnt vmcnt(8)
	s_waitcnt lgkmcnt(0)
	s_setprio 0
	s_barrier
	v_mfma_f32_16x16x32_bf16 v[62:65], v[130:133], v[190:193], v[62:65]
	v_mfma_f32_16x16x32_bf16 v[58:61], v[154:157], v[190:193], v[58:61]
	v_mfma_f32_16x16x32_bf16 v[46:49], v[130:133], v[198:201], v[46:49]
	v_mfma_f32_16x16x32_bf16 v[42:45], v[154:157], v[198:201], v[42:45]
	v_mfma_f32_16x16x32_bf16 v[30:33], v[130:133], v[206:209], v[30:33]
	v_mfma_f32_16x16x32_bf16 v[26:29], v[154:157], v[206:209], v[26:29]
	v_mfma_f32_16x16x32_bf16 v[14:17], v[130:133], v[214:217], v[14:17]
	v_mfma_f32_16x16x32_bf16 v[10:13], v[154:157], v[214:217], v[10:13]
	v_mfma_f32_16x16x32_bf16 v[62:65], v[134:137], v[194:197], v[62:65]
	v_mfma_f32_16x16x32_bf16 v[58:61], v[166:169], v[194:197], v[58:61]
	v_mfma_f32_16x16x32_bf16 v[46:49], v[134:137], v[202:205], v[46:49]
	v_mfma_f32_16x16x32_bf16 v[42:45], v[166:169], v[202:205], v[42:45]
	v_mfma_f32_16x16x32_bf16 v[30:33], v[134:137], v[210:213], v[30:33]
	v_mfma_f32_16x16x32_bf16 v[26:29], v[166:169], v[210:213], v[26:29]
	v_mfma_f32_16x16x32_bf16 v[14:17], v[134:137], v[218:221], v[14:17]
	v_mfma_f32_16x16x32_bf16 v[10:13], v[166:169], v[218:221], v[10:13]
	v_mfma_f32_16x16x32_bf16 v[54:57], v[174:177], v[190:193], v[54:57]
	v_mfma_f32_16x16x32_bf16 v[50:53], v[182:185], v[190:193], v[50:53]
	v_mfma_f32_16x16x32_bf16 v[38:41], v[174:177], v[198:201], v[38:41]
	v_mfma_f32_16x16x32_bf16 v[34:37], v[182:185], v[198:201], v[34:37]
	v_mfma_f32_16x16x32_bf16 v[22:25], v[174:177], v[206:209], v[22:25]
	v_mfma_f32_16x16x32_bf16 v[18:21], v[182:185], v[206:209], v[18:21]
	v_mfma_f32_16x16x32_bf16 v[6:9], v[174:177], v[214:217], v[6:9]
	v_mfma_f32_16x16x32_bf16 v[2:5], v[182:185], v[214:217], v[2:5]
	v_mfma_f32_16x16x32_bf16 v[54:57], v[178:181], v[194:197], v[54:57]
	v_mfma_f32_16x16x32_bf16 v[50:53], v[186:189], v[194:197], v[50:53]
	v_mfma_f32_16x16x32_bf16 v[38:41], v[178:181], v[202:205], v[38:41]
	v_mfma_f32_16x16x32_bf16 v[34:37], v[186:189], v[202:205], v[34:37]
	v_mfma_f32_16x16x32_bf16 v[22:25], v[178:181], v[210:213], v[22:25]
	v_mfma_f32_16x16x32_bf16 v[18:21], v[186:189], v[210:213], v[18:21]
	v_mfma_f32_16x16x32_bf16 v[6:9], v[178:181], v[218:221], v[6:9]
	v_mfma_f32_16x16x32_bf16 v[2:5], v[186:189], v[218:221], v[2:5]
	s_barrier
; #define PG8_STAGE(bufoff, gbase, voff) do { _Pragma("unroll") for (int _i = 0; _i < 2; ++_i) \
;         __builtin_amdgcn_global_load_lds((const unsigned*)((const char*)(gbase) + (voff)[_i]), (LAS unsigned*)(lds + (bufoff) + ldsw + _i * 8192), 16, 0, 0); } while (0)
; #define PG8_LDA(dst, b, h) do { _Pragma("unroll") for (int m = 0; m < 4; ++m) _Pragma("unroll") for (int k = 0; k < 2; ++k) dst[m][k] = *(const LAS bf16x8*)(lds + PG8_SA(b, h) + aoff + m * 2048 + k * 1024); } while (0)
; #define PG8_LDB(dst, b, h) do { _Pragma("unroll") for (int n = 0; n < 2; ++n) _Pragma("unroll") for (int k = 0; k < 2; ++k) dst[n][k] = *(const LAS bf16x8*)(lds + PG8_SB(b, h) + boff + n * 2048 + k * 1024); } while (0)
; #define PG8_MMA(ai, bj, At, Bt) do { __builtin_amdgcn_s_setprio(1); _Pragma("unroll") for (int m = 0; m < 4; ++m) _Pragma("unroll") for (int n = 0; n < 2; ++n) _Pragma("unroll") for (int k = 0; k < 2; ++k) \
;         acc[ai][bj][m][n] = __builtin_amdgcn_mfma_f32_16x16x32_bf16(Bt[n][k], At[m][k], acc[ai][bj][m][n], 0, 0, 0); __builtin_amdgcn_s_setprio(0); } while (0)
; #define PG8_WAIT_V(n) asm volatile("s_waitcnt vmcnt(" #n ")" ::: "memory")
; #define PG8_WAIT_L(n) asm volatile("s_waitcnt lgkmcnt(" #n ")" ::: "memory")
; #define PG8_BAR __builtin_amdgcn_s_barrier()
; #define PG8_SCHED __builtin_amdgcn_sched_barrier(0)
; template <class Epi>
; __device__ __forceinline__ void gemm_phase(LAS unsigned char* lds, const Gemm g, const StaticOrder& S, const Epi& E) {
;     ...
;             PG8_LDB(B0, 1, 0); PG8_LDB(B1, 1, 1); PG8_SCHED; PG8_LDA(At, 1, 0); PG8_STAGE(PG8_SA(0, 1), a2 + hstep, voffA);
;             PG8_WAIT_V(8); PG8_WAIT_L(0); PG8_BAR; PG8_MMA(0, 0, At, B0); PG8_MMA(0, 1, At, B1); PG8_BAR; PG8_SCHED;
;             PG8_LDA(At, 1, 1); PG8_STAGE(PG8_SB(1, 0), b3, voffB); PG8_STAGE(PG8_SB(1, 1), b3 + hstep, voffB); PG8_STAGE(PG8_SA(1, 0), a3, voffA);
;             PG8_WAIT_V(8); PG8_WAIT_L(0); PG8_BAR; PG8_MMA(1, 0, At, B0); PG8_MMA(1, 1, At, B1); PG8_BAR; PG8_SCHED;
;         }
	s_setprio 1
	s_add_i32 s60, 0, 0x18000
	s_add_i32 s61, 0, 0x1c000
	v_add_u32_e32 v166, s60, v160
	v_add_u32_e32 v186, s61, v160
	ds_read_b128 v[130:133], v166
	ds_read_b128 v[134:137], v166 offset:1024
	ds_read_b128 v[154:157], v166 offset:2048
	ds_read_b128 v[166:169], v166 offset:3072
	ds_read_b128 v[174:177], v186
	ds_read_b128 v[178:181], v186 offset:1024
	ds_read_b128 v[182:185], v186 offset:2048
	ds_read_b128 v[186:189], v186 offset:3072
	s_add_u32 s26, s26, 0xb0000
	s_addc_u32 s27, s27, 0
	s_mov_b32 m0, s41
	ds_read_b128 v[190:193], v164 offset:32768
	ds_read_b128 v[194:197], v164 offset:33792
	ds_read_b128 v[198:201], v164 offset:34816
	ds_read_b128 v[202:205], v164 offset:35840
	ds_read_b128 v[206:209], v164 offset:36864
	ds_read_b128 v[210:213], v164 offset:37888
	ds_read_b128 v[214:217], v164 offset:38912
	ds_read_b128 v[218:221], v164 offset:39936
	global_load_lds_dwordx4 v138, s[26:27]
	s_mov_b32 m0, s42
	s_nop 0
	global_load_lds_dwordx4 v142, s[26:27]
	s_waitcnt vmcnt(8)
	s_waitcnt lgkmcnt(0)
	s_setprio 0
	s_barrier
	v_mfma_f32_16x16x32_bf16 v[126:129], v[130:133], v[190:193], v[126:129]
	v_mfma_f32_16x16x32_bf16 v[122:125], v[154:157], v[190:193], v[122:125]
	v_mfma_f32_16x16x32_bf16 v[110:113], v[130:133], v[198:201], v[110:113]
	v_mfma_f32_16x16x32_bf16 v[106:109], v[154:157], v[198:201], v[106:109]
	v_mfma_f32_16x16x32_bf16 v[94:97], v[130:133], v[206:209], v[94:97]
	v_mfma_f32_16x16x32_bf16 v[90:93], v[154:157], v[206:209], v[90:93]
	v_mfma_f32_16x16x32_bf16 v[78:81], v[130:133], v[214:217], v[78:81]
	v_mfma_f32_16x16x32_bf16 v[74:77], v[154:157], v[214:217], v[74:77]
	v_mfma_f32_16x16x32_bf16 v[126:129], v[134:137], v[194:197], v[126:129]
	v_mfma_f32_16x16x32_bf16 v[122:125], v[166:169], v[194:197], v[122:125]
	v_mfma_f32_16x16x32_bf16 v[110:113], v[134:137], v[202:205], v[110:113]
	v_mfma_f32_16x16x32_bf16 v[106:109], v[166:169], v[202:205], v[106:109]
	v_mfma_f32_16x16x32_bf16 v[94:97], v[134:137], v[210:213], v[94:97]
	v_mfma_f32_16x16x32_bf16 v[90:93], v[166:169], v[210:213], v[90:93]
	v_mfma_f32_16x16x32_bf16 v[78:81], v[134:137], v[218:221], v[78:81]
	v_mfma_f32_16x16x32_bf16 v[74:77], v[166:169], v[218:221], v[74:77]
	v_mfma_f32_16x16x32_bf16 v[118:121], v[174:177], v[190:193], v[118:121]
	v_mfma_f32_16x16x32_bf16 v[114:117], v[182:185], v[190:193], v[114:117]
	v_mfma_f32_16x16x32_bf16 v[102:105], v[174:177], v[198:201], v[102:105]
	v_mfma_f32_16x16x32_bf16 v[98:101], v[182:185], v[198:201], v[98:101]
	v_mfma_f32_16x16x32_bf16 v[86:89], v[174:177], v[206:209], v[86:89]
	v_mfma_f32_16x16x32_bf16 v[82:85], v[182:185], v[206:209], v[82:85]
	v_mfma_f32_16x16x32_bf16 v[70:73], v[174:177], v[214:217], v[70:73]
	v_mfma_f32_16x16x32_bf16 v[66:69], v[182:185], v[214:217], v[66:69]
	v_mfma_f32_16x16x32_bf16 v[118:121], v[178:181], v[194:197], v[118:121]
	v_mfma_f32_16x16x32_bf16 v[114:117], v[186:189], v[194:197], v[114:117]
	v_mfma_f32_16x16x32_bf16 v[102:105], v[178:181], v[202:205], v[102:105]
	v_mfma_f32_16x16x32_bf16 v[98:101], v[186:189], v[202:205], v[98:101]
	v_mfma_f32_16x16x32_bf16 v[86:89], v[178:181], v[210:213], v[86:89]
	v_mfma_f32_16x16x32_bf16 v[82:85], v[186:189], v[210:213], v[82:85]
	v_mfma_f32_16x16x32_bf16 v[70:73], v[178:181], v[218:221], v[70:73]
	v_mfma_f32_16x16x32_bf16 v[66:69], v[186:189], v[218:221], v[66:69]
	s_barrier
	s_setprio 1
	s_add_i32 s26, s60, s38
	s_mov_b32 m0, s26
	ds_read_b128 v[190:193], v164 offset:49152
	ds_read_b128 v[194:197], v164 offset:50176
	ds_read_b128 v[198:201], v164 offset:51200
	ds_read_b128 v[202:205], v164 offset:52224
	ds_read_b128 v[206:209], v164 offset:53248
	ds_read_b128 v[210:213], v164 offset:54272
	ds_read_b128 v[214:217], v164 offset:55296
	ds_read_b128 v[218:221], v164 offset:56320
	global_load_lds_dwordx4 v140, s[98:99]
	s_add_i32 m0, s26, 0x2000
	s_add_u32 s24, s24, 0xb0080
	s_addc_u32 s25, s25, 0
	s_add_i32 s26, s61, s38
	global_load_lds_dwordx4 v144, s[98:99]
	s_mov_b32 m0, s26
	s_nop 0
	global_load_lds_dwordx4 v140, s[24:25]
	s_add_i32 m0, s26, 0x2000
	s_nop 0
	global_load_lds_dwordx4 v144, s[24:25]
	s_mov_b32 m0, s44
	s_nop 0
	global_load_lds_dwordx4 v138, s[100:101]
	s_mov_b32 m0, s45
	s_nop 0
	global_load_lds_dwordx4 v142, s[100:101]
	s_waitcnt vmcnt(8)
	s_waitcnt lgkmcnt(0)
	s_setprio 0
	s_barrier
	v_mfma_f32_16x16x32_bf16 v[62:65], v[130:133], v[190:193], v[62:65]
	v_mfma_f32_16x16x32_bf16 v[58:61], v[154:157], v[190:193], v[58:61]
	v_mfma_f32_16x16x32_bf16 v[46:49], v[130:133], v[198:201], v[46:49]
	v_mfma_f32_16x16x32_bf16 v[42:45], v[154:157], v[198:201], v[42:45]
	v_mfma_f32_16x16x32_bf16 v[30:33], v[130:133], v[206:209], v[30:33]
	v_mfma_f32_16x16x32_bf16 v[26:29], v[154:157], v[206:209], v[26:29]
	v_mfma_f32_16x16x32_bf16 v[14:17], v[130:133], v[214:217], v[14:17]
	v_mfma_f32_16x16x32_bf16 v[10:13], v[154:157], v[214:217], v[10:13]
	v_mfma_f32_16x16x32_bf16 v[62:65], v[134:137], v[194:197], v[62:65]
	v_mfma_f32_16x16x32_bf16 v[58:61], v[166:169], v[194:197], v[58:61]
	v_mfma_f32_16x16x32_bf16 v[46:49], v[134:137], v[202:205], v[46:49]
	v_mfma_f32_16x16x32_bf16 v[42:45], v[166:169], v[202:205], v[42:45]
	v_mfma_f32_16x16x32_bf16 v[30:33], v[134:137], v[210:213], v[30:33]
	v_mfma_f32_16x16x32_bf16 v[26:29], v[166:169], v[210:213], v[26:29]
	v_mfma_f32_16x16x32_bf16 v[14:17], v[134:137], v[218:221], v[14:17]
	v_mfma_f32_16x16x32_bf16 v[10:13], v[166:169], v[218:221], v[10:13]
	v_mfma_f32_16x16x32_bf16 v[54:57], v[174:177], v[190:193], v[54:57]
	v_mfma_f32_16x16x32_bf16 v[50:53], v[182:185], v[190:193], v[50:53]
	v_mfma_f32_16x16x32_bf16 v[38:41], v[174:177], v[198:201], v[38:41]
	v_mfma_f32_16x16x32_bf16 v[34:37], v[182:185], v[198:201], v[34:37]
	v_mfma_f32_16x16x32_bf16 v[22:25], v[174:177], v[206:209], v[22:25]
	v_mfma_f32_16x16x32_bf16 v[18:21], v[182:185], v[206:209], v[18:21]
	v_mfma_f32_16x16x32_bf16 v[6:9], v[174:177], v[214:217], v[6:9]
	v_mfma_f32_16x16x32_bf16 v[2:5], v[182:185], v[214:217], v[2:5]
	v_mfma_f32_16x16x32_bf16 v[54:57], v[178:181], v[194:197], v[54:57]
	v_mfma_f32_16x16x32_bf16 v[50:53], v[186:189], v[194:197], v[50:53]
	v_mfma_f32_16x16x32_bf16 v[38:41], v[178:181], v[202:205], v[38:41]
	v_mfma_f32_16x16x32_bf16 v[34:37], v[186:189], v[202:205], v[34:37]
	v_mfma_f32_16x16x32_bf16 v[22:25], v[178:181], v[210:213], v[22:25]
	v_mfma_f32_16x16x32_bf16 v[18:21], v[186:189], v[210:213], v[18:21]
	v_mfma_f32_16x16x32_bf16 v[6:9], v[178:181], v[218:221], v[6:9]
	v_mfma_f32_16x16x32_bf16 v[2:5], v[186:189], v[218:221], v[2:5]
	s_barrier
	s_setprio 1
	s_add_i32 s59, s59, 2
	s_add_u32 s22, s22, 0x100
	s_addc_u32 s23, s23, 0
	s_add_u32 s57, s57, 0x100
	s_addc_u32 s58, s58, 0
	s_cmp_gt_u32 s59, 41
	s_cbranch_scc0 .LBB0_971
	s_and_b64 vcc, exec, s[18:19]
	s_cbranch_vccz .LBB0_974
	s_barrier
